# k14 + conv_waits: delete 305 provably no-op s_waitcnt lgkmcnt(0) in the FFT conv region
# speedup vs baseline: 1.0264x; 1.0012x over previous
; __device__ __forceinline__ c2 cmul(c2 a, c2 b) { return (c2){a.x * b.x - a.y * b.y, a.x * b.y + a.y * b.x}; }
; __device__ __forceinline__ c2 mni(c2 a) { return (c2){a.y, -a.x}; }
; __device__ __forceinline__ void dft8(c2 (&x)[8]) {
;     const float s = 0.70710678118654752f;
;     const c2 a0 = x[0] + x[4], a4 = x[0] - x[4], a1 = x[1] + x[5], a5 = x[1] - x[5], a2 = x[2] + x[6], a6 = x[2] - x[6], a3 = x[3] + x[7], a7 = x[3] - x[7];
;     const c2 a5w = (c2){(a5.x + a5.y) * s, (a5.y - a5.x) * s};
;     const c2 a6w = mni(a6);
;     const c2 a7w = (c2){(a7.y - a7.x) * s, -(a7.x + a7.y) * s};
;     const c2 b0 = a0 + a2, b1 = a0 - a2, b2 = a1 + a3, b3 = mni(a1 - a3);
;     x[0] = b0 + b2; x[4] = b0 - b2; x[2] = b1 + b3; x[6] = b1 - b3;
;     const c2 c0 = a4 + a6w, c1 = a4 - a6w, c2_ = a5w + a7w, c3 = mni(a5w - a7w);
;     x[1] = c0 + c2_; x[5] = c0 - c2_; x[3] = c1 + c3; x[7] = c1 - c3;
; }
; __device__ __forceinline__ c2 mpi(c2 a) { return (c2){-a.y, a.x}; }
; __device__ __forceinline__ void idft8(c2 (&x)[8]) {
;     const float s = 0.70710678118654752f;
;     const c2 a0 = x[0] + x[4], a4 = x[0] - x[4], a1 = x[1] + x[5], a5 = x[1] - x[5], a2 = x[2] + x[6], a6 = x[2] - x[6], a3 = x[3] + x[7], a7 = x[3] - x[7];
;     const c2 a5w = (c2){(a5.x - a5.y) * s, (a5.x + a5.y) * s};
;     const c2 a6w = mpi(a6);
;     const c2 a7w = (c2){-(a7.x + a7.y) * s, (a7.x - a7.y) * s};
;     const c2 b0 = a0 + a2, b1 = a0 - a2, b2 = a1 + a3, b3 = mpi(a1 - a3);
;     x[0] = b0 + b2; x[4] = b0 - b2; x[2] = b1 + b3; x[6] = b1 - b3;
;     const c2 c0 = a4 + a6w, c1 = a4 - a6w, c2_ = a5w + a7w, c3 = mpi(a5w - a7w);
;     x[1] = c0 + c2_; x[5] = c0 - c2_; x[3] = c1 + c3; x[7] = c1 - c3;
; }
; __device__ __forceinline__ void fwd_s0(c2 (&x)[8], c2* buf, const c2* tws, int tid) {
;     dft8(x);
; #pragma unroll
;     for (int q = 1; q < 8; ++q) x[q] = cmul(x[q], tws[(q - 1) * 512 + tid]);
;     { c2* bp_ = buf + LP(tid);
; #pragma unroll
;     for (int q = 0; q < 8; ++q) bp_[576 * q] = x[q]; }
; }
; __device__ __forceinline__ void phase_conv(const Params& p, int o, unsigned char* smem, int wave) {
;     ...
;             c2 K[8], dmy[8];
; #pragma unroll
;             for (int r = 0; r < 8; ++r) { K[r] = (c2){subfilt(hf, hb, L, 0, tid + 512 * r), 0.f}; dmy[r] = (c2){0.f, 0.f}; }
;             __syncthreads();
;             fft_fwd_regs2(K, dmy, buf0, buf1, tws, tid);
.LBB0_287:
	s_or_b64 exec, exec, s[72:73]
	s_waitcnt vmcnt(0)
	v_pk_add_f32 v[8:9], v[0:1], v[4:5]
	v_sub_f32_e32 v56, v0, v4
	v_sub_f32_e32 v4, v1, v5
	v_pk_add_f32 v[0:1], v[2:3], v[6:7]
	v_sub_f32_e32 v7, v3, v7
	s_barrier
	v_sub_f32_e32 v5, v2, v6
	v_sub_f32_e32 v6, 0, v7
	v_add_f32_e32 v7, 0, v7
	v_pk_add_f32 v[10:11], v[8:9], v[0:1] neg_lo:[0,1] neg_hi:[0,1]
	v_add_f32_e32 v2, 0, v4
	v_sub_f32_e32 v3, 0, v4
	v_pk_mul_f32 v[6:7], v[6:7], s[20:21]
	v_pk_add_f32 v[0:1], v[8:9], v[0:1]
	v_pk_add_f32 v[8:9], v[10:11], 0 neg_lo:[1,1] neg_hi:[1,1]
	v_xor_b32_e32 v5, 0x80000000, v5
	v_mov_b32_e32 v4, v57
	v_mov_b32_e32 v12, v10
	v_mov_b32_e32 v13, v57
	v_mov_b32_e32 v8, v57
	v_pk_fma_f32 v[16:17], v[2:3], s[20:21], v[6:7] op_sel_hi:[1,0,1]
	v_pk_fma_f32 v[2:3], v[2:3], s[20:21], v[6:7] op_sel_hi:[1,0,1] neg_lo:[0,0,1] neg_hi:[0,0,1]
	v_pk_add_f32 v[14:15], v[12:13], v[8:9]
	v_pk_add_f32 v[8:9], v[12:13], v[8:9] neg_lo:[0,1] neg_hi:[0,1]
	v_pk_add_f32 v[12:13], v[56:57], v[4:5]
	v_pk_add_f32 v[4:5], v[56:57], v[4:5] neg_lo:[0,1] neg_hi:[0,1]
	v_xor_b32_e32 v7, 0x80000000, v2
	v_mov_b32_e32 v6, v3
	v_pk_add_f32 v[2:3], v[12:13], v[16:17]
	v_pk_add_f32 v[12:13], v[12:13], v[16:17] neg_lo:[0,1] neg_hi:[0,1]
	v_pk_add_f32 v[16:17], v[4:5], v[6:7]
	v_pk_add_f32 v[4:5], v[4:5], v[6:7] neg_lo:[0,1] neg_hi:[0,1]
	s_waitcnt lgkmcnt(0)
	v_pk_mul_f32 v[24:25], v[210:211], v[2:3] op_sel:[1,1] op_sel_hi:[0,1]
	v_fma_f32 v26, v210, v2, -v24
	v_fma_f32 v27, v211, v2, v25
	v_pk_add_f32 v[10:11], v[0:1], v[0:1] op_sel:[0,1] op_sel_hi:[1,0]
	v_pk_mul_f32 v[2:3], v[14:15], v[212:213] op_sel:[1,1] op_sel_hi:[1,0]
	v_pk_add_f32 v[0:1], v[0:1], v[0:1] op_sel:[0,1] op_sel_hi:[0,1] neg_lo:[0,1] neg_hi:[0,1]
	v_fma_f32 v18, v14, v212, -v2
	v_fma_f32 v19, v14, v213, v3
	v_pk_mul_f32 v[2:3], v[214:215], v[16:17] op_sel:[1,1] op_sel_hi:[0,1]
	v_fma_f32 v6, v214, v16, -v2
	v_fma_f32 v7, v215, v16, v3
	v_pk_mul_f32 v[2:3], v[216:217], 0 op_sel_hi:[1,0]
	v_mov_b32_e32 v11, v57
	v_fma_f32 v14, v0, v216, -v3
	v_fma_f32 v15, v1, v217, v2
	v_pk_mul_f32 v[20:21], v[12:13], v[218:219] op_sel:[1,1] op_sel_hi:[1,0]
	v_fma_f32 v22, v12, v218, -v20
	v_fma_f32 v23, v12, v219, v21
	v_pk_mul_f32 v[12:13], v[8:9], v[220:221] op_sel:[1,1] op_sel_hi:[1,0]
	v_mov_b32_e32 v56, v57
	v_fma_f32 v16, v8, v220, -v12
	v_fma_f32 v17, v8, v221, v13
	v_pk_mul_f32 v[0:1], v[4:5], v[222:223] op_sel:[1,1] op_sel_hi:[1,0]
	v_add_u32_e32 v191, 0x9000, v117
	v_fma_f32 v8, v4, v222, -v0
	v_fma_f32 v9, v4, v223, v1
	ds_write2st64_b64 v115, v[10:11], v[26:27] offset1:9
	ds_write2st64_b64 v115, v[18:19], v[6:7] offset0:18 offset1:27
	ds_write2st64_b64 v115, v[14:15], v[22:23] offset0:36 offset1:45
	ds_write2st64_b64 v115, v[16:17], v[8:9] offset0:54 offset1:63
	s_waitcnt lgkmcnt(0)
	v_pk_mul_f32 v[8:9], v[210:211], 0 op_sel_hi:[1,0]
	v_add_u32_e32 v192, 0x9800, v117
	v_pk_fma_f32 v[10:11], v[210:211], 0, v[8:9] op_sel:[0,0,1] op_sel_hi:[1,0,0] neg_lo:[0,0,1] neg_hi:[0,0,1]
	v_pk_fma_f32 v[0:1], v[210:211], 0, v[8:9] op_sel_hi:[1,0,0]
	v_pk_mul_f32 v[14:15], v[218:219], 0 op_sel_hi:[1,0]
	v_mov_b32_e32 v11, v1
	v_pk_mul_f32 v[0:1], v[212:213], 0 op_sel_hi:[1,0]
	v_pk_fma_f32 v[16:17], v[218:219], 0, v[14:15] op_sel:[0,0,1] op_sel_hi:[1,0,0] neg_lo:[0,0,1] neg_hi:[0,0,1]
	v_pk_fma_f32 v[8:9], v[212:213], 0, v[0:1] op_sel:[0,0,1] op_sel_hi:[1,0,0] neg_lo:[0,0,1] neg_hi:[0,0,1]
	v_pk_fma_f32 v[0:1], v[212:213], 0, v[0:1] op_sel_hi:[1,0,0]
	v_pk_fma_f32 v[12:13], v[218:219], 0, v[14:15] op_sel_hi:[1,0,0]
	v_mov_b32_e32 v9, v1
	v_pk_mul_f32 v[0:1], v[214:215], 0 op_sel_hi:[1,0]
	v_mov_b32_e32 v17, v13
	v_pk_fma_f32 v[2:3], v[214:215], 0, v[0:1] op_sel:[0,0,1] op_sel_hi:[1,0,0] neg_lo:[0,0,1] neg_hi:[0,0,1]
	v_pk_fma_f32 v[0:1], v[214:215], 0, v[0:1] op_sel_hi:[1,0,0]
	v_add_u32_e32 v193, 0x9000, v119
	v_mov_b32_e32 v3, v1
	v_pk_mul_f32 v[0:1], v[216:217], 0 op_sel_hi:[1,0]
	v_mov_b32_e32 v63, v57
	v_pk_fma_f32 v[4:5], v[216:217], 0, v[0:1] op_sel:[0,0,1] op_sel_hi:[1,0,0] neg_lo:[0,0,1] neg_hi:[0,0,1]
	v_pk_fma_f32 v[0:1], v[216:217], 0, v[0:1] op_sel_hi:[1,0,0]
	s_movk_i32 s3, 0x2000
	v_mov_b32_e32 v5, v1
	v_mov_b64_e32 v[6:7], v[222:223]
	s_mov_b32 s92, 0
	v_mov_b32_e32 v67, v66
	v_pk_mul_f32 v[12:13], v[220:221], 0 op_sel_hi:[1,0]
	s_nop 0
	v_pk_fma_f32 v[14:15], v[220:221], 0, v[12:13] op_sel:[0,0,1] op_sel_hi:[1,0,0] neg_lo:[0,0,1] neg_hi:[0,0,1]
	v_pk_fma_f32 v[0:1], v[220:221], 0, v[12:13] op_sel_hi:[1,0,0]
	s_nop 0
	v_mov_b32_e32 v15, v1
	v_pk_mul_f32 v[0:1], v[6:7], 0 op_sel_hi:[1,0]
	s_nop 0
	v_pk_fma_f32 v[12:13], v[6:7], 0, v[0:1] op_sel:[0,0,1] op_sel_hi:[1,0,0] neg_lo:[0,0,1] neg_hi:[0,0,1]
	v_pk_fma_f32 v[0:1], v[6:7], 0, v[0:1] op_sel_hi:[1,0,0]
	s_nop 0
	v_mov_b32_e32 v13, v1
	ds_write2st64_b64 v115, v[56:57], v[10:11] offset0:72 offset1:81
	ds_write2st64_b64 v115, v[8:9], v[2:3] offset0:90 offset1:99
	ds_write2st64_b64 v115, v[4:5], v[16:17] offset0:108 offset1:117
	ds_write_b64 v115, v[14:15] offset:64512
	ds_write_b64 v116, v[12:13] offset:32256
	s_waitcnt lgkmcnt(0)
	s_barrier
; __device__ __forceinline__ c2 cmul(c2 a, c2 b) { return (c2){a.x * b.x - a.y * b.y, a.x * b.y + a.y * b.x}; }
; __device__ __forceinline__ c2 mni(c2 a) { return (c2){a.y, -a.x}; }
; __device__ __forceinline__ void dft8(c2 (&x)[8]) {
;     const float s = 0.70710678118654752f;
;     const c2 a0 = x[0] + x[4], a4 = x[0] - x[4], a1 = x[1] + x[5], a5 = x[1] - x[5], a2 = x[2] + x[6], a6 = x[2] - x[6], a3 = x[3] + x[7], a7 = x[3] - x[7];
;     const c2 a5w = (c2){(a5.x + a5.y) * s, (a5.y - a5.x) * s};
;     const c2 a6w = mni(a6);
;     const c2 a7w = (c2){(a7.y - a7.x) * s, -(a7.x + a7.y) * s};
;     const c2 b0 = a0 + a2, b1 = a0 - a2, b2 = a1 + a3, b3 = mni(a1 - a3);
;     x[0] = b0 + b2; x[4] = b0 - b2; x[2] = b1 + b3; x[6] = b1 - b3;
;     const c2 c0 = a4 + a6w, c1 = a4 - a6w, c2_ = a5w + a7w, c3 = mni(a5w - a7w);
;     x[1] = c0 + c2_; x[5] = c0 - c2_; x[3] = c1 + c3; x[7] = c1 - c3;
; }
; template <int S> __device__ __forceinline__ void fwd_mid(c2* buf, const c2* tws, int tid) {
;     constexpr int lq = 9 - 3 * S, Q = 1 << lq; const c2* T = tws + (S == 1 ? 3584 : 4032);
;     const int k = tid & (Q - 1), base = ((tid >> lq) << (lq + 3)) + k;
;     c2 x[8];
;     c2* bp_ = buf + LP(base); constexpr int QP = Q + Q / 8;
; #pragma unroll
;     for (int r = 0; r < 8; ++r) x[r] = bp_[r * QP];
;     dft8(x);
; #pragma unroll
;     for (int q = 1; q < 8; ++q) x[q] = cmul(x[q], T[(q - 1) * Q + k]);
; #pragma unroll
;     for (int q = 0; q < 8; ++q) bp_[q * QP] = x[q];
; }
	ds_read2_b64 v[0:3], v117 offset1:72
	v_add_u32_e32 v56, 0x800, v117
	ds_read2_b64 v[4:7], v56 offset0:32 offset1:104
	ds_read2_b64 v[8:11], v117 offset0:144 offset1:216
	ds_read2_b64 v[12:15], v56 offset0:176 offset1:248
	v_mov_b64_e32 v[18:19], v[224:225]
	s_waitcnt lgkmcnt(0)
	v_pk_add_f32 v[16:17], v[0:1], v[4:5]
	v_pk_add_f32 v[0:1], v[0:1], v[4:5] neg_lo:[0,1] neg_hi:[0,1]
	v_pk_add_f32 v[4:5], v[2:3], v[6:7]
	v_pk_add_f32 v[2:3], v[2:3], v[6:7] neg_lo:[0,1] neg_hi:[0,1]
	v_pk_add_f32 v[6:7], v[8:9], v[12:13]
	v_pk_add_f32 v[8:9], v[8:9], v[12:13] neg_lo:[0,1] neg_hi:[0,1]
	v_pk_add_f32 v[12:13], v[10:11], v[14:15]
	v_pk_add_f32 v[10:11], v[10:11], v[14:15] neg_lo:[0,1] neg_hi:[0,1]
	v_pk_add_f32 v[14:15], v[2:3], v[2:3] op_sel:[1,0]
	v_pk_add_f32 v[2:3], v[2:3], v[2:3] op_sel_hi:[1,0] neg_lo:[0,1] neg_hi:[0,1]
	s_nop 0
	v_mov_b32_e32 v15, v3
	v_xor_b32_e32 v3, 0x80000000, v8
	v_mov_b32_e32 v2, v9
	v_pk_add_f32 v[8:9], v[10:11], v[10:11] op_sel:[1,0] neg_lo:[0,1] neg_hi:[0,1]
	v_pk_add_f32 v[10:11], v[10:11], v[10:11] op_sel_hi:[1,0]
	s_nop 0
	v_mov_b32_e32 v9, v11
	v_pk_add_f32 v[10:11], v[16:17], v[6:7]
	v_pk_add_f32 v[6:7], v[16:17], v[6:7] neg_lo:[0,1] neg_hi:[0,1]
	v_pk_add_f32 v[16:17], v[4:5], v[12:13]
	v_pk_add_f32 v[4:5], v[4:5], v[12:13] neg_lo:[0,1] neg_hi:[0,1]
	v_pk_mul_f32 v[8:9], v[8:9], s[20:21]
	v_xor_b32_e32 v13, 0x80000000, v4
	v_mov_b32_e32 v12, v5
	v_pk_add_f32 v[4:5], v[10:11], v[16:17]
	v_pk_add_f32 v[10:11], v[10:11], v[16:17] neg_lo:[0,1] neg_hi:[0,1]
	v_pk_add_f32 v[16:17], v[6:7], v[12:13]
	v_pk_add_f32 v[6:7], v[6:7], v[12:13] neg_lo:[0,1] neg_hi:[0,1]
	v_pk_add_f32 v[12:13], v[0:1], v[2:3]
	v_pk_add_f32 v[0:1], v[0:1], v[2:3] neg_lo:[0,1] neg_hi:[0,1]
	v_pk_fma_f32 v[2:3], v[14:15], s[20:21], v[8:9] op_sel_hi:[1,0,1]
	v_pk_fma_f32 v[8:9], v[14:15], s[20:21], v[8:9] op_sel_hi:[1,0,1] neg_lo:[0,0,1] neg_hi:[0,0,1]
	s_nop 0
	v_xor_b32_e32 v15, 0x80000000, v8
	v_mov_b32_e32 v14, v9
	v_pk_add_f32 v[8:9], v[12:13], v[2:3]
	v_pk_add_f32 v[2:3], v[12:13], v[2:3] neg_lo:[0,1] neg_hi:[0,1]
	v_pk_add_f32 v[12:13], v[0:1], v[14:15]
	v_pk_add_f32 v[0:1], v[0:1], v[14:15] neg_lo:[0,1] neg_hi:[0,1]
	v_pk_mul_f32 v[24:25], v[18:19], v[8:9] op_sel:[1,1] op_sel_hi:[0,1]
	v_fma_f32 v26, v18, v8, -v24
	v_fma_f32 v27, v19, v8, v25
	s_nop 0
	v_pk_mul_f32 v[8:9], v[226:227], v[16:17] op_sel:[1,1] op_sel_hi:[0,1]
	v_fma_f32 v18, v226, v16, -v8
	v_fma_f32 v19, v227, v16, v9
	v_pk_mul_f32 v[8:9], v[228:229], v[12:13] op_sel:[1,1] op_sel_hi:[0,1]
	v_fma_f32 v14, v228, v12, -v8
	v_fma_f32 v15, v229, v12, v9
	v_pk_mul_f32 v[20:21], v[232:233], v[2:3] op_sel:[1,1] op_sel_hi:[0,1]
	v_pk_mul_f32 v[8:9], v[10:11], v[230:231] op_sel:[1,1] op_sel_hi:[1,0]
	s_nop 0
	v_fma_f32 v12, v10, v230, -v8
	v_fma_f32 v13, v10, v231, v9
	v_mov_b64_e32 v[10:11], v[236:237]
	v_fma_f32 v22, v232, v2, -v20
	v_fma_f32 v23, v233, v2, v21
	ds_write2_b64 v117, v[4:5], v[26:27] offset1:72
	ds_write2_b64 v117, v[18:19], v[14:15] offset0:144 offset1:216
	s_waitcnt lgkmcnt(0)
	v_pk_mul_f32 v[2:3], v[6:7], v[234:235] op_sel:[1,1] op_sel_hi:[1,0]
	s_nop 0
	v_fma_f32 v16, v6, v234, -v2
	v_fma_f32 v17, v6, v235, v3
	v_pk_mul_f32 v[2:3], v[10:11], v[0:1] op_sel:[1,1] op_sel_hi:[0,1]
	v_fma_f32 v8, v10, v0, -v2
	v_fma_f32 v9, v11, v0, v3
	ds_read2_b64 v[4:7], v192 offset0:32 offset1:104
	ds_read2_b64 v[0:3], v191 offset1:72
	ds_write2_b64 v56, v[12:13], v[22:23] offset0:32 offset1:104
	ds_write2_b64 v56, v[16:17], v[8:9] offset0:176 offset1:248
	ds_read2_b64 v[8:11], v191 offset0:144 offset1:216
	ds_read2_b64 v[12:15], v192 offset0:176 offset1:248
	v_mov_b64_e32 v[18:19], v[224:225]
	s_waitcnt lgkmcnt(0)
	v_pk_add_f32 v[16:17], v[0:1], v[4:5]
	v_pk_add_f32 v[0:1], v[0:1], v[4:5] neg_lo:[0,1] neg_hi:[0,1]
	v_pk_add_f32 v[4:5], v[2:3], v[6:7]
	v_pk_add_f32 v[2:3], v[2:3], v[6:7] neg_lo:[0,1] neg_hi:[0,1]
	v_pk_add_f32 v[6:7], v[8:9], v[12:13]
	v_pk_add_f32 v[8:9], v[8:9], v[12:13] neg_lo:[0,1] neg_hi:[0,1]
	v_pk_add_f32 v[12:13], v[10:11], v[14:15]
	v_pk_add_f32 v[10:11], v[10:11], v[14:15] neg_lo:[0,1] neg_hi:[0,1]
	v_pk_add_f32 v[14:15], v[2:3], v[2:3] op_sel:[1,0]
	v_pk_add_f32 v[2:3], v[2:3], v[2:3] op_sel_hi:[1,0] neg_lo:[0,1] neg_hi:[0,1]
	s_nop 0
	v_mov_b32_e32 v15, v3
	v_xor_b32_e32 v3, 0x80000000, v8
	v_mov_b32_e32 v2, v9
	v_pk_add_f32 v[8:9], v[10:11], v[10:11] op_sel:[1,0] neg_lo:[0,1] neg_hi:[0,1]
	v_pk_add_f32 v[10:11], v[10:11], v[10:11] op_sel_hi:[1,0]
	s_nop 0
	v_mov_b32_e32 v9, v11
	v_pk_add_f32 v[10:11], v[16:17], v[6:7]
	v_pk_add_f32 v[6:7], v[16:17], v[6:7] neg_lo:[0,1] neg_hi:[0,1]
	v_pk_add_f32 v[16:17], v[4:5], v[12:13]
	v_pk_add_f32 v[4:5], v[4:5], v[12:13] neg_lo:[0,1] neg_hi:[0,1]
	v_pk_mul_f32 v[8:9], v[8:9], s[20:21]
	v_xor_b32_e32 v13, 0x80000000, v4
	v_mov_b32_e32 v12, v5
	v_pk_add_f32 v[4:5], v[10:11], v[16:17]
	v_pk_add_f32 v[10:11], v[10:11], v[16:17] neg_lo:[0,1] neg_hi:[0,1]
	v_pk_add_f32 v[16:17], v[6:7], v[12:13]
	v_pk_add_f32 v[6:7], v[6:7], v[12:13] neg_lo:[0,1] neg_hi:[0,1]
	v_pk_add_f32 v[12:13], v[0:1], v[2:3]
	v_pk_add_f32 v[0:1], v[0:1], v[2:3] neg_lo:[0,1] neg_hi:[0,1]
	v_pk_fma_f32 v[2:3], v[14:15], s[20:21], v[8:9] op_sel_hi:[1,0,1]
	v_pk_fma_f32 v[8:9], v[14:15], s[20:21], v[8:9] op_sel_hi:[1,0,1] neg_lo:[0,0,1] neg_hi:[0,0,1]
	s_nop 0
	v_xor_b32_e32 v15, 0x80000000, v8
	v_mov_b32_e32 v14, v9
	v_pk_add_f32 v[8:9], v[12:13], v[2:3]
	v_pk_add_f32 v[2:3], v[12:13], v[2:3] neg_lo:[0,1] neg_hi:[0,1]
	v_pk_add_f32 v[12:13], v[0:1], v[14:15]
	v_pk_add_f32 v[0:1], v[0:1], v[14:15] neg_lo:[0,1] neg_hi:[0,1]
	v_pk_mul_f32 v[24:25], v[18:19], v[8:9] op_sel:[1,1] op_sel_hi:[0,1]
	v_fma_f32 v26, v18, v8, -v24
	v_fma_f32 v27, v19, v8, v25
	s_nop 0
	v_pk_mul_f32 v[8:9], v[226:227], v[16:17] op_sel:[1,1] op_sel_hi:[0,1]
	v_fma_f32 v18, v226, v16, -v8
	v_fma_f32 v19, v227, v16, v9
	v_pk_mul_f32 v[8:9], v[228:229], v[12:13] op_sel:[1,1] op_sel_hi:[0,1]
	v_fma_f32 v14, v228, v12, -v8
	v_fma_f32 v15, v229, v12, v9
	v_pk_mul_f32 v[20:21], v[232:233], v[2:3] op_sel:[1,1] op_sel_hi:[0,1]
	v_pk_mul_f32 v[8:9], v[10:11], v[230:231] op_sel:[1,1] op_sel_hi:[1,0]
	s_nop 0
	v_fma_f32 v12, v10, v230, -v8
	v_fma_f32 v13, v10, v231, v9
	v_mov_b64_e32 v[8:9], v[234:235]
	v_mov_b64_e32 v[10:11], v[236:237]
	v_fma_f32 v22, v232, v2, -v20
	v_fma_f32 v23, v233, v2, v21
	s_nop 0
	v_pk_mul_f32 v[2:3], v[6:7], v[8:9] op_sel:[1,1] op_sel_hi:[1,0]
	s_nop 0
	v_fma_f32 v16, v6, v8, -v2
	v_fma_f32 v17, v6, v9, v3
	v_pk_mul_f32 v[2:3], v[10:11], v[0:1] op_sel:[1,1] op_sel_hi:[0,1]
	v_fma_f32 v6, v10, v0, -v2
	v_fma_f32 v7, v11, v0, v3
	s_nop 0
	ds_write2_b64 v191, v[4:5], v[26:27] offset1:72
	ds_write2_b64 v191, v[18:19], v[14:15] offset0:144 offset1:216
	ds_write2_b64 v192, v[12:13], v[22:23] offset0:32 offset1:104
	ds_write2_b64 v192, v[16:17], v[6:7] offset0:176 offset1:248
	s_waitcnt lgkmcnt(0)
	s_barrier
; __device__ __forceinline__ c2 cmul(c2 a, c2 b) { return (c2){a.x * b.x - a.y * b.y, a.x * b.y + a.y * b.x}; }
; __device__ __forceinline__ c2 mni(c2 a) { return (c2){a.y, -a.x}; }
; __device__ __forceinline__ void dft8(c2 (&x)[8]) {
;     const float s = 0.70710678118654752f;
;     const c2 a0 = x[0] + x[4], a4 = x[0] - x[4], a1 = x[1] + x[5], a5 = x[1] - x[5], a2 = x[2] + x[6], a6 = x[2] - x[6], a3 = x[3] + x[7], a7 = x[3] - x[7];
;     const c2 a5w = (c2){(a5.x + a5.y) * s, (a5.y - a5.x) * s};
;     const c2 a6w = mni(a6);
;     const c2 a7w = (c2){(a7.y - a7.x) * s, -(a7.x + a7.y) * s};
;     const c2 b0 = a0 + a2, b1 = a0 - a2, b2 = a1 + a3, b3 = mni(a1 - a3);
;     x[0] = b0 + b2; x[4] = b0 - b2; x[2] = b1 + b3; x[6] = b1 - b3;
;     const c2 c0 = a4 + a6w, c1 = a4 - a6w, c2_ = a5w + a7w, c3 = mni(a5w - a7w);
;     x[1] = c0 + c2_; x[5] = c0 - c2_; x[3] = c1 + c3; x[7] = c1 - c3;
; }
; template <int S> __device__ __forceinline__ void fwd_mid(c2* buf, const c2* tws, int tid) {
;     constexpr int lq = 9 - 3 * S, Q = 1 << lq; const c2* T = tws + (S == 1 ? 3584 : 4032);
;     const int k = tid & (Q - 1), base = ((tid >> lq) << (lq + 3)) + k;
;     c2 x[8];
;     c2* bp_ = buf + LP(base); constexpr int QP = Q + Q / 8;
; #pragma unroll
;     for (int r = 0; r < 8; ++r) x[r] = bp_[r * QP];
;     dft8(x);
; #pragma unroll
;     for (int q = 1; q < 8; ++q) x[q] = cmul(x[q], T[(q - 1) * Q + k]);
; #pragma unroll
;     for (int q = 0; q < 8; ++q) bp_[q * QP] = x[q];
; }
	ds_read2_b64 v[0:3], v119 offset1:9
	ds_read2_b64 v[4:7], v119 offset0:36 offset1:45
	ds_read2_b64 v[8:11], v119 offset0:18 offset1:27
	ds_read2_b64 v[12:15], v119 offset0:54 offset1:63
	v_mov_b64_e32 v[18:19], v[238:239]
	s_waitcnt lgkmcnt(0)
	v_pk_add_f32 v[16:17], v[0:1], v[4:5]
	v_pk_add_f32 v[0:1], v[0:1], v[4:5] neg_lo:[0,1] neg_hi:[0,1]
	v_pk_add_f32 v[4:5], v[2:3], v[6:7]
	v_pk_add_f32 v[2:3], v[2:3], v[6:7] neg_lo:[0,1] neg_hi:[0,1]
	v_pk_add_f32 v[6:7], v[8:9], v[12:13]
	v_pk_add_f32 v[8:9], v[8:9], v[12:13] neg_lo:[0,1] neg_hi:[0,1]
	v_pk_add_f32 v[12:13], v[10:11], v[14:15]
	v_pk_add_f32 v[10:11], v[10:11], v[14:15] neg_lo:[0,1] neg_hi:[0,1]
	v_pk_add_f32 v[14:15], v[2:3], v[2:3] op_sel:[1,0]
	v_pk_add_f32 v[2:3], v[2:3], v[2:3] op_sel_hi:[1,0] neg_lo:[0,1] neg_hi:[0,1]
	s_nop 0
	v_mov_b32_e32 v15, v3
	v_xor_b32_e32 v3, 0x80000000, v8
	v_mov_b32_e32 v2, v9
	v_pk_add_f32 v[8:9], v[10:11], v[10:11] op_sel:[1,0] neg_lo:[0,1] neg_hi:[0,1]
	v_pk_add_f32 v[10:11], v[10:11], v[10:11] op_sel_hi:[1,0]
	s_nop 0
	v_mov_b32_e32 v9, v11
	v_pk_add_f32 v[10:11], v[16:17], v[6:7]
	v_pk_add_f32 v[6:7], v[16:17], v[6:7] neg_lo:[0,1] neg_hi:[0,1]
	v_pk_add_f32 v[16:17], v[4:5], v[12:13]
	v_pk_add_f32 v[4:5], v[4:5], v[12:13] neg_lo:[0,1] neg_hi:[0,1]
	v_pk_mul_f32 v[8:9], v[8:9], s[20:21]
	v_xor_b32_e32 v13, 0x80000000, v4
	v_mov_b32_e32 v12, v5
	v_pk_add_f32 v[4:5], v[10:11], v[16:17]
	v_pk_add_f32 v[10:11], v[10:11], v[16:17] neg_lo:[0,1] neg_hi:[0,1]
	v_pk_add_f32 v[16:17], v[6:7], v[12:13]
	v_pk_add_f32 v[6:7], v[6:7], v[12:13] neg_lo:[0,1] neg_hi:[0,1]
	v_pk_add_f32 v[12:13], v[0:1], v[2:3]
	v_pk_add_f32 v[0:1], v[0:1], v[2:3] neg_lo:[0,1] neg_hi:[0,1]
	v_pk_fma_f32 v[2:3], v[14:15], s[20:21], v[8:9] op_sel_hi:[1,0,1]
	v_pk_fma_f32 v[8:9], v[14:15], s[20:21], v[8:9] op_sel_hi:[1,0,1] neg_lo:[0,0,1] neg_hi:[0,0,1]
	s_nop 0
	v_xor_b32_e32 v15, 0x80000000, v8
	v_mov_b32_e32 v14, v9
	v_pk_add_f32 v[8:9], v[12:13], v[2:3]
	v_pk_add_f32 v[2:3], v[12:13], v[2:3] neg_lo:[0,1] neg_hi:[0,1]
	v_pk_add_f32 v[12:13], v[0:1], v[14:15]
	v_pk_add_f32 v[0:1], v[0:1], v[14:15] neg_lo:[0,1] neg_hi:[0,1]
	v_pk_mul_f32 v[24:25], v[18:19], v[8:9] op_sel:[1,1] op_sel_hi:[0,1]
	v_fma_f32 v26, v18, v8, -v24
	v_fma_f32 v27, v19, v8, v25
	s_nop 0
	v_pk_mul_f32 v[8:9], v[240:241], v[16:17] op_sel:[1,1] op_sel_hi:[0,1]
	v_fma_f32 v18, v240, v16, -v8
	v_fma_f32 v19, v241, v16, v9
	v_pk_mul_f32 v[8:9], v[242:243], v[12:13] op_sel:[1,1] op_sel_hi:[0,1]
	v_fma_f32 v14, v242, v12, -v8
	v_fma_f32 v15, v243, v12, v9
	v_pk_mul_f32 v[20:21], v[246:247], v[2:3] op_sel:[1,1] op_sel_hi:[0,1]
	v_pk_mul_f32 v[8:9], v[10:11], v[244:245] op_sel:[1,1] op_sel_hi:[1,0]
	s_nop 0
	v_fma_f32 v12, v10, v244, -v8
	v_fma_f32 v13, v10, v245, v9
	v_mov_b64_e32 v[10:11], v[250:251]
	v_fma_f32 v22, v246, v2, -v20
	v_fma_f32 v23, v247, v2, v21
	ds_write2_b64 v119, v[4:5], v[26:27] offset1:9
	ds_write2_b64 v119, v[18:19], v[14:15] offset0:18 offset1:27
	s_waitcnt lgkmcnt(0)
	v_pk_mul_f32 v[2:3], v[6:7], v[248:249] op_sel:[1,1] op_sel_hi:[1,0]
	s_nop 0
	v_fma_f32 v16, v6, v248, -v2
	v_fma_f32 v17, v6, v249, v3
	v_pk_mul_f32 v[2:3], v[10:11], v[0:1] op_sel:[1,1] op_sel_hi:[0,1]
	v_fma_f32 v8, v10, v0, -v2
	v_fma_f32 v9, v11, v0, v3
	s_nop 0
	ds_read2_b64 v[0:3], v193 offset1:9
	ds_read2_b64 v[4:7], v193 offset0:36 offset1:45
	ds_write2_b64 v119, v[12:13], v[22:23] offset0:36 offset1:45
	ds_write2_b64 v119, v[16:17], v[8:9] offset0:54 offset1:63
	ds_read2_b64 v[8:11], v193 offset0:18 offset1:27
	ds_read2_b64 v[12:15], v193 offset0:54 offset1:63
	v_mov_b64_e32 v[18:19], v[238:239]
	s_waitcnt lgkmcnt(0)
	v_pk_add_f32 v[16:17], v[0:1], v[4:5]
	v_pk_add_f32 v[0:1], v[0:1], v[4:5] neg_lo:[0,1] neg_hi:[0,1]
	v_pk_add_f32 v[4:5], v[2:3], v[6:7]
	v_pk_add_f32 v[2:3], v[2:3], v[6:7] neg_lo:[0,1] neg_hi:[0,1]
	v_pk_add_f32 v[6:7], v[8:9], v[12:13]
	v_pk_add_f32 v[8:9], v[8:9], v[12:13] neg_lo:[0,1] neg_hi:[0,1]
	v_pk_add_f32 v[12:13], v[10:11], v[14:15]
	v_pk_add_f32 v[10:11], v[10:11], v[14:15] neg_lo:[0,1] neg_hi:[0,1]
	v_pk_add_f32 v[14:15], v[2:3], v[2:3] op_sel:[1,0]
	v_pk_add_f32 v[2:3], v[2:3], v[2:3] op_sel_hi:[1,0] neg_lo:[0,1] neg_hi:[0,1]
	s_nop 0
	v_mov_b32_e32 v15, v3
	v_xor_b32_e32 v3, 0x80000000, v8
	v_mov_b32_e32 v2, v9
	v_pk_add_f32 v[8:9], v[10:11], v[10:11] op_sel:[1,0] neg_lo:[0,1] neg_hi:[0,1]
	v_pk_add_f32 v[10:11], v[10:11], v[10:11] op_sel_hi:[1,0]
	s_nop 0
	v_mov_b32_e32 v9, v11
	v_pk_add_f32 v[10:11], v[16:17], v[6:7]
	v_pk_add_f32 v[6:7], v[16:17], v[6:7] neg_lo:[0,1] neg_hi:[0,1]
	v_pk_add_f32 v[16:17], v[4:5], v[12:13]
	v_pk_add_f32 v[4:5], v[4:5], v[12:13] neg_lo:[0,1] neg_hi:[0,1]
	v_pk_mul_f32 v[8:9], v[8:9], s[20:21]
	v_xor_b32_e32 v13, 0x80000000, v4
	v_mov_b32_e32 v12, v5
	v_pk_add_f32 v[4:5], v[10:11], v[16:17]
	v_pk_add_f32 v[10:11], v[10:11], v[16:17] neg_lo:[0,1] neg_hi:[0,1]
	v_pk_add_f32 v[16:17], v[6:7], v[12:13]
	v_pk_add_f32 v[6:7], v[6:7], v[12:13] neg_lo:[0,1] neg_hi:[0,1]
	v_pk_add_f32 v[12:13], v[0:1], v[2:3]
	v_pk_add_f32 v[0:1], v[0:1], v[2:3] neg_lo:[0,1] neg_hi:[0,1]
	v_pk_fma_f32 v[2:3], v[14:15], s[20:21], v[8:9] op_sel_hi:[1,0,1]
	v_pk_fma_f32 v[8:9], v[14:15], s[20:21], v[8:9] op_sel_hi:[1,0,1] neg_lo:[0,0,1] neg_hi:[0,0,1]
	s_nop 0
	v_xor_b32_e32 v15, 0x80000000, v8
	v_mov_b32_e32 v14, v9
	v_pk_add_f32 v[8:9], v[12:13], v[2:3]
	v_pk_add_f32 v[2:3], v[12:13], v[2:3] neg_lo:[0,1] neg_hi:[0,1]
	v_pk_add_f32 v[12:13], v[0:1], v[14:15]
	v_pk_add_f32 v[0:1], v[0:1], v[14:15] neg_lo:[0,1] neg_hi:[0,1]
	v_pk_mul_f32 v[24:25], v[18:19], v[8:9] op_sel:[1,1] op_sel_hi:[0,1]
	v_fma_f32 v26, v18, v8, -v24
	v_fma_f32 v27, v19, v8, v25
	s_nop 0
; __device__ __forceinline__ c2 cmul(c2 a, c2 b) { return (c2){a.x * b.x - a.y * b.y, a.x * b.y + a.y * b.x}; }
; template <int S> __device__ __forceinline__ void fwd_mid(c2* buf, const c2* tws, int tid) {
;     constexpr int lq = 9 - 3 * S, Q = 1 << lq; const c2* T = tws + (S == 1 ? 3584 : 4032);
;     const int k = tid & (Q - 1), base = ((tid >> lq) << (lq + 3)) + k;
;     c2 x[8];
;     c2* bp_ = buf + LP(base); constexpr int QP = Q + Q / 8;
; #pragma unroll
;     for (int r = 0; r < 8; ++r) x[r] = bp_[r * QP];
;     dft8(x);
; #pragma unroll
;     for (int q = 1; q < 8; ++q) x[q] = cmul(x[q], T[(q - 1) * Q + k]);
; #pragma unroll
;     for (int q = 0; q < 8; ++q) bp_[q * QP] = x[q];
; }
; __device__ __forceinline__ void fwd_s3(c2 (&x)[8], const c2* buf, int tid) {
; #pragma unroll
;     for (int r = 0; r < 8; ++r) x[r] = buf[9 * tid + r];
;     dft8(x);
; }
; __device__ __forceinline__ QuadRegs quad_load(const bf16_t* zsrc, const bf16_t* gsrc, int gstart, bool joined, bool first, bool last, int tid) {
;     const bf16_t* src = ((tid >> 8) ? gsrc : zsrc) + gstart; const int ci = tid & 255;
;     QuadRegs R;
; #pragma unroll
;     for (int k = 0; k < 4; ++k) { R.v[k] = *(const u32x4*)(src + 2048 * k + 8 * ci); R.h[k] = 0u; }
;     if (joined) {
;         if (ci == 0) {
; #pragma unroll
;             for (int k = 0; k < 4; ++k) if (k > 0 || !first) R.h[k] = src[2048 * k - 1]; }
;         if (ci == 255) {
; #pragma unroll
;             for (int k = 0; k < 4; ++k) if (k < 3 || !last) R.h[k] = src[2048 * (k + 1)]; }
;     }
;     return R;
; }
	v_pk_mul_f32 v[8:9], v[240:241], v[16:17] op_sel:[1,1] op_sel_hi:[0,1]
	v_fma_f32 v18, v240, v16, -v8
	v_fma_f32 v19, v241, v16, v9
	v_pk_mul_f32 v[8:9], v[242:243], v[12:13] op_sel:[1,1] op_sel_hi:[0,1]
	v_fma_f32 v14, v242, v12, -v8
	v_fma_f32 v15, v243, v12, v9
	v_pk_mul_f32 v[20:21], v[246:247], v[2:3] op_sel:[1,1] op_sel_hi:[0,1]
	v_pk_mul_f32 v[8:9], v[10:11], v[244:245] op_sel:[1,1] op_sel_hi:[1,0]
	s_nop 0
	v_fma_f32 v12, v10, v244, -v8
	v_fma_f32 v13, v10, v245, v9
	v_mov_b64_e32 v[10:11], v[250:251]
	v_fma_f32 v22, v246, v2, -v20
	v_fma_f32 v23, v247, v2, v21
	s_nop 0
	v_pk_mul_f32 v[2:3], v[6:7], v[248:249] op_sel:[1,1] op_sel_hi:[1,0]
	s_nop 0
	v_fma_f32 v16, v6, v248, -v2
	v_fma_f32 v17, v6, v249, v3
	v_pk_mul_f32 v[2:3], v[10:11], v[0:1] op_sel:[1,1] op_sel_hi:[0,1]
	v_fma_f32 v6, v10, v0, -v2
	v_fma_f32 v7, v11, v0, v3
	s_nop 0
	v_mov_b32_e32 v0, s78
	v_mov_b32_e32 v1, s79
	v_cndmask_b32_e64 v69, v0, v1, s[0:1]
	v_mov_b32_e32 v0, s68
	v_mov_b32_e32 v1, s69
	v_cndmask_b32_e64 v68, v0, v1, s[0:1]
	v_lshl_add_u64 v[8:9], v[68:69], 0, v[62:63]
	ds_write2_b64 v193, v[4:5], v[26:27] offset1:9
	ds_write2_b64 v193, v[18:19], v[14:15] offset0:18 offset1:27
	ds_write2_b64 v193, v[12:13], v[22:23] offset0:36 offset1:45
	ds_write2_b64 v193, v[16:17], v[6:7] offset0:54 offset1:63
	v_add_co_u32_e32 v4, vcc, s3, v8
	s_movk_i32 s3, 0x3000
	s_nop 0
	v_addc_co_u32_e32 v5, vcc, 0, v9, vcc
	v_add_co_u32_e32 v12, vcc, s3, v8
	s_waitcnt lgkmcnt(0)
	s_nop 0
	v_addc_co_u32_e32 v13, vcc, 0, v9, vcc
	s_barrier
	global_load_dwordx4 v[0:3], v[4:5], off offset:-4096
	s_nop 0
	global_load_dwordx4 v[4:7], v[4:5], off
	s_nop 0
	global_load_dwordx4 v[8:11], v[8:9], off
	s_nop 0
	global_load_dwordx4 v[12:15], v[12:13], off
	ds_read2_b64 v[16:19], v121 offset1:1
	ds_read2_b64 v[20:23], v121 offset0:4 offset1:5
	ds_read2_b64 v[24:27], v121 offset0:2 offset1:3
	ds_read2_b64 v[28:31], v121 offset0:6 offset1:7
	s_waitcnt lgkmcnt(0)
	v_pk_add_f32 v[32:33], v[16:17], v[20:21]
	v_pk_add_f32 v[16:17], v[16:17], v[20:21] neg_lo:[0,1] neg_hi:[0,1]
	v_pk_add_f32 v[20:21], v[18:19], v[22:23]
	v_pk_add_f32 v[18:19], v[18:19], v[22:23] neg_lo:[0,1] neg_hi:[0,1]
	v_pk_add_f32 v[22:23], v[24:25], v[28:29]
	v_pk_add_f32 v[24:25], v[24:25], v[28:29] neg_lo:[0,1] neg_hi:[0,1]
	v_pk_add_f32 v[28:29], v[26:27], v[30:31]
	v_pk_add_f32 v[26:27], v[26:27], v[30:31] neg_lo:[0,1] neg_hi:[0,1]
	v_pk_add_f32 v[34:35], v[18:19], v[18:19] op_sel:[1,0]
	v_pk_add_f32 v[18:19], v[18:19], v[18:19] op_sel_hi:[1,0] neg_lo:[0,1] neg_hi:[0,1]
	v_pk_add_f32 v[30:31], v[20:21], v[28:29]
	v_mov_b32_e32 v35, v19
	v_xor_b32_e32 v19, 0x80000000, v24
	v_mov_b32_e32 v18, v25
	v_pk_add_f32 v[24:25], v[26:27], v[26:27] op_sel:[1,0] neg_lo:[0,1] neg_hi:[0,1]
	v_pk_add_f32 v[26:27], v[26:27], v[26:27] op_sel_hi:[1,0]
	v_pk_add_f32 v[20:21], v[20:21], v[28:29] neg_lo:[0,1] neg_hi:[0,1]
	v_mov_b32_e32 v25, v27
	v_pk_mul_f32 v[36:37], v[24:25], s[20:21]
	v_pk_add_f32 v[26:27], v[32:33], v[22:23]
	v_pk_add_f32 v[22:23], v[32:33], v[22:23] neg_lo:[0,1] neg_hi:[0,1]
	v_xor_b32_e32 v33, 0x80000000, v20
	v_mov_b32_e32 v32, v21
	v_pk_add_f32 v[24:25], v[26:27], v[30:31]
	v_pk_add_f32 v[26:27], v[26:27], v[30:31] neg_lo:[0,1] neg_hi:[0,1]
	v_pk_add_f32 v[28:29], v[22:23], v[32:33]
	v_pk_add_f32 v[30:31], v[22:23], v[32:33] neg_lo:[0,1] neg_hi:[0,1]
	v_pk_fma_f32 v[22:23], v[34:35], s[20:21], v[36:37] op_sel_hi:[1,0,1] neg_lo:[0,0,1] neg_hi:[0,0,1]
	v_pk_add_f32 v[20:21], v[16:17], v[18:19]
	v_pk_add_f32 v[16:17], v[16:17], v[18:19] neg_lo:[0,1] neg_hi:[0,1]
	v_pk_fma_f32 v[18:19], v[34:35], s[20:21], v[36:37] op_sel_hi:[1,0,1]
	v_xor_b32_e32 v39, 0x80000000, v22
	v_mov_b32_e32 v38, v23
	v_pk_add_f32 v[32:33], v[20:21], v[18:19]
	v_pk_add_f32 v[34:35], v[20:21], v[18:19] neg_lo:[0,1] neg_hi:[0,1]
	v_pk_add_f32 v[36:37], v[16:17], v[38:39]
	v_pk_add_f32 v[38:39], v[16:17], v[38:39] neg_lo:[0,1] neg_hi:[0,1]
	v_lshl_add_u64 v[16:17], v[68:69], 0, v[60:61]
	v_pk_mov_b32 v[40:41], v[24:25], v[24:25] op_sel:[1,0]
	v_pk_mov_b32 v[42:43], v[32:33], v[32:33] op_sel:[1,0]
	v_pk_mov_b32 v[44:45], v[28:29], v[28:29] op_sel:[1,0]
	v_pk_mov_b32 v[46:47], v[36:37], v[36:37] op_sel:[1,0]
	v_pk_mov_b32 v[48:49], v[26:27], v[26:27] op_sel:[1,0]
	v_pk_mov_b32 v[50:51], v[34:35], v[34:35] op_sel:[1,0]
	v_pk_mov_b32 v[52:53], v[30:31], v[30:31] op_sel:[1,0]
	v_pk_mov_b32 v[54:55], v[38:39], v[38:39] op_sel:[1,0]
	v_lshl_add_u64 v[68:69], v[16:17], 0, s[28:29]
	s_branch .LBB0_289
; __device__ __forceinline__ c2 cmul(c2 a, c2 b) { return (c2){a.x * b.x - a.y * b.y, a.x * b.y + a.y * b.x}; }
; #define ZVAL(r, t) ((o == 0) ? dwl((r), (t), zw0, zw1, zw2, zb) : bf2f((r)[8 + (t)]))
; __device__ __forceinline__ void fwd_s0(c2 (&x)[8], c2* buf, const c2* tws, int tid) {
;     dft8(x);
; #pragma unroll
;     for (int q = 1; q < 8; ++q) x[q] = cmul(x[q], tws[(q - 1) * 512 + tid]);
;     { c2* bp_ = buf + LP(tid);
; #pragma unroll
;     for (int q = 0; q < 8; ++q) bp_[576 * q] = x[q]; }
; }
; __device__ __forceinline__ void phase_conv(const Params& p, int o, unsigned char* smem, int wave) {
;     ...
;                 c2 x0[8], x1[8], zk0[4], zk1[4];
; #pragma unroll
;                 for (int r = 0; r < 4; ++r) { const int t = tid + 512 * r;
;                     x0[r] = (c2){ZVAL(raw, t), ZVAL(raw + RAWROW, t)}; x1[r] = (c2){ZVAL(raw + 2 * RAWROW, t), ZVAL(raw + 3 * RAWROW, t)}; zk0[r] = x0[r]; zk1[r] = x1[r];
;                     x0[4 + r] = (c2){0.f, 0.f}; x1[4 + r] = (c2){0.f, 0.f}; }
;                 fft_fwd_regs2(x0, x1, buf0, buf1, tws, tid);
.LBB0_288:
	v_pk_add_f32 v[16:17], v[84:85], 0 op_sel_hi:[1,0]
	v_pk_add_f32 v[18:19], v[82:83], 0 op_sel_hi:[1,0]
	v_pk_add_f32 v[20:21], v[78:79], 0 op_sel_hi:[1,0]
	v_pk_add_f32 v[22:23], v[80:81], 0 op_sel_hi:[1,0]
	v_sub_f32_e32 v90, v81, v80
	v_add_f32_e32 v91, v81, v80
	v_add_f32_e32 v86, v83, v82
	v_sub_f32_e32 v87, v83, v82
	v_pk_mul_f32 v[90:91], v[90:91], s[20:21]
	v_pk_add_f32 v[92:93], v[16:17], v[20:21]
	v_pk_add_f32 v[20:21], v[16:17], v[20:21] neg_lo:[0,1] neg_hi:[0,1]
	v_pk_add_f32 v[94:95], v[18:19], v[22:23]
	v_pk_add_f32 v[16:17], v[18:19], v[22:23] neg_lo:[0,1] neg_hi:[0,1]
	v_xor_b32_e32 v89, 0x80000000, v78
	v_mov_b32_e32 v88, v79
	v_xor_b32_e32 v19, 0x80000000, v16
	v_mov_b32_e32 v18, v17
	v_pk_add_f32 v[16:17], v[92:93], v[94:95]
	v_pk_add_f32 v[22:23], v[92:93], v[94:95] neg_lo:[0,1] neg_hi:[0,1]
	v_pk_fma_f32 v[94:95], v[86:87], s[20:21], v[90:91] op_sel_hi:[1,0,1]
	v_pk_fma_f32 v[86:87], v[86:87], s[20:21], v[90:91] op_sel_hi:[1,0,1] neg_lo:[0,0,1] neg_hi:[0,0,1]
	v_pk_add_f32 v[92:93], v[20:21], v[18:19]
	v_pk_add_f32 v[18:19], v[20:21], v[18:19] neg_lo:[0,1] neg_hi:[0,1]
	v_pk_add_f32 v[20:21], v[84:85], v[88:89]
	v_pk_add_f32 v[88:89], v[84:85], v[88:89] neg_lo:[0,1] neg_hi:[0,1]
	v_xor_b32_e32 v91, 0x80000000, v86
	v_mov_b32_e32 v90, v87
	v_pk_add_f32 v[86:87], v[20:21], v[94:95]
	v_pk_add_f32 v[20:21], v[20:21], v[94:95] neg_lo:[0,1] neg_hi:[0,1]
	v_pk_add_f32 v[94:95], v[88:89], v[90:91]
	v_pk_add_f32 v[88:89], v[88:89], v[90:91] neg_lo:[0,1] neg_hi:[0,1]
	v_add_u32_e32 v63, 0x9000, v121
	v_add_u32_e32 v205, 0x9020, v121
	v_add_u32_e32 v204, 0x9010, v121
	v_add_u32_e32 v206, 0x9030, v121
	s_waitcnt lgkmcnt(0)
	v_mul_f32_e32 v96, v87, v211
	v_mul_f32_e32 v98, v86, v211
	v_fma_f32 v96, v86, v210, -v96
	v_fma_f32 v87, v87, v210, v98
	v_mov_b32_e32 v97, v87
	s_mov_b32 s84, s21
	s_mov_b32 s85, s20
	v_lshl_add_u64 v[68:69], v[68:69], 0, s[28:29]
	v_mul_f32_e32 v86, v93, v213
	v_fma_f32 v98, v92, v212, -v86
	v_mul_f32_e32 v86, v92, v213
	v_fma_f32 v99, v93, v212, v86
	v_sub_f32_e32 v90, v71, v70
	v_add_f32_e32 v91, v71, v70
	v_pk_mul_f32 v[90:91], v[90:91], s[20:21]
	v_mul_f32_e32 v86, v95, v215
	v_fma_f32 v100, v94, v214, -v86
	v_mul_f32_e32 v86, v94, v215
	v_fma_f32 v101, v95, v214, v86
	v_mul_f32_e32 v86, v23, v217
	v_fma_f32 v102, v22, v216, -v86
	v_mul_f32_e32 v86, v22, v217
	v_fma_f32 v23, v23, v216, v86
	v_mov_b32_e32 v103, v23
	v_add_f32_e32 v86, v75, v74
	v_sub_f32_e32 v87, v75, v74
	v_mul_f32_e32 v22, v21, v219
	v_fma_f32 v194, v20, v218, -v22
	v_mul_f32_e32 v22, v20, v219
	v_fma_f32 v21, v21, v218, v22
	v_mov_b32_e32 v195, v21
	v_pk_add_f32 v[22:23], v[70:71], 0 op_sel_hi:[1,0]
	v_mul_f32_e32 v20, v19, v221
	v_fma_f32 v196, v18, v220, -v20
	v_mul_f32_e32 v20, v18, v221
	v_fma_f32 v19, v19, v220, v20
	ds_write2st64_b64 v115, v[16:17], v[96:97] offset1:9
	v_mov_b32_e32 v197, v19
	v_pk_add_f32 v[16:17], v[76:77], 0 op_sel_hi:[1,0]
	v_pk_add_f32 v[20:21], v[72:73], 0 op_sel_hi:[1,0]
	s_waitcnt lgkmcnt(0)
	v_mul_f32_e32 v18, v89, v223
	v_fma_f32 v198, v88, v222, -v18
	v_mul_f32_e32 v18, v88, v223
	v_fma_f32 v199, v89, v222, v18
	v_pk_add_f32 v[18:19], v[74:75], 0 op_sel_hi:[1,0]
	v_pk_add_f32 v[92:93], v[16:17], v[20:21]
	v_pk_add_f32 v[20:21], v[16:17], v[20:21] neg_lo:[0,1] neg_hi:[0,1]
	v_pk_add_f32 v[94:95], v[18:19], v[22:23]
	v_pk_add_f32 v[16:17], v[18:19], v[22:23] neg_lo:[0,1] neg_hi:[0,1]
	v_xor_b32_e32 v89, 0x80000000, v72
	v_mov_b32_e32 v88, v73
	v_xor_b32_e32 v19, 0x80000000, v16
	v_mov_b32_e32 v18, v17
	v_pk_add_f32 v[16:17], v[92:93], v[94:95]
	v_pk_add_f32 v[22:23], v[92:93], v[94:95] neg_lo:[0,1] neg_hi:[0,1]
	v_pk_fma_f32 v[94:95], v[86:87], s[20:21], v[90:91] op_sel_hi:[1,0,1]
	v_pk_fma_f32 v[86:87], v[86:87], s[20:21], v[90:91] op_sel_hi:[1,0,1] neg_lo:[0,0,1] neg_hi:[0,0,1]
	ds_write2st64_b64 v115, v[98:99], v[100:101] offset0:18 offset1:27
	ds_write2st64_b64 v115, v[102:103], v[194:195] offset0:36 offset1:45
	ds_write2st64_b64 v115, v[196:197], v[198:199] offset0:54 offset1:63
	v_pk_add_f32 v[92:93], v[20:21], v[18:19]
	v_pk_add_f32 v[18:19], v[20:21], v[18:19] neg_lo:[0,1] neg_hi:[0,1]
	v_pk_add_f32 v[20:21], v[76:77], v[88:89]
	v_pk_add_f32 v[88:89], v[76:77], v[88:89] neg_lo:[0,1] neg_hi:[0,1]
	v_xor_b32_e32 v91, 0x80000000, v86
	v_mov_b32_e32 v90, v87
	v_pk_add_f32 v[86:87], v[20:21], v[94:95]
	v_pk_add_f32 v[20:21], v[20:21], v[94:95] neg_lo:[0,1] neg_hi:[0,1]
	v_pk_add_f32 v[94:95], v[88:89], v[90:91]
	v_pk_add_f32 v[88:89], v[88:89], v[90:91] neg_lo:[0,1] neg_hi:[0,1]
	s_waitcnt lgkmcnt(0)
	v_mul_f32_e32 v96, v87, v211
	v_mul_f32_e32 v98, v86, v211
	v_fma_f32 v96, v86, v210, -v96
	v_fma_f32 v87, v87, v210, v98
	v_mov_b32_e32 v97, v87
	v_mul_f32_e32 v86, v93, v213
	v_fma_f32 v98, v92, v212, -v86
	v_mul_f32_e32 v86, v92, v213
	v_fma_f32 v99, v93, v212, v86
	v_mul_f32_e32 v86, v95, v215
	v_fma_f32 v100, v94, v214, -v86
	v_mul_f32_e32 v86, v94, v215
	v_fma_f32 v101, v95, v214, v86
	v_mul_f32_e32 v86, v23, v217
	v_fma_f32 v102, v22, v216, -v86
	v_mul_f32_e32 v86, v22, v217
	v_fma_f32 v23, v23, v216, v86
	v_mov_b32_e32 v103, v23
	v_mul_f32_e32 v22, v21, v219
	v_fma_f32 v194, v20, v218, -v22
	v_mul_f32_e32 v22, v20, v219
	v_fma_f32 v21, v21, v218, v22
	v_mov_b32_e32 v195, v21
	v_mul_f32_e32 v20, v19, v221
	v_fma_f32 v196, v18, v220, -v20
	v_mul_f32_e32 v20, v18, v221
	v_fma_f32 v19, v19, v220, v20
	v_mov_b64_e32 v[94:95], v[222:223]
	v_mov_b32_e32 v197, v19
	ds_write2st64_b64 v115, v[16:17], v[96:97] offset0:72 offset1:81
	ds_write2st64_b64 v115, v[98:99], v[100:101] offset0:90 offset1:99
	ds_write2st64_b64 v115, v[102:103], v[194:195] offset0:108 offset1:117
	s_waitcnt lgkmcnt(0)
	v_mul_f32_e32 v18, v89, v95
	v_fma_f32 v198, v88, v94, -v18
	v_mul_f32_e32 v18, v88, v95
	v_fma_f32 v199, v89, v94, v18
	ds_write_b64 v115, v[196:197] offset:64512
	ds_write_b64 v116, v[198:199] offset:32256
	s_waitcnt lgkmcnt(0)
	s_barrier
; __device__ __forceinline__ c2 cmul(c2 a, c2 b) { return (c2){a.x * b.x - a.y * b.y, a.x * b.y + a.y * b.x}; }
; __device__ __forceinline__ c2 mni(c2 a) { return (c2){a.y, -a.x}; }
; __device__ __forceinline__ void dft8(c2 (&x)[8]) {
;     const float s = 0.70710678118654752f;
;     const c2 a0 = x[0] + x[4], a4 = x[0] - x[4], a1 = x[1] + x[5], a5 = x[1] - x[5], a2 = x[2] + x[6], a6 = x[2] - x[6], a3 = x[3] + x[7], a7 = x[3] - x[7];
;     const c2 a5w = (c2){(a5.x + a5.y) * s, (a5.y - a5.x) * s};
;     const c2 a6w = mni(a6);
;     const c2 a7w = (c2){(a7.y - a7.x) * s, -(a7.x + a7.y) * s};
;     const c2 b0 = a0 + a2, b1 = a0 - a2, b2 = a1 + a3, b3 = mni(a1 - a3);
;     x[0] = b0 + b2; x[4] = b0 - b2; x[2] = b1 + b3; x[6] = b1 - b3;
;     const c2 c0 = a4 + a6w, c1 = a4 - a6w, c2_ = a5w + a7w, c3 = mni(a5w - a7w);
;     x[1] = c0 + c2_; x[5] = c0 - c2_; x[3] = c1 + c3; x[7] = c1 - c3;
; }
; template <int S> __device__ __forceinline__ void fwd_mid(c2* buf, const c2* tws, int tid) {
;     constexpr int lq = 9 - 3 * S, Q = 1 << lq; const c2* T = tws + (S == 1 ? 3584 : 4032);
;     const int k = tid & (Q - 1), base = ((tid >> lq) << (lq + 3)) + k;
;     c2 x[8];
;     c2* bp_ = buf + LP(base); constexpr int QP = Q + Q / 8;
; #pragma unroll
;     for (int r = 0; r < 8; ++r) x[r] = bp_[r * QP];
;     dft8(x);
; #pragma unroll
;     for (int q = 1; q < 8; ++q) x[q] = cmul(x[q], T[(q - 1) * Q + k]);
; #pragma unroll
;     for (int q = 0; q < 8; ++q) bp_[q * QP] = x[q];
; }
	ds_read2_b64 v[16:19], v117 offset1:72
	ds_read2_b64 v[20:23], v117 offset0:144 offset1:216
	ds_read2_b64 v[86:89], v56 offset0:32 offset1:104
	ds_read2_b64 v[90:93], v56 offset0:176 offset1:248
	s_waitcnt lgkmcnt(0)
	v_pk_add_f32 v[94:95], v[16:17], v[86:87]
	v_pk_add_f32 v[16:17], v[16:17], v[86:87] neg_lo:[0,1] neg_hi:[0,1]
	v_pk_add_f32 v[86:87], v[18:19], v[88:89]
	v_pk_add_f32 v[18:19], v[18:19], v[88:89] neg_lo:[0,1] neg_hi:[0,1]
	v_pk_add_f32 v[88:89], v[20:21], v[90:91]
	v_pk_add_f32 v[20:21], v[20:21], v[90:91] neg_lo:[0,1] neg_hi:[0,1]
	v_pk_add_f32 v[90:91], v[22:23], v[92:93]
	v_pk_add_f32 v[22:23], v[22:23], v[92:93] neg_lo:[0,1] neg_hi:[0,1]
	v_pk_add_f32 v[92:93], v[18:19], v[18:19] op_sel:[1,0]
	v_pk_add_f32 v[18:19], v[18:19], v[18:19] op_sel_hi:[1,0] neg_lo:[0,1] neg_hi:[0,1]
	s_nop 0
	v_mov_b32_e32 v93, v19
	v_xor_b32_e32 v19, 0x80000000, v20
	v_mov_b32_e32 v18, v21
	v_pk_add_f32 v[20:21], v[22:23], v[22:23] op_sel:[1,0] neg_lo:[0,1] neg_hi:[0,1]
	v_pk_add_f32 v[22:23], v[22:23], v[22:23] op_sel_hi:[1,0]
	s_nop 0
	v_mov_b32_e32 v21, v23
	v_pk_add_f32 v[22:23], v[94:95], v[88:89]
	v_pk_add_f32 v[88:89], v[94:95], v[88:89] neg_lo:[0,1] neg_hi:[0,1]
	v_pk_add_f32 v[94:95], v[86:87], v[90:91]
	v_pk_add_f32 v[86:87], v[86:87], v[90:91] neg_lo:[0,1] neg_hi:[0,1]
	v_pk_mul_f32 v[20:21], v[20:21], s[20:21]
	v_xor_b32_e32 v91, 0x80000000, v86
	v_mov_b32_e32 v90, v87
	v_pk_add_f32 v[86:87], v[22:23], v[94:95]
	v_pk_add_f32 v[22:23], v[22:23], v[94:95] neg_lo:[0,1] neg_hi:[0,1]
	v_pk_add_f32 v[94:95], v[88:89], v[90:91]
	v_pk_add_f32 v[88:89], v[88:89], v[90:91] neg_lo:[0,1] neg_hi:[0,1]
	v_pk_add_f32 v[90:91], v[16:17], v[18:19]
	v_pk_add_f32 v[16:17], v[16:17], v[18:19] neg_lo:[0,1] neg_hi:[0,1]
	v_pk_fma_f32 v[18:19], v[92:93], s[20:21], v[20:21] op_sel_hi:[1,0,1]
	v_pk_fma_f32 v[20:21], v[92:93], s[20:21], v[20:21] op_sel_hi:[1,0,1] neg_lo:[0,0,1] neg_hi:[0,0,1]
	s_nop 0
	v_xor_b32_e32 v93, 0x80000000, v20
	v_mov_b32_e32 v92, v21
	v_pk_add_f32 v[20:21], v[90:91], v[18:19]
	v_pk_add_f32 v[18:19], v[90:91], v[18:19] neg_lo:[0,1] neg_hi:[0,1]
	v_pk_add_f32 v[90:91], v[16:17], v[92:93]
	v_pk_add_f32 v[16:17], v[16:17], v[92:93] neg_lo:[0,1] neg_hi:[0,1]
	v_pk_mul_f32 v[96:97], v[224:225], v[20:21] op_sel:[1,1] op_sel_hi:[0,1]
	v_fma_f32 v98, v224, v20, -v96
	v_fma_f32 v99, v225, v20, v97
	s_nop 0
	v_pk_mul_f32 v[92:93], v[226:227], v[94:95] op_sel:[1,1] op_sel_hi:[0,1]
	v_fma_f32 v96, v226, v94, -v92
	v_fma_f32 v97, v227, v94, v93
	s_nop 0
	v_pk_mul_f32 v[92:93], v[228:229], v[90:91] op_sel:[1,1] op_sel_hi:[0,1]
	v_fma_f32 v94, v228, v90, -v92
	v_fma_f32 v95, v229, v90, v93
	s_nop 0
	v_pk_mul_f32 v[90:91], v[22:23], v[230:231] op_sel:[1,1] op_sel_hi:[1,0]
	s_nop 0
	v_fma_f32 v92, v22, v230, -v90
	v_fma_f32 v93, v22, v231, v91
	v_pk_mul_f32 v[22:23], v[232:233], v[18:19] op_sel:[1,1] op_sel_hi:[0,1]
	v_fma_f32 v90, v232, v18, -v22
	v_fma_f32 v91, v233, v18, v23
	s_nop 0
	v_pk_mul_f32 v[20:21], v[88:89], v[234:235] op_sel:[1,1] op_sel_hi:[1,0]
	s_nop 0
	v_fma_f32 v22, v88, v234, -v20
	v_fma_f32 v23, v88, v235, v21
	v_mov_b64_e32 v[18:19], v[236:237]
	v_pk_mul_f32 v[20:21], v[18:19], v[16:17] op_sel:[1,1] op_sel_hi:[0,1]
	v_fma_f32 v88, v18, v16, -v20
	v_fma_f32 v89, v19, v16, v21
	s_nop 0
	ds_write2_b64 v117, v[86:87], v[98:99] offset1:72
	ds_write2_b64 v117, v[96:97], v[94:95] offset0:144 offset1:216
	ds_write2_b64 v56, v[92:93], v[90:91] offset0:32 offset1:104
	ds_write2_b64 v56, v[22:23], v[88:89] offset0:176 offset1:248
	ds_read2_b64 v[16:19], v191 offset1:72
	ds_read2_b64 v[20:23], v191 offset0:144 offset1:216
	ds_read2_b64 v[86:89], v192 offset0:32 offset1:104
	ds_read2_b64 v[90:93], v192 offset0:176 offset1:248
	s_waitcnt lgkmcnt(0)
	v_pk_add_f32 v[94:95], v[16:17], v[86:87]
	v_pk_add_f32 v[16:17], v[16:17], v[86:87] neg_lo:[0,1] neg_hi:[0,1]
	v_pk_add_f32 v[86:87], v[18:19], v[88:89]
	v_pk_add_f32 v[18:19], v[18:19], v[88:89] neg_lo:[0,1] neg_hi:[0,1]
	v_pk_add_f32 v[88:89], v[20:21], v[90:91]
	v_pk_add_f32 v[20:21], v[20:21], v[90:91] neg_lo:[0,1] neg_hi:[0,1]
	v_pk_add_f32 v[90:91], v[22:23], v[92:93]
	v_pk_add_f32 v[22:23], v[22:23], v[92:93] neg_lo:[0,1] neg_hi:[0,1]
	v_pk_add_f32 v[92:93], v[18:19], v[18:19] op_sel:[1,0]
	v_pk_add_f32 v[18:19], v[18:19], v[18:19] op_sel_hi:[1,0] neg_lo:[0,1] neg_hi:[0,1]
	s_nop 0
	v_mov_b32_e32 v93, v19
	v_xor_b32_e32 v19, 0x80000000, v20
	v_mov_b32_e32 v18, v21
	v_pk_add_f32 v[20:21], v[22:23], v[22:23] op_sel:[1,0] neg_lo:[0,1] neg_hi:[0,1]
	v_pk_add_f32 v[22:23], v[22:23], v[22:23] op_sel_hi:[1,0]
	s_nop 0
	v_mov_b32_e32 v21, v23
	v_pk_add_f32 v[22:23], v[94:95], v[88:89]
	v_pk_add_f32 v[88:89], v[94:95], v[88:89] neg_lo:[0,1] neg_hi:[0,1]
	v_pk_add_f32 v[94:95], v[86:87], v[90:91]
	v_pk_add_f32 v[86:87], v[86:87], v[90:91] neg_lo:[0,1] neg_hi:[0,1]
	v_pk_mul_f32 v[20:21], v[20:21], s[20:21]
	v_xor_b32_e32 v91, 0x80000000, v86
	v_mov_b32_e32 v90, v87
	v_pk_add_f32 v[86:87], v[22:23], v[94:95]
	v_pk_add_f32 v[22:23], v[22:23], v[94:95] neg_lo:[0,1] neg_hi:[0,1]
	v_pk_add_f32 v[94:95], v[88:89], v[90:91]
	v_pk_add_f32 v[88:89], v[88:89], v[90:91] neg_lo:[0,1] neg_hi:[0,1]
	v_pk_add_f32 v[90:91], v[16:17], v[18:19]
	v_pk_add_f32 v[16:17], v[16:17], v[18:19] neg_lo:[0,1] neg_hi:[0,1]
	v_pk_fma_f32 v[18:19], v[92:93], s[20:21], v[20:21] op_sel_hi:[1,0,1]
	v_pk_fma_f32 v[20:21], v[92:93], s[20:21], v[20:21] op_sel_hi:[1,0,1] neg_lo:[0,0,1] neg_hi:[0,0,1]
	s_nop 0
	v_xor_b32_e32 v93, 0x80000000, v20
	v_mov_b32_e32 v92, v21
	v_pk_add_f32 v[20:21], v[90:91], v[18:19]
	v_pk_add_f32 v[18:19], v[90:91], v[18:19] neg_lo:[0,1] neg_hi:[0,1]
	v_pk_add_f32 v[90:91], v[16:17], v[92:93]
	v_pk_add_f32 v[16:17], v[16:17], v[92:93] neg_lo:[0,1] neg_hi:[0,1]
	v_pk_mul_f32 v[96:97], v[224:225], v[20:21] op_sel:[1,1] op_sel_hi:[0,1]
	v_fma_f32 v98, v224, v20, -v96
	v_fma_f32 v99, v225, v20, v97
	s_nop 0
	v_pk_mul_f32 v[92:93], v[226:227], v[94:95] op_sel:[1,1] op_sel_hi:[0,1]
	v_fma_f32 v96, v226, v94, -v92
	v_fma_f32 v97, v227, v94, v93
	s_nop 0
	v_pk_mul_f32 v[92:93], v[228:229], v[90:91] op_sel:[1,1] op_sel_hi:[0,1]
	v_fma_f32 v94, v228, v90, -v92
	v_fma_f32 v95, v229, v90, v93
	s_nop 0
	v_pk_mul_f32 v[90:91], v[22:23], v[230:231] op_sel:[1,1] op_sel_hi:[1,0]
	s_nop 0
	v_fma_f32 v92, v22, v230, -v90
	v_fma_f32 v93, v22, v231, v91
	v_pk_mul_f32 v[22:23], v[232:233], v[18:19] op_sel:[1,1] op_sel_hi:[0,1]
	v_fma_f32 v90, v232, v18, -v22
	v_fma_f32 v91, v233, v18, v23
	s_nop 0
	v_pk_mul_f32 v[20:21], v[88:89], v[234:235] op_sel:[1,1] op_sel_hi:[1,0]
	s_nop 0
	v_fma_f32 v22, v88, v234, -v20
	v_fma_f32 v23, v88, v235, v21
	v_mov_b64_e32 v[18:19], v[236:237]
	v_pk_mul_f32 v[20:21], v[18:19], v[16:17] op_sel:[1,1] op_sel_hi:[0,1]
	v_fma_f32 v88, v18, v16, -v20
	v_fma_f32 v89, v19, v16, v21
	s_nop 0
	ds_write2_b64 v191, v[86:87], v[98:99] offset1:72
	ds_write2_b64 v191, v[96:97], v[94:95] offset0:144 offset1:216
	ds_write2_b64 v192, v[92:93], v[90:91] offset0:32 offset1:104
	ds_write2_b64 v192, v[22:23], v[88:89] offset0:176 offset1:248
	s_waitcnt lgkmcnt(0)
	s_barrier
; __device__ __forceinline__ c2 cmul(c2 a, c2 b) { return (c2){a.x * b.x - a.y * b.y, a.x * b.y + a.y * b.x}; }
; __device__ __forceinline__ c2 mni(c2 a) { return (c2){a.y, -a.x}; }
; __device__ __forceinline__ void dft8(c2 (&x)[8]) {
;     const float s = 0.70710678118654752f;
;     const c2 a0 = x[0] + x[4], a4 = x[0] - x[4], a1 = x[1] + x[5], a5 = x[1] - x[5], a2 = x[2] + x[6], a6 = x[2] - x[6], a3 = x[3] + x[7], a7 = x[3] - x[7];
;     const c2 a5w = (c2){(a5.x + a5.y) * s, (a5.y - a5.x) * s};
;     const c2 a6w = mni(a6);
;     const c2 a7w = (c2){(a7.y - a7.x) * s, -(a7.x + a7.y) * s};
;     const c2 b0 = a0 + a2, b1 = a0 - a2, b2 = a1 + a3, b3 = mni(a1 - a3);
;     x[0] = b0 + b2; x[4] = b0 - b2; x[2] = b1 + b3; x[6] = b1 - b3;
;     const c2 c0 = a4 + a6w, c1 = a4 - a6w, c2_ = a5w + a7w, c3 = mni(a5w - a7w);
;     x[1] = c0 + c2_; x[5] = c0 - c2_; x[3] = c1 + c3; x[7] = c1 - c3;
; }
; template <int S> __device__ __forceinline__ void fwd_mid(c2* buf, const c2* tws, int tid) {
;     constexpr int lq = 9 - 3 * S, Q = 1 << lq; const c2* T = tws + (S == 1 ? 3584 : 4032);
;     const int k = tid & (Q - 1), base = ((tid >> lq) << (lq + 3)) + k;
;     c2 x[8];
;     c2* bp_ = buf + LP(base); constexpr int QP = Q + Q / 8;
; #pragma unroll
;     for (int r = 0; r < 8; ++r) x[r] = bp_[r * QP];
;     dft8(x);
; #pragma unroll
;     for (int q = 1; q < 8; ++q) x[q] = cmul(x[q], T[(q - 1) * Q + k]);
; #pragma unroll
;     for (int q = 0; q < 8; ++q) bp_[q * QP] = x[q];
; }
	ds_read2_b64 v[16:19], v119 offset1:9
	ds_read2_b64 v[20:23], v119 offset0:18 offset1:27
	ds_read2_b64 v[86:89], v119 offset0:36 offset1:45
	ds_read2_b64 v[90:93], v119 offset0:54 offset1:63
	s_waitcnt lgkmcnt(0)
	v_pk_add_f32 v[94:95], v[16:17], v[86:87]
	v_pk_add_f32 v[16:17], v[16:17], v[86:87] neg_lo:[0,1] neg_hi:[0,1]
	v_pk_add_f32 v[86:87], v[18:19], v[88:89]
	v_pk_add_f32 v[18:19], v[18:19], v[88:89] neg_lo:[0,1] neg_hi:[0,1]
	v_pk_add_f32 v[88:89], v[20:21], v[90:91]
	v_pk_add_f32 v[20:21], v[20:21], v[90:91] neg_lo:[0,1] neg_hi:[0,1]
	v_pk_add_f32 v[90:91], v[22:23], v[92:93]
	v_pk_add_f32 v[22:23], v[22:23], v[92:93] neg_lo:[0,1] neg_hi:[0,1]
	v_pk_add_f32 v[92:93], v[18:19], v[18:19] op_sel:[1,0]
	v_pk_add_f32 v[18:19], v[18:19], v[18:19] op_sel_hi:[1,0] neg_lo:[0,1] neg_hi:[0,1]
	s_nop 0
	v_mov_b32_e32 v93, v19
	v_xor_b32_e32 v19, 0x80000000, v20
	v_mov_b32_e32 v18, v21
	v_pk_add_f32 v[20:21], v[22:23], v[22:23] op_sel:[1,0] neg_lo:[0,1] neg_hi:[0,1]
	v_pk_add_f32 v[22:23], v[22:23], v[22:23] op_sel_hi:[1,0]
	s_nop 0
	v_mov_b32_e32 v21, v23
	v_pk_add_f32 v[22:23], v[94:95], v[88:89]
	v_pk_add_f32 v[88:89], v[94:95], v[88:89] neg_lo:[0,1] neg_hi:[0,1]
	v_pk_add_f32 v[94:95], v[86:87], v[90:91]
	v_pk_add_f32 v[86:87], v[86:87], v[90:91] neg_lo:[0,1] neg_hi:[0,1]
	v_pk_mul_f32 v[20:21], v[20:21], s[20:21]
	v_xor_b32_e32 v91, 0x80000000, v86
	v_mov_b32_e32 v90, v87
	v_pk_add_f32 v[86:87], v[22:23], v[94:95]
	v_pk_add_f32 v[22:23], v[22:23], v[94:95] neg_lo:[0,1] neg_hi:[0,1]
	v_pk_add_f32 v[94:95], v[88:89], v[90:91]
	v_pk_add_f32 v[88:89], v[88:89], v[90:91] neg_lo:[0,1] neg_hi:[0,1]
	v_pk_add_f32 v[90:91], v[16:17], v[18:19]
	v_pk_add_f32 v[16:17], v[16:17], v[18:19] neg_lo:[0,1] neg_hi:[0,1]
	v_pk_fma_f32 v[18:19], v[92:93], s[20:21], v[20:21] op_sel_hi:[1,0,1]
	v_pk_fma_f32 v[20:21], v[92:93], s[20:21], v[20:21] op_sel_hi:[1,0,1] neg_lo:[0,0,1] neg_hi:[0,0,1]
	s_nop 0
	v_xor_b32_e32 v93, 0x80000000, v20
	v_mov_b32_e32 v92, v21
	v_pk_add_f32 v[20:21], v[90:91], v[18:19]
	v_pk_add_f32 v[18:19], v[90:91], v[18:19] neg_lo:[0,1] neg_hi:[0,1]
	v_pk_add_f32 v[90:91], v[16:17], v[92:93]
	v_pk_add_f32 v[16:17], v[16:17], v[92:93] neg_lo:[0,1] neg_hi:[0,1]
	v_pk_mul_f32 v[96:97], v[238:239], v[20:21] op_sel:[1,1] op_sel_hi:[0,1]
	v_fma_f32 v98, v238, v20, -v96
	v_fma_f32 v99, v239, v20, v97
	s_nop 0
	v_pk_mul_f32 v[92:93], v[240:241], v[94:95] op_sel:[1,1] op_sel_hi:[0,1]
	v_fma_f32 v96, v240, v94, -v92
	v_fma_f32 v97, v241, v94, v93
	s_nop 0
	v_pk_mul_f32 v[92:93], v[242:243], v[90:91] op_sel:[1,1] op_sel_hi:[0,1]
	v_fma_f32 v94, v242, v90, -v92
	v_fma_f32 v95, v243, v90, v93
	s_nop 0
	v_pk_mul_f32 v[90:91], v[22:23], v[244:245] op_sel:[1,1] op_sel_hi:[1,0]
	s_nop 0
	v_fma_f32 v92, v22, v244, -v90
	v_fma_f32 v93, v22, v245, v91
	v_pk_mul_f32 v[22:23], v[246:247], v[18:19] op_sel:[1,1] op_sel_hi:[0,1]
	v_fma_f32 v90, v246, v18, -v22
	v_fma_f32 v91, v247, v18, v23
	s_nop 0
	v_pk_mul_f32 v[20:21], v[88:89], v[248:249] op_sel:[1,1] op_sel_hi:[1,0]
	s_nop 0
	v_fma_f32 v22, v88, v248, -v20
	v_fma_f32 v23, v88, v249, v21
	v_mov_b64_e32 v[18:19], v[250:251]
	v_pk_mul_f32 v[20:21], v[18:19], v[16:17] op_sel:[1,1] op_sel_hi:[0,1]
	v_fma_f32 v88, v18, v16, -v20
	v_fma_f32 v89, v19, v16, v21
	s_nop 0
	ds_write2_b64 v119, v[86:87], v[98:99] offset1:9
	ds_write2_b64 v119, v[96:97], v[94:95] offset0:18 offset1:27
	ds_write2_b64 v119, v[92:93], v[90:91] offset0:36 offset1:45
	ds_write2_b64 v119, v[22:23], v[88:89] offset0:54 offset1:63
	ds_read2_b64 v[16:19], v193 offset1:9
	ds_read2_b64 v[20:23], v193 offset0:18 offset1:27
	ds_read2_b64 v[86:89], v193 offset0:36 offset1:45
	ds_read2_b64 v[90:93], v193 offset0:54 offset1:63
	s_waitcnt lgkmcnt(0)
	v_pk_add_f32 v[94:95], v[16:17], v[86:87]
	v_pk_add_f32 v[16:17], v[16:17], v[86:87] neg_lo:[0,1] neg_hi:[0,1]
	v_pk_add_f32 v[86:87], v[18:19], v[88:89]
	v_pk_add_f32 v[18:19], v[18:19], v[88:89] neg_lo:[0,1] neg_hi:[0,1]
	v_pk_add_f32 v[88:89], v[20:21], v[90:91]
	v_pk_add_f32 v[20:21], v[20:21], v[90:91] neg_lo:[0,1] neg_hi:[0,1]
	v_pk_add_f32 v[90:91], v[22:23], v[92:93]
	v_pk_add_f32 v[22:23], v[22:23], v[92:93] neg_lo:[0,1] neg_hi:[0,1]
	v_pk_add_f32 v[92:93], v[18:19], v[18:19] op_sel:[1,0]
	v_pk_add_f32 v[18:19], v[18:19], v[18:19] op_sel_hi:[1,0] neg_lo:[0,1] neg_hi:[0,1]
	s_nop 0
	v_mov_b32_e32 v93, v19
	v_xor_b32_e32 v19, 0x80000000, v20
	v_mov_b32_e32 v18, v21
	v_pk_add_f32 v[20:21], v[22:23], v[22:23] op_sel:[1,0] neg_lo:[0,1] neg_hi:[0,1]
	v_pk_add_f32 v[22:23], v[22:23], v[22:23] op_sel_hi:[1,0]
	s_nop 0
	v_mov_b32_e32 v21, v23
	v_pk_add_f32 v[22:23], v[94:95], v[88:89]
	v_pk_add_f32 v[88:89], v[94:95], v[88:89] neg_lo:[0,1] neg_hi:[0,1]
	v_pk_add_f32 v[94:95], v[86:87], v[90:91]
	v_pk_add_f32 v[86:87], v[86:87], v[90:91] neg_lo:[0,1] neg_hi:[0,1]
	v_pk_mul_f32 v[20:21], v[20:21], s[20:21]
	v_xor_b32_e32 v91, 0x80000000, v86
	v_mov_b32_e32 v90, v87
	v_pk_add_f32 v[86:87], v[22:23], v[94:95]
	v_pk_add_f32 v[22:23], v[22:23], v[94:95] neg_lo:[0,1] neg_hi:[0,1]
	v_pk_add_f32 v[94:95], v[88:89], v[90:91]
	v_pk_add_f32 v[88:89], v[88:89], v[90:91] neg_lo:[0,1] neg_hi:[0,1]
	v_pk_add_f32 v[90:91], v[16:17], v[18:19]
	v_pk_add_f32 v[16:17], v[16:17], v[18:19] neg_lo:[0,1] neg_hi:[0,1]
	v_pk_fma_f32 v[18:19], v[92:93], s[20:21], v[20:21] op_sel_hi:[1,0,1]
	v_pk_fma_f32 v[20:21], v[92:93], s[20:21], v[20:21] op_sel_hi:[1,0,1] neg_lo:[0,0,1] neg_hi:[0,0,1]
	s_nop 0
	v_xor_b32_e32 v93, 0x80000000, v20
	v_mov_b32_e32 v92, v21
	v_pk_add_f32 v[20:21], v[90:91], v[18:19]
	v_pk_add_f32 v[18:19], v[90:91], v[18:19] neg_lo:[0,1] neg_hi:[0,1]
	v_pk_add_f32 v[90:91], v[16:17], v[92:93]
	v_pk_add_f32 v[16:17], v[16:17], v[92:93] neg_lo:[0,1] neg_hi:[0,1]
	v_pk_mul_f32 v[96:97], v[238:239], v[20:21] op_sel:[1,1] op_sel_hi:[0,1]
	v_fma_f32 v98, v238, v20, -v96
	v_fma_f32 v99, v239, v20, v97
	s_nop 0
	v_pk_mul_f32 v[92:93], v[240:241], v[94:95] op_sel:[1,1] op_sel_hi:[0,1]
	v_fma_f32 v96, v240, v94, -v92
	v_fma_f32 v97, v241, v94, v93
	s_nop 0
	v_pk_mul_f32 v[92:93], v[242:243], v[90:91] op_sel:[1,1] op_sel_hi:[0,1]
	v_fma_f32 v94, v242, v90, -v92
	v_fma_f32 v95, v243, v90, v93
	s_nop 0
	v_pk_mul_f32 v[90:91], v[22:23], v[244:245] op_sel:[1,1] op_sel_hi:[1,0]
	s_nop 0
	v_fma_f32 v92, v22, v244, -v90
	v_fma_f32 v93, v22, v245, v91
	v_pk_mul_f32 v[22:23], v[246:247], v[18:19] op_sel:[1,1] op_sel_hi:[0,1]
	v_fma_f32 v90, v246, v18, -v22
	v_fma_f32 v91, v247, v18, v23
	s_nop 0
	v_pk_mul_f32 v[20:21], v[88:89], v[248:249] op_sel:[1,1] op_sel_hi:[1,0]
	s_nop 0
	v_fma_f32 v22, v88, v248, -v20
	v_fma_f32 v23, v88, v249, v21
	v_mov_b64_e32 v[18:19], v[250:251]
	v_pk_mul_f32 v[20:21], v[18:19], v[16:17] op_sel:[1,1] op_sel_hi:[0,1]
	v_fma_f32 v88, v18, v16, -v20
	v_fma_f32 v89, v19, v16, v21
	s_nop 0
	ds_write2_b64 v193, v[86:87], v[98:99] offset1:9
	ds_write2_b64 v193, v[96:97], v[94:95] offset0:18 offset1:27
	ds_write2_b64 v193, v[92:93], v[90:91] offset0:36 offset1:45
	ds_write2_b64 v193, v[22:23], v[88:89] offset0:54 offset1:63
	s_waitcnt lgkmcnt(0)
	s_barrier
; __device__ __forceinline__ c2 cmul(c2 a, c2 b) { return (c2){a.x * b.x - a.y * b.y, a.x * b.y + a.y * b.x}; }
; __device__ __forceinline__ c2 mni(c2 a) { return (c2){a.y, -a.x}; }
; __device__ __forceinline__ void dft8(c2 (&x)[8]) {
;     const float s = 0.70710678118654752f;
;     const c2 a0 = x[0] + x[4], a4 = x[0] - x[4], a1 = x[1] + x[5], a5 = x[1] - x[5], a2 = x[2] + x[6], a6 = x[2] - x[6], a3 = x[3] + x[7], a7 = x[3] - x[7];
;     const c2 a5w = (c2){(a5.x + a5.y) * s, (a5.y - a5.x) * s};
;     const c2 a6w = mni(a6);
;     const c2 a7w = (c2){(a7.y - a7.x) * s, -(a7.x + a7.y) * s};
;     const c2 b0 = a0 + a2, b1 = a0 - a2, b2 = a1 + a3, b3 = mni(a1 - a3);
;     x[0] = b0 + b2; x[4] = b0 - b2; x[2] = b1 + b3; x[6] = b1 - b3;
;     const c2 c0 = a4 + a6w, c1 = a4 - a6w, c2_ = a5w + a7w, c3 = mni(a5w - a7w);
;     x[1] = c0 + c2_; x[5] = c0 - c2_; x[3] = c1 + c3; x[7] = c1 - c3;
; }
; __device__ __forceinline__ void phase_conv(const Params& p, int o, unsigned char* smem, int wave) {
;     ...
;                 fft_fwd_regs2(x0, x1, buf0, buf1, tws, tid);
; #pragma unroll
;                 for (int q = 0; q < 8; ++q) { x0[q] = cmul(x0[q], K[q]); x1[q] = cmul(x1[q], K[q]); }
;                 fft_inv_regs2(x0, x1, buf0, buf1, tws, tid);
	ds_read2_b64 v[16:19], v121 offset1:1
	ds_read2_b64 v[20:23], v121 offset0:2 offset1:3
	ds_read2_b64 v[86:89], v121 offset0:4 offset1:5
	ds_read2_b64 v[90:93], v121 offset0:6 offset1:7
	s_waitcnt lgkmcnt(0)
	v_pk_add_f32 v[94:95], v[16:17], v[86:87]
	v_pk_add_f32 v[16:17], v[16:17], v[86:87] neg_lo:[0,1] neg_hi:[0,1]
	v_pk_add_f32 v[86:87], v[18:19], v[88:89]
	v_pk_add_f32 v[18:19], v[18:19], v[88:89] neg_lo:[0,1] neg_hi:[0,1]
	v_pk_add_f32 v[88:89], v[20:21], v[90:91]
	v_pk_add_f32 v[20:21], v[20:21], v[90:91] neg_lo:[0,1] neg_hi:[0,1]
	v_pk_add_f32 v[90:91], v[22:23], v[92:93]
	v_pk_add_f32 v[22:23], v[22:23], v[92:93] neg_lo:[0,1] neg_hi:[0,1]
	v_pk_add_f32 v[92:93], v[18:19], v[18:19] op_sel:[1,0]
	v_pk_add_f32 v[18:19], v[18:19], v[18:19] op_sel_hi:[1,0] neg_lo:[0,1] neg_hi:[0,1]
	s_nop 0
	v_mov_b32_e32 v93, v19
	v_xor_b32_e32 v19, 0x80000000, v20
	v_mov_b32_e32 v18, v21
	v_pk_add_f32 v[20:21], v[22:23], v[22:23] op_sel:[1,0] neg_lo:[0,1] neg_hi:[0,1]
	v_pk_add_f32 v[22:23], v[22:23], v[22:23] op_sel_hi:[1,0]
	s_nop 0
	v_mov_b32_e32 v21, v23
	v_pk_mul_f32 v[20:21], v[20:21], s[20:21]
	v_pk_add_f32 v[22:23], v[94:95], v[88:89]
	v_pk_add_f32 v[88:89], v[94:95], v[88:89] neg_lo:[0,1] neg_hi:[0,1]
	v_pk_add_f32 v[94:95], v[86:87], v[90:91]
	v_pk_add_f32 v[86:87], v[86:87], v[90:91] neg_lo:[0,1] neg_hi:[0,1]
	v_pk_add_f32 v[96:97], v[22:23], v[94:95]
	v_pk_add_f32 v[94:95], v[22:23], v[94:95] neg_lo:[0,1] neg_hi:[0,1]
	v_pk_add_f32 v[22:23], v[16:17], v[18:19]
	v_pk_add_f32 v[16:17], v[16:17], v[18:19] neg_lo:[0,1] neg_hi:[0,1]
	v_pk_fma_f32 v[18:19], v[92:93], s[20:21], v[20:21] op_sel_hi:[1,0,1]
	v_pk_fma_f32 v[20:21], v[92:93], s[20:21], v[20:21] op_sel_hi:[1,0,1] neg_lo:[0,0,1] neg_hi:[0,0,1]
	v_xor_b32_e32 v91, 0x80000000, v86
	v_mov_b32_e32 v90, v87
	v_xor_b32_e32 v87, 0x80000000, v20
	v_mov_b32_e32 v86, v21
	v_pk_add_f32 v[98:99], v[88:89], v[90:91]
	v_pk_add_f32 v[100:101], v[88:89], v[90:91] neg_lo:[0,1] neg_hi:[0,1]
	v_pk_add_f32 v[102:103], v[22:23], v[18:19]
	v_pk_add_f32 v[194:195], v[22:23], v[18:19] neg_lo:[0,1] neg_hi:[0,1]
	v_pk_add_f32 v[196:197], v[16:17], v[86:87]
	v_pk_add_f32 v[198:199], v[16:17], v[86:87] neg_lo:[0,1] neg_hi:[0,1]
	ds_read2_b64 v[16:19], v63 offset1:1
	ds_read2_b64 v[20:23], v204 offset1:1
	ds_read2_b64 v[86:89], v205 offset1:1
	ds_read2_b64 v[90:93], v206 offset1:1
	s_waitcnt lgkmcnt(0)
	v_pk_add_f32 v[200:201], v[16:17], v[86:87]
	v_pk_add_f32 v[16:17], v[16:17], v[86:87] neg_lo:[0,1] neg_hi:[0,1]
	v_pk_add_f32 v[86:87], v[18:19], v[88:89]
	v_pk_add_f32 v[18:19], v[18:19], v[88:89] neg_lo:[0,1] neg_hi:[0,1]
	v_pk_add_f32 v[88:89], v[20:21], v[90:91]
	v_pk_add_f32 v[20:21], v[20:21], v[90:91] neg_lo:[0,1] neg_hi:[0,1]
	v_pk_add_f32 v[90:91], v[22:23], v[92:93]
	v_pk_add_f32 v[22:23], v[22:23], v[92:93] neg_lo:[0,1] neg_hi:[0,1]
	v_pk_add_f32 v[92:93], v[18:19], v[18:19] op_sel:[1,0]
	v_pk_add_f32 v[18:19], v[18:19], v[18:19] op_sel_hi:[1,0] neg_lo:[0,1] neg_hi:[0,1]
	s_nop 0
	v_mov_b32_e32 v93, v19
	v_xor_b32_e32 v19, 0x80000000, v20
	v_mov_b32_e32 v18, v21
	v_pk_add_f32 v[20:21], v[22:23], v[22:23] op_sel:[1,0] neg_lo:[0,1] neg_hi:[0,1]
	v_pk_add_f32 v[22:23], v[22:23], v[22:23] op_sel_hi:[1,0]
	s_nop 0
	v_mov_b32_e32 v21, v23
	v_pk_add_f32 v[22:23], v[200:201], v[88:89]
	v_pk_add_f32 v[88:89], v[200:201], v[88:89] neg_lo:[0,1] neg_hi:[0,1]
	v_pk_add_f32 v[200:201], v[86:87], v[90:91]
	v_pk_add_f32 v[86:87], v[86:87], v[90:91] neg_lo:[0,1] neg_hi:[0,1]
	v_pk_mul_f32 v[20:21], v[20:21], s[20:21]
	v_xor_b32_e32 v91, 0x80000000, v86
	v_mov_b32_e32 v90, v87
	v_pk_add_f32 v[86:87], v[22:23], v[200:201]
	v_pk_add_f32 v[22:23], v[22:23], v[200:201] neg_lo:[0,1] neg_hi:[0,1]
	v_pk_add_f32 v[200:201], v[88:89], v[90:91]
	v_pk_add_f32 v[88:89], v[88:89], v[90:91] neg_lo:[0,1] neg_hi:[0,1]
	v_pk_add_f32 v[90:91], v[16:17], v[18:19]
	v_pk_add_f32 v[16:17], v[16:17], v[18:19] neg_lo:[0,1] neg_hi:[0,1]
	v_pk_fma_f32 v[18:19], v[92:93], s[20:21], v[20:21] op_sel_hi:[1,0,1]
	v_pk_fma_f32 v[20:21], v[92:93], s[20:21], v[20:21] op_sel_hi:[1,0,1] neg_lo:[0,0,1] neg_hi:[0,0,1]
	s_nop 0
	v_xor_b32_e32 v93, 0x80000000, v20
	v_mov_b32_e32 v92, v21
	v_pk_add_f32 v[20:21], v[90:91], v[18:19]
	v_pk_add_f32 v[18:19], v[90:91], v[18:19] neg_lo:[0,1] neg_hi:[0,1]
	v_pk_add_f32 v[90:91], v[16:17], v[92:93]
	v_pk_add_f32 v[16:17], v[16:17], v[92:93] neg_lo:[0,1] neg_hi:[0,1]
	v_pk_mul_f32 v[92:93], v[40:41], v[96:97] op_sel:[0,1]
	s_nop 0
	v_fma_f32 v202, v24, v96, -v92
	v_fma_f32 v203, v25, v96, v93
	s_nop 0
	v_pk_mul_f32 v[92:93], v[40:41], v[86:87] op_sel:[0,1]
	s_nop 0
	v_fma_f32 v96, v24, v86, -v92
	v_fma_f32 v97, v25, v86, v93
	s_nop 0
	v_pk_mul_f32 v[86:87], v[42:43], v[102:103] op_sel:[0,1]
	s_nop 0
	v_fma_f32 v92, v32, v102, -v86
	v_fma_f32 v93, v33, v102, v87
	s_nop 0
	v_pk_mul_f32 v[86:87], v[42:43], v[20:21] op_sel:[0,1]
	s_nop 0
	v_fma_f32 v102, v32, v20, -v86
	v_fma_f32 v103, v33, v20, v87
	s_nop 0
	v_pk_mul_f32 v[20:21], v[44:45], v[98:99] op_sel:[0,1]
	s_nop 0
	v_fma_f32 v86, v28, v98, -v20
	v_fma_f32 v87, v29, v98, v21
	s_nop 0
	v_pk_mul_f32 v[20:21], v[44:45], v[200:201] op_sel:[0,1]
	s_nop 0
	v_fma_f32 v98, v28, v200, -v20
	v_fma_f32 v99, v29, v200, v21
	s_nop 0
	v_pk_mul_f32 v[20:21], v[46:47], v[196:197] op_sel:[0,1]
	s_nop 0
	v_fma_f32 v200, v36, v196, -v20
	v_fma_f32 v201, v37, v196, v21
	s_nop 0
	v_pk_mul_f32 v[20:21], v[46:47], v[90:91] op_sel:[0,1]
	s_nop 0
	v_fma_f32 v196, v36, v90, -v20
	v_fma_f32 v197, v37, v90, v21
	s_nop 0
	v_pk_mul_f32 v[20:21], v[48:49], v[94:95] op_sel:[0,1]
	s_nop 0
	v_fma_f32 v90, v26, v94, -v20
	v_fma_f32 v91, v27, v94, v21
	s_nop 0
	v_pk_mul_f32 v[20:21], v[48:49], v[22:23] op_sel:[0,1]
; __device__ __forceinline__ c2 cmul(c2 a, c2 b) { return (c2){a.x * b.x - a.y * b.y, a.x * b.y + a.y * b.x}; }
; __device__ __forceinline__ void idft8(c2 (&x)[8]) {
;     const float s = 0.70710678118654752f;
;     const c2 a0 = x[0] + x[4], a4 = x[0] - x[4], a1 = x[1] + x[5], a5 = x[1] - x[5], a2 = x[2] + x[6], a6 = x[2] - x[6], a3 = x[3] + x[7], a7 = x[3] - x[7];
;     const c2 a5w = (c2){(a5.x - a5.y) * s, (a5.x + a5.y) * s};
;     const c2 a6w = mpi(a6);
;     const c2 a7w = (c2){-(a7.x + a7.y) * s, (a7.x - a7.y) * s};
;     const c2 b0 = a0 + a2, b1 = a0 - a2, b2 = a1 + a3, b3 = mpi(a1 - a3);
;     x[0] = b0 + b2; x[4] = b0 - b2; x[2] = b1 + b3; x[6] = b1 - b3;
;     const c2 c0 = a4 + a6w, c1 = a4 - a6w, c2_ = a5w + a7w, c3 = mpi(a5w - a7w);
;     x[1] = c0 + c2_; x[5] = c0 - c2_; x[3] = c1 + c3; x[7] = c1 - c3;
; }
; __device__ __forceinline__ void fwd_s0(c2 (&x)[8], c2* buf, const c2* tws, int tid) {
;     dft8(x);
; #pragma unroll
;     for (int q = 1; q < 8; ++q) x[q] = cmul(x[q], tws[(q - 1) * 512 + tid]);
;     { c2* bp_ = buf + LP(tid);
; #pragma unroll
;     for (int q = 0; q < 8; ++q) bp_[576 * q] = x[q]; }
; }
; template <int S> __device__ __forceinline__ void fwd_mid(c2* buf, const c2* tws, int tid) {
;     constexpr int lq = 9 - 3 * S, Q = 1 << lq; const c2* T = tws + (S == 1 ? 3584 : 4032);
;     const int k = tid & (Q - 1), base = ((tid >> lq) << (lq + 3)) + k;
;     c2 x[8];
;     c2* bp_ = buf + LP(base); constexpr int QP = Q + Q / 8;
; #pragma unroll
;     for (int r = 0; r < 8; ++r) x[r] = bp_[r * QP];
;     dft8(x);
; #pragma unroll
;     for (int q = 1; q < 8; ++q) x[q] = cmul(x[q], T[(q - 1) * Q + k]);
; #pragma unroll
;     for (int q = 0; q < 8; ++q) bp_[q * QP] = x[q];
; }
; __device__ __forceinline__ void fwd_s3(c2 (&x)[8], const c2* buf, int tid) {
; #pragma unroll
;     for (int r = 0; r < 8; ++r) x[r] = buf[9 * tid + r];
;     dft8(x);
; }
; __device__ __forceinline__ void inv_s3(c2 (&x)[8], c2* buf, int tid) {
;     idft8(x);
; #pragma unroll
;     for (int q = 0; q < 8; ++q) buf[9 * tid + q] = x[q];
; }
; __device__ __forceinline__ void phase_conv(const Params& p, int o, unsigned char* smem, int wave) {
;     ...
;                 for (int q = 0; q < 8; ++q) { x0[q] = cmul(x0[q], K[q]); x1[q] = cmul(x1[q], K[q]); }
;                 fft_inv_regs2(x0, x1, buf0, buf1, tws, tid);
	s_nop 0
	v_fma_f32 v94, v26, v22, -v20
	v_fma_f32 v95, v27, v22, v21
	s_nop 0
	v_pk_mul_f32 v[20:21], v[50:51], v[194:195] op_sel:[0,1]
	s_nop 0
	v_fma_f32 v22, v34, v194, -v20
	v_fma_f32 v23, v35, v194, v21
	s_nop 0
	v_pk_mul_f32 v[20:21], v[50:51], v[18:19] op_sel:[0,1]
	s_nop 0
	v_fma_f32 v194, v34, v18, -v20
	v_fma_f32 v195, v35, v18, v21
	s_nop 0
	v_pk_mul_f32 v[18:19], v[52:53], v[100:101] op_sel:[0,1]
	s_nop 0
	v_fma_f32 v20, v30, v100, -v18
	v_fma_f32 v21, v31, v100, v19
	s_nop 0
	v_pk_mul_f32 v[18:19], v[52:53], v[88:89] op_sel:[0,1]
	s_nop 0
	v_fma_f32 v100, v30, v88, -v18
	v_fma_f32 v101, v31, v88, v19
	s_nop 0
	v_pk_mul_f32 v[18:19], v[54:55], v[198:199] op_sel:[0,1]
	s_nop 0
	v_fma_f32 v88, v38, v198, -v18
	v_fma_f32 v89, v39, v198, v19
	s_nop 0
	v_pk_mul_f32 v[18:19], v[54:55], v[16:17] op_sel:[0,1]
	s_nop 0
	v_fma_f32 v198, v38, v16, -v18
	v_fma_f32 v199, v39, v16, v19
	v_pk_add_f32 v[18:19], v[202:203], v[90:91] neg_lo:[0,1] neg_hi:[0,1]
	v_pk_add_f32 v[16:17], v[202:203], v[90:91]
	v_pk_add_f32 v[90:91], v[92:93], v[22:23]
	v_pk_add_f32 v[22:23], v[92:93], v[22:23] neg_lo:[0,1] neg_hi:[0,1]
	v_pk_add_f32 v[92:93], v[86:87], v[20:21]
	v_pk_add_f32 v[20:21], v[86:87], v[20:21] neg_lo:[0,1] neg_hi:[0,1]
	v_pk_add_f32 v[86:87], v[200:201], v[88:89]
	v_pk_add_f32 v[88:89], v[200:201], v[88:89] neg_lo:[0,1] neg_hi:[0,1]
	v_pk_add_f32 v[200:201], v[22:23], v[22:23] op_sel:[0,1] neg_lo:[0,1] neg_hi:[0,1]
	v_pk_add_f32 v[22:23], v[22:23], v[22:23] op_sel_hi:[0,1]
	v_mov_b32_e32 v201, v23
	v_xor_b32_e32 v22, 0x80000000, v21
	v_mov_b32_e32 v23, v20
	v_pk_add_f32 v[20:21], v[88:89], v[88:89] op_sel:[0,1]
	v_pk_add_f32 v[88:89], v[88:89], v[88:89] op_sel_hi:[0,1] neg_lo:[0,1] neg_hi:[0,1]
	v_mov_b32_e32 v21, v89
	v_pk_add_f32 v[88:89], v[16:17], v[92:93]
	v_pk_add_f32 v[16:17], v[16:17], v[92:93] neg_lo:[0,1] neg_hi:[0,1]
	v_pk_add_f32 v[92:93], v[90:91], v[86:87]
	v_pk_add_f32 v[86:87], v[90:91], v[86:87] neg_lo:[0,1] neg_hi:[0,1]
	v_pk_mul_f32 v[20:21], v[20:21], s[84:85]
	v_xor_b32_e32 v90, 0x80000000, v87
	v_mov_b32_e32 v91, v86
	v_pk_add_f32 v[86:87], v[88:89], v[92:93]
	v_pk_add_f32 v[88:89], v[88:89], v[92:93] neg_lo:[0,1] neg_hi:[0,1]
	v_pk_add_f32 v[92:93], v[16:17], v[90:91]
	v_pk_add_f32 v[16:17], v[16:17], v[90:91] neg_lo:[0,1] neg_hi:[0,1]
	v_pk_add_f32 v[90:91], v[18:19], v[22:23]
	v_pk_add_f32 v[18:19], v[18:19], v[22:23] neg_lo:[0,1] neg_hi:[0,1]
	v_pk_fma_f32 v[22:23], v[200:201], s[20:21], v[20:21] op_sel_hi:[1,0,1]
	v_pk_fma_f32 v[20:21], v[200:201], s[20:21], v[20:21] op_sel_hi:[1,0,1] neg_lo:[0,0,1] neg_hi:[0,0,1]
	s_nop 0
	v_xor_b32_e32 v200, 0x80000000, v21
	v_mov_b32_e32 v201, v20
	v_pk_add_f32 v[20:21], v[90:91], v[22:23]
	v_pk_add_f32 v[22:23], v[90:91], v[22:23] neg_lo:[0,1] neg_hi:[0,1]
	v_pk_add_f32 v[90:91], v[18:19], v[200:201]
	v_pk_add_f32 v[18:19], v[18:19], v[200:201] neg_lo:[0,1] neg_hi:[0,1]
	ds_write2_b64 v121, v[86:87], v[20:21] offset1:1
	ds_write2_b64 v121, v[92:93], v[90:91] offset0:2 offset1:3
	ds_write2_b64 v121, v[88:89], v[22:23] offset0:4 offset1:5
	ds_write2_b64 v121, v[16:17], v[18:19] offset0:6 offset1:7
	v_pk_add_f32 v[22:23], v[102:103], v[194:195] neg_lo:[0,1] neg_hi:[0,1]
	v_pk_add_f32 v[16:17], v[96:97], v[94:95]
	v_pk_add_f32 v[18:19], v[96:97], v[94:95] neg_lo:[0,1] neg_hi:[0,1]
	v_pk_add_f32 v[88:89], v[98:99], v[100:101] neg_lo:[0,1] neg_hi:[0,1]
	v_pk_add_f32 v[92:93], v[196:197], v[198:199] neg_lo:[0,1] neg_hi:[0,1]
	v_pk_add_f32 v[94:95], v[22:23], v[22:23] op_sel:[0,1] neg_lo:[0,1] neg_hi:[0,1]
	v_pk_add_f32 v[22:23], v[22:23], v[22:23] op_sel_hi:[0,1]
	v_pk_add_f32 v[20:21], v[102:103], v[194:195]
	v_pk_add_f32 v[86:87], v[98:99], v[100:101]
	v_pk_add_f32 v[90:91], v[196:197], v[198:199]
	v_mov_b32_e32 v95, v23
	v_xor_b32_e32 v22, 0x80000000, v89
	v_mov_b32_e32 v23, v88
	v_pk_add_f32 v[88:89], v[92:93], v[92:93] op_sel:[0,1]
	v_pk_add_f32 v[92:93], v[92:93], v[92:93] op_sel_hi:[0,1] neg_lo:[0,1] neg_hi:[0,1]
	v_mov_b32_e32 v89, v93
	v_pk_add_f32 v[92:93], v[16:17], v[86:87]
	v_pk_add_f32 v[16:17], v[16:17], v[86:87] neg_lo:[0,1] neg_hi:[0,1]
	v_pk_add_f32 v[86:87], v[20:21], v[90:91]
	v_pk_add_f32 v[20:21], v[20:21], v[90:91] neg_lo:[0,1] neg_hi:[0,1]
	v_pk_mul_f32 v[88:89], v[88:89], s[84:85]
	v_xor_b32_e32 v90, 0x80000000, v21
	v_mov_b32_e32 v91, v20
	v_pk_add_f32 v[20:21], v[92:93], v[86:87]
	v_pk_add_f32 v[86:87], v[92:93], v[86:87] neg_lo:[0,1] neg_hi:[0,1]
	v_pk_add_f32 v[92:93], v[16:17], v[90:91]
	v_pk_add_f32 v[16:17], v[16:17], v[90:91] neg_lo:[0,1] neg_hi:[0,1]
	v_pk_add_f32 v[90:91], v[18:19], v[22:23]
	v_pk_add_f32 v[18:19], v[18:19], v[22:23] neg_lo:[0,1] neg_hi:[0,1]
	v_pk_fma_f32 v[22:23], v[94:95], s[20:21], v[88:89] op_sel_hi:[1,0,1]
	v_pk_fma_f32 v[88:89], v[94:95], s[20:21], v[88:89] op_sel_hi:[1,0,1] neg_lo:[0,0,1] neg_hi:[0,0,1]
	s_nop 0
	v_xor_b32_e32 v94, 0x80000000, v89
	v_mov_b32_e32 v95, v88
	v_pk_add_f32 v[88:89], v[90:91], v[22:23]
	v_pk_add_f32 v[22:23], v[90:91], v[22:23] neg_lo:[0,1] neg_hi:[0,1]
	v_pk_add_f32 v[90:91], v[18:19], v[94:95]
	v_pk_add_f32 v[18:19], v[18:19], v[94:95] neg_lo:[0,1] neg_hi:[0,1]
	ds_write2_b64 v63, v[20:21], v[88:89] offset1:1
	ds_write2_b64 v204, v[92:93], v[90:91] offset1:1
	ds_write2_b64 v205, v[86:87], v[22:23] offset1:1
	ds_write2_b64 v206, v[16:17], v[18:19] offset1:1
	s_waitcnt lgkmcnt(0)
	s_barrier
; __device__ __forceinline__ c2 cmulc(c2 a, c2 b) { return (c2){a.x * b.x + a.y * b.y, a.y * b.x - a.x * b.y}; }
; __device__ __forceinline__ c2 mpi(c2 a) { return (c2){-a.y, a.x}; }
; __device__ __forceinline__ void idft8(c2 (&x)[8]) {
;     const float s = 0.70710678118654752f;
;     const c2 a0 = x[0] + x[4], a4 = x[0] - x[4], a1 = x[1] + x[5], a5 = x[1] - x[5], a2 = x[2] + x[6], a6 = x[2] - x[6], a3 = x[3] + x[7], a7 = x[3] - x[7];
;     const c2 a5w = (c2){(a5.x - a5.y) * s, (a5.x + a5.y) * s};
;     const c2 a6w = mpi(a6);
;     const c2 a7w = (c2){-(a7.x + a7.y) * s, (a7.x - a7.y) * s};
;     const c2 b0 = a0 + a2, b1 = a0 - a2, b2 = a1 + a3, b3 = mpi(a1 - a3);
;     x[0] = b0 + b2; x[4] = b0 - b2; x[2] = b1 + b3; x[6] = b1 - b3;
;     const c2 c0 = a4 + a6w, c1 = a4 - a6w, c2_ = a5w + a7w, c3 = mpi(a5w - a7w);
;     x[1] = c0 + c2_; x[5] = c0 - c2_; x[3] = c1 + c3; x[7] = c1 - c3;
; }
; template <int S> __device__ __forceinline__ void inv_mid(c2* buf, const c2* tws, int tid) {
;     constexpr int lq = 9 - 3 * S, Q = 1 << lq; const c2* T = tws + (S == 1 ? 3584 : 4032);
;     const int k = tid & (Q - 1), base = ((tid >> lq) << (lq + 3)) + k;
;     c2 x[8];
;     c2* bp_ = buf + LP(base); constexpr int QP = Q + Q / 8;
; #pragma unroll
;     for (int r = 0; r < 8; ++r) { c2 v = bp_[r * QP]; if (r) v = cmulc(v, T[(r - 1) * Q + k]); x[r] = v; }
;     idft8(x);
; #pragma unroll
;     for (int q = 0; q < 8; ++q) bp_[q * QP] = x[q];
; }
	ds_read2_b64 v[16:19], v119 offset1:9
	v_mov_b64_e32 v[94:95], v[238:239]
	ds_read2_b64 v[20:23], v119 offset0:18 offset1:27
	v_mov_b64_e32 v[96:97], v[240:241]
	v_mov_b64_e32 v[98:99], v[242:243]
	ds_read2_b64 v[86:89], v119 offset0:36 offset1:45
	v_mov_b64_e32 v[100:101], v[244:245]
	v_mov_b64_e32 v[102:103], v[246:247]
	ds_read2_b64 v[90:93], v119 offset0:54 offset1:63
	v_mov_b64_e32 v[194:195], v[248:249]
	s_waitcnt lgkmcnt(0)
	v_pk_mul_f32 v[198:199], v[92:93], v[250:251] op_sel:[1,1] op_sel_hi:[0,1]
	v_fma_f32 v200, v92, v250, v198
	v_fma_f32 v201, v93, v250, -v199
	s_nop 0
	v_pk_mul_f32 v[92:93], v[18:19], v[94:95] op_sel:[1,1] op_sel_hi:[0,1]
	v_fma_f32 v196, v18, v94, v92
	v_fma_f32 v197, v19, v94, -v93
	s_nop 0
	v_pk_mul_f32 v[18:19], v[20:21], v[96:97] op_sel:[1,1] op_sel_hi:[0,1]
	v_fma_f32 v92, v20, v96, v18
	v_fma_f32 v93, v21, v96, -v19
	s_nop 0
	v_pk_mul_f32 v[18:19], v[22:23], v[98:99] op_sel:[1,1] op_sel_hi:[0,1]
	v_fma_f32 v20, v22, v98, v18
	v_fma_f32 v21, v23, v98, -v19
	s_nop 0
	v_pk_mul_f32 v[18:19], v[86:87], v[100:101] op_sel:[1,1] op_sel_hi:[0,1]
	v_fma_f32 v22, v86, v100, v18
	v_fma_f32 v23, v87, v100, -v19
	s_nop 0
	v_pk_mul_f32 v[18:19], v[88:89], v[102:103] op_sel:[1,1] op_sel_hi:[0,1]
	v_fma_f32 v86, v88, v102, v18
	v_fma_f32 v87, v89, v102, -v19
	s_nop 0
	v_pk_mul_f32 v[18:19], v[90:91], v[194:195] op_sel:[1,1] op_sel_hi:[0,1]
	v_fma_f32 v88, v90, v194, v18
	v_fma_f32 v89, v91, v194, -v19
	s_nop 0
	v_pk_add_f32 v[18:19], v[16:17], v[22:23]
	v_pk_add_f32 v[16:17], v[16:17], v[22:23] neg_lo:[0,1] neg_hi:[0,1]
	v_pk_add_f32 v[22:23], v[196:197], v[86:87]
	v_pk_add_f32 v[86:87], v[196:197], v[86:87] neg_lo:[0,1] neg_hi:[0,1]
	v_pk_add_f32 v[90:91], v[92:93], v[88:89]
	v_pk_add_f32 v[88:89], v[92:93], v[88:89] neg_lo:[0,1] neg_hi:[0,1]
	v_pk_add_f32 v[92:93], v[20:21], v[200:201]
	v_pk_add_f32 v[20:21], v[20:21], v[200:201] neg_lo:[0,1] neg_hi:[0,1]
	v_pk_add_f32 v[94:95], v[86:87], v[86:87] op_sel:[0,1] neg_lo:[0,1] neg_hi:[0,1]
	v_pk_add_f32 v[86:87], v[86:87], v[86:87] op_sel_hi:[0,1]
	v_mov_b32_e32 v95, v87
	v_xor_b32_e32 v86, 0x80000000, v89
	v_mov_b32_e32 v87, v88
	v_pk_add_f32 v[88:89], v[20:21], v[20:21] op_sel:[0,1]
	v_pk_add_f32 v[20:21], v[20:21], v[20:21] op_sel_hi:[0,1] neg_lo:[0,1] neg_hi:[0,1]
	v_mov_b32_e32 v89, v21
	v_pk_mul_f32 v[20:21], v[88:89], s[84:85]
	v_pk_add_f32 v[88:89], v[18:19], v[90:91]
	v_pk_add_f32 v[18:19], v[18:19], v[90:91] neg_lo:[0,1] neg_hi:[0,1]
	v_pk_add_f32 v[90:91], v[22:23], v[92:93]
	v_pk_add_f32 v[22:23], v[22:23], v[92:93] neg_lo:[0,1] neg_hi:[0,1]
	s_nop 0
	v_xor_b32_e32 v92, 0x80000000, v23
	v_mov_b32_e32 v93, v22
	v_pk_add_f32 v[22:23], v[88:89], v[90:91]
	v_pk_add_f32 v[88:89], v[88:89], v[90:91] neg_lo:[0,1] neg_hi:[0,1]
	v_pk_add_f32 v[90:91], v[18:19], v[92:93]
	v_pk_add_f32 v[18:19], v[18:19], v[92:93] neg_lo:[0,1] neg_hi:[0,1]
	v_pk_add_f32 v[92:93], v[16:17], v[86:87]
	v_pk_add_f32 v[16:17], v[16:17], v[86:87] neg_lo:[0,1] neg_hi:[0,1]
	v_pk_fma_f32 v[86:87], v[94:95], s[20:21], v[20:21] op_sel_hi:[1,0,1]
	v_pk_fma_f32 v[20:21], v[94:95], s[20:21], v[20:21] op_sel_hi:[1,0,1] neg_lo:[0,0,1] neg_hi:[0,0,1]
	s_nop 0
	v_xor_b32_e32 v94, 0x80000000, v21
	v_mov_b32_e32 v95, v20
	v_pk_add_f32 v[20:21], v[92:93], v[86:87]
	v_pk_add_f32 v[86:87], v[92:93], v[86:87] neg_lo:[0,1] neg_hi:[0,1]
	v_pk_add_f32 v[92:93], v[16:17], v[94:95]
	v_pk_add_f32 v[16:17], v[16:17], v[94:95] neg_lo:[0,1] neg_hi:[0,1]
	ds_write2_b64 v119, v[22:23], v[20:21] offset1:9
	ds_write2_b64 v119, v[90:91], v[92:93] offset0:18 offset1:27
	ds_write2_b64 v119, v[88:89], v[86:87] offset0:36 offset1:45
	ds_write2_b64 v119, v[18:19], v[16:17] offset0:54 offset1:63
	ds_read2_b64 v[16:19], v193 offset1:9
	v_mov_b64_e32 v[94:95], v[238:239]
	ds_read2_b64 v[20:23], v193 offset0:18 offset1:27
	v_mov_b64_e32 v[96:97], v[240:241]
	v_mov_b64_e32 v[98:99], v[242:243]
	ds_read2_b64 v[86:89], v193 offset0:36 offset1:45
	v_mov_b64_e32 v[100:101], v[244:245]
	v_mov_b64_e32 v[102:103], v[246:247]
	ds_read2_b64 v[90:93], v193 offset0:54 offset1:63
	v_mov_b64_e32 v[194:195], v[248:249]
	s_waitcnt lgkmcnt(0)
	v_pk_mul_f32 v[198:199], v[92:93], v[250:251] op_sel:[1,1] op_sel_hi:[0,1]
	v_fma_f32 v200, v92, v250, v198
	v_fma_f32 v201, v93, v250, -v199
	s_nop 0
	v_pk_mul_f32 v[92:93], v[18:19], v[94:95] op_sel:[1,1] op_sel_hi:[0,1]
	v_fma_f32 v196, v18, v94, v92
	v_fma_f32 v197, v19, v94, -v93
	s_nop 0
	v_pk_mul_f32 v[18:19], v[20:21], v[96:97] op_sel:[1,1] op_sel_hi:[0,1]
	v_fma_f32 v92, v20, v96, v18
	v_fma_f32 v93, v21, v96, -v19
	s_nop 0
	v_pk_mul_f32 v[18:19], v[22:23], v[98:99] op_sel:[1,1] op_sel_hi:[0,1]
	v_fma_f32 v20, v22, v98, v18
	v_fma_f32 v21, v23, v98, -v19
	s_nop 0
	v_pk_mul_f32 v[18:19], v[86:87], v[100:101] op_sel:[1,1] op_sel_hi:[0,1]
	v_fma_f32 v22, v86, v100, v18
	v_fma_f32 v23, v87, v100, -v19
	s_nop 0
	v_pk_mul_f32 v[18:19], v[88:89], v[102:103] op_sel:[1,1] op_sel_hi:[0,1]
	v_fma_f32 v86, v88, v102, v18
	v_fma_f32 v87, v89, v102, -v19
	s_nop 0
	v_pk_mul_f32 v[18:19], v[90:91], v[194:195] op_sel:[1,1] op_sel_hi:[0,1]
	v_fma_f32 v88, v90, v194, v18
	v_fma_f32 v89, v91, v194, -v19
	s_nop 0
	v_pk_add_f32 v[18:19], v[16:17], v[22:23]
	v_pk_add_f32 v[16:17], v[16:17], v[22:23] neg_lo:[0,1] neg_hi:[0,1]
	v_pk_add_f32 v[22:23], v[196:197], v[86:87]
	v_pk_add_f32 v[86:87], v[196:197], v[86:87] neg_lo:[0,1] neg_hi:[0,1]
	v_pk_add_f32 v[90:91], v[92:93], v[88:89]
	v_pk_add_f32 v[88:89], v[92:93], v[88:89] neg_lo:[0,1] neg_hi:[0,1]
	v_pk_add_f32 v[92:93], v[20:21], v[200:201]
	v_pk_add_f32 v[20:21], v[20:21], v[200:201] neg_lo:[0,1] neg_hi:[0,1]
	v_pk_add_f32 v[94:95], v[86:87], v[86:87] op_sel:[0,1] neg_lo:[0,1] neg_hi:[0,1]
; __device__ __forceinline__ c2 cmulc(c2 a, c2 b) { return (c2){a.x * b.x + a.y * b.y, a.y * b.x - a.x * b.y}; }
; __device__ __forceinline__ c2 mpi(c2 a) { return (c2){-a.y, a.x}; }
; __device__ __forceinline__ void idft8(c2 (&x)[8]) {
;     const float s = 0.70710678118654752f;
;     const c2 a0 = x[0] + x[4], a4 = x[0] - x[4], a1 = x[1] + x[5], a5 = x[1] - x[5], a2 = x[2] + x[6], a6 = x[2] - x[6], a3 = x[3] + x[7], a7 = x[3] - x[7];
;     const c2 a5w = (c2){(a5.x - a5.y) * s, (a5.x + a5.y) * s};
;     const c2 a6w = mpi(a6);
;     const c2 a7w = (c2){-(a7.x + a7.y) * s, (a7.x - a7.y) * s};
;     const c2 b0 = a0 + a2, b1 = a0 - a2, b2 = a1 + a3, b3 = mpi(a1 - a3);
;     x[0] = b0 + b2; x[4] = b0 - b2; x[2] = b1 + b3; x[6] = b1 - b3;
;     const c2 c0 = a4 + a6w, c1 = a4 - a6w, c2_ = a5w + a7w, c3 = mpi(a5w - a7w);
;     x[1] = c0 + c2_; x[5] = c0 - c2_; x[3] = c1 + c3; x[7] = c1 - c3;
; }
; template <int S> __device__ __forceinline__ void inv_mid(c2* buf, const c2* tws, int tid) {
;     constexpr int lq = 9 - 3 * S, Q = 1 << lq; const c2* T = tws + (S == 1 ? 3584 : 4032);
;     const int k = tid & (Q - 1), base = ((tid >> lq) << (lq + 3)) + k;
;     c2 x[8];
;     c2* bp_ = buf + LP(base); constexpr int QP = Q + Q / 8;
; #pragma unroll
;     for (int r = 0; r < 8; ++r) { c2 v = bp_[r * QP]; if (r) v = cmulc(v, T[(r - 1) * Q + k]); x[r] = v; }
;     idft8(x);
; #pragma unroll
;     for (int q = 0; q < 8; ++q) bp_[q * QP] = x[q];
; }
	v_pk_add_f32 v[86:87], v[86:87], v[86:87] op_sel_hi:[0,1]
	v_mov_b32_e32 v95, v87
	v_xor_b32_e32 v86, 0x80000000, v89
	v_mov_b32_e32 v87, v88
	v_pk_add_f32 v[88:89], v[20:21], v[20:21] op_sel:[0,1]
	v_pk_add_f32 v[20:21], v[20:21], v[20:21] op_sel_hi:[0,1] neg_lo:[0,1] neg_hi:[0,1]
	v_mov_b32_e32 v89, v21
	v_pk_mul_f32 v[20:21], v[88:89], s[84:85]
	v_pk_add_f32 v[88:89], v[18:19], v[90:91]
	v_pk_add_f32 v[18:19], v[18:19], v[90:91] neg_lo:[0,1] neg_hi:[0,1]
	v_pk_add_f32 v[90:91], v[22:23], v[92:93]
	v_pk_add_f32 v[22:23], v[22:23], v[92:93] neg_lo:[0,1] neg_hi:[0,1]
	s_nop 0
	v_xor_b32_e32 v92, 0x80000000, v23
	v_mov_b32_e32 v93, v22
	v_pk_add_f32 v[22:23], v[88:89], v[90:91]
	v_pk_add_f32 v[88:89], v[88:89], v[90:91] neg_lo:[0,1] neg_hi:[0,1]
	v_pk_add_f32 v[90:91], v[18:19], v[92:93]
	v_pk_add_f32 v[18:19], v[18:19], v[92:93] neg_lo:[0,1] neg_hi:[0,1]
	v_pk_add_f32 v[92:93], v[16:17], v[86:87]
	v_pk_add_f32 v[16:17], v[16:17], v[86:87] neg_lo:[0,1] neg_hi:[0,1]
	v_pk_fma_f32 v[86:87], v[94:95], s[20:21], v[20:21] op_sel_hi:[1,0,1]
	v_pk_fma_f32 v[20:21], v[94:95], s[20:21], v[20:21] op_sel_hi:[1,0,1] neg_lo:[0,0,1] neg_hi:[0,0,1]
	s_nop 0
	v_xor_b32_e32 v94, 0x80000000, v21
	v_mov_b32_e32 v95, v20
	v_pk_add_f32 v[20:21], v[92:93], v[86:87]
	v_pk_add_f32 v[86:87], v[92:93], v[86:87] neg_lo:[0,1] neg_hi:[0,1]
	v_pk_add_f32 v[92:93], v[16:17], v[94:95]
	v_pk_add_f32 v[16:17], v[16:17], v[94:95] neg_lo:[0,1] neg_hi:[0,1]
	ds_write2_b64 v193, v[22:23], v[20:21] offset1:9
	ds_write2_b64 v193, v[90:91], v[92:93] offset0:18 offset1:27
	ds_write2_b64 v193, v[88:89], v[86:87] offset0:36 offset1:45
	ds_write2_b64 v193, v[18:19], v[16:17] offset0:54 offset1:63
	s_waitcnt lgkmcnt(0)
	s_barrier
	ds_read2_b64 v[16:19], v117 offset1:72
	v_mov_b64_e32 v[94:95], v[224:225]
	ds_read2_b64 v[20:23], v117 offset0:144 offset1:216
	v_mov_b64_e32 v[96:97], v[226:227]
	v_mov_b64_e32 v[98:99], v[228:229]
	ds_read2_b64 v[86:89], v56 offset0:32 offset1:104
	v_mov_b64_e32 v[100:101], v[230:231]
	v_mov_b64_e32 v[102:103], v[232:233]
	ds_read2_b64 v[90:93], v56 offset0:176 offset1:248
	v_mov_b64_e32 v[194:195], v[234:235]
	s_waitcnt lgkmcnt(0)
	v_pk_mul_f32 v[198:199], v[92:93], v[236:237] op_sel:[1,1] op_sel_hi:[0,1]
	v_fma_f32 v200, v92, v236, v198
	v_fma_f32 v201, v93, v236, -v199
	s_nop 0
	v_pk_mul_f32 v[92:93], v[18:19], v[94:95] op_sel:[1,1] op_sel_hi:[0,1]
	v_fma_f32 v196, v18, v94, v92
	v_fma_f32 v197, v19, v94, -v93
	s_nop 0
	v_pk_mul_f32 v[18:19], v[20:21], v[96:97] op_sel:[1,1] op_sel_hi:[0,1]
	v_fma_f32 v92, v20, v96, v18
	v_fma_f32 v93, v21, v96, -v19
	s_nop 0
	v_pk_mul_f32 v[18:19], v[22:23], v[98:99] op_sel:[1,1] op_sel_hi:[0,1]
	v_fma_f32 v20, v22, v98, v18
	v_fma_f32 v21, v23, v98, -v19
	s_nop 0
	v_pk_mul_f32 v[18:19], v[86:87], v[100:101] op_sel:[1,1] op_sel_hi:[0,1]
	v_fma_f32 v22, v86, v100, v18
	v_fma_f32 v23, v87, v100, -v19
	s_nop 0
	v_pk_mul_f32 v[18:19], v[88:89], v[102:103] op_sel:[1,1] op_sel_hi:[0,1]
	v_fma_f32 v86, v88, v102, v18
	v_fma_f32 v87, v89, v102, -v19
	s_nop 0
	v_pk_mul_f32 v[18:19], v[90:91], v[194:195] op_sel:[1,1] op_sel_hi:[0,1]
	v_fma_f32 v88, v90, v194, v18
	v_fma_f32 v89, v91, v194, -v19
	s_nop 0
	v_pk_add_f32 v[18:19], v[16:17], v[22:23]
	v_pk_add_f32 v[16:17], v[16:17], v[22:23] neg_lo:[0,1] neg_hi:[0,1]
	v_pk_add_f32 v[22:23], v[196:197], v[86:87]
	v_pk_add_f32 v[86:87], v[196:197], v[86:87] neg_lo:[0,1] neg_hi:[0,1]
	v_pk_add_f32 v[90:91], v[92:93], v[88:89]
	v_pk_add_f32 v[88:89], v[92:93], v[88:89] neg_lo:[0,1] neg_hi:[0,1]
	v_pk_add_f32 v[92:93], v[20:21], v[200:201]
	v_pk_add_f32 v[20:21], v[20:21], v[200:201] neg_lo:[0,1] neg_hi:[0,1]
	v_pk_add_f32 v[94:95], v[86:87], v[86:87] op_sel:[0,1] neg_lo:[0,1] neg_hi:[0,1]
	v_pk_add_f32 v[86:87], v[86:87], v[86:87] op_sel_hi:[0,1]
	v_mov_b32_e32 v95, v87
	v_xor_b32_e32 v86, 0x80000000, v89
	v_mov_b32_e32 v87, v88
	v_pk_add_f32 v[88:89], v[20:21], v[20:21] op_sel:[0,1]
	v_pk_add_f32 v[20:21], v[20:21], v[20:21] op_sel_hi:[0,1] neg_lo:[0,1] neg_hi:[0,1]
	v_mov_b32_e32 v89, v21
	v_pk_mul_f32 v[20:21], v[88:89], s[84:85]
	v_pk_add_f32 v[88:89], v[18:19], v[90:91]
	v_pk_add_f32 v[18:19], v[18:19], v[90:91] neg_lo:[0,1] neg_hi:[0,1]
	v_pk_add_f32 v[90:91], v[22:23], v[92:93]
	v_pk_add_f32 v[22:23], v[22:23], v[92:93] neg_lo:[0,1] neg_hi:[0,1]
	s_nop 0
	v_xor_b32_e32 v92, 0x80000000, v23
	v_mov_b32_e32 v93, v22
	v_pk_add_f32 v[22:23], v[88:89], v[90:91]
	v_pk_add_f32 v[88:89], v[88:89], v[90:91] neg_lo:[0,1] neg_hi:[0,1]
	v_pk_add_f32 v[90:91], v[18:19], v[92:93]
	v_pk_add_f32 v[18:19], v[18:19], v[92:93] neg_lo:[0,1] neg_hi:[0,1]
	v_pk_add_f32 v[92:93], v[16:17], v[86:87]
	v_pk_add_f32 v[16:17], v[16:17], v[86:87] neg_lo:[0,1] neg_hi:[0,1]
	v_pk_fma_f32 v[86:87], v[94:95], s[20:21], v[20:21] op_sel_hi:[1,0,1]
	v_pk_fma_f32 v[20:21], v[94:95], s[20:21], v[20:21] op_sel_hi:[1,0,1] neg_lo:[0,0,1] neg_hi:[0,0,1]
	s_nop 0
	v_xor_b32_e32 v94, 0x80000000, v21
	v_mov_b32_e32 v95, v20
	v_pk_add_f32 v[20:21], v[92:93], v[86:87]
	v_pk_add_f32 v[86:87], v[92:93], v[86:87] neg_lo:[0,1] neg_hi:[0,1]
	v_pk_add_f32 v[92:93], v[16:17], v[94:95]
	v_pk_add_f32 v[16:17], v[16:17], v[94:95] neg_lo:[0,1] neg_hi:[0,1]
	ds_write2_b64 v117, v[22:23], v[20:21] offset1:72
	ds_write2_b64 v117, v[90:91], v[92:93] offset0:144 offset1:216
	ds_write2_b64 v56, v[88:89], v[86:87] offset0:32 offset1:104
	ds_write2_b64 v56, v[18:19], v[16:17] offset0:176 offset1:248
	ds_read2_b64 v[16:19], v191 offset1:72
	v_mov_b64_e32 v[94:95], v[224:225]
	ds_read2_b64 v[20:23], v191 offset0:144 offset1:216
	v_mov_b64_e32 v[96:97], v[226:227]
	v_mov_b64_e32 v[98:99], v[228:229]
	ds_read2_b64 v[86:89], v192 offset0:32 offset1:104
	v_mov_b64_e32 v[100:101], v[230:231]
	v_mov_b64_e32 v[102:103], v[232:233]
	ds_read2_b64 v[90:93], v192 offset0:176 offset1:248
	v_mov_b64_e32 v[194:195], v[234:235]
	s_waitcnt lgkmcnt(0)
; __device__ __forceinline__ c2 cmulc(c2 a, c2 b) { return (c2){a.x * b.x + a.y * b.y, a.y * b.x - a.x * b.y}; }
; __device__ __forceinline__ c2 mpi(c2 a) { return (c2){-a.y, a.x}; }
; __device__ __forceinline__ void idft8(c2 (&x)[8]) {
;     const float s = 0.70710678118654752f;
;     const c2 a0 = x[0] + x[4], a4 = x[0] - x[4], a1 = x[1] + x[5], a5 = x[1] - x[5], a2 = x[2] + x[6], a6 = x[2] - x[6], a3 = x[3] + x[7], a7 = x[3] - x[7];
;     const c2 a5w = (c2){(a5.x - a5.y) * s, (a5.x + a5.y) * s};
;     const c2 a6w = mpi(a6);
;     const c2 a7w = (c2){-(a7.x + a7.y) * s, (a7.x - a7.y) * s};
;     const c2 b0 = a0 + a2, b1 = a0 - a2, b2 = a1 + a3, b3 = mpi(a1 - a3);
;     x[0] = b0 + b2; x[4] = b0 - b2; x[2] = b1 + b3; x[6] = b1 - b3;
;     const c2 c0 = a4 + a6w, c1 = a4 - a6w, c2_ = a5w + a7w, c3 = mpi(a5w - a7w);
;     x[1] = c0 + c2_; x[5] = c0 - c2_; x[3] = c1 + c3; x[7] = c1 - c3;
; }
; template <int S> __device__ __forceinline__ void inv_mid(c2* buf, const c2* tws, int tid) {
;     constexpr int lq = 9 - 3 * S, Q = 1 << lq; const c2* T = tws + (S == 1 ? 3584 : 4032);
;     const int k = tid & (Q - 1), base = ((tid >> lq) << (lq + 3)) + k;
;     c2 x[8];
;     c2* bp_ = buf + LP(base); constexpr int QP = Q + Q / 8;
; #pragma unroll
;     for (int r = 0; r < 8; ++r) { c2 v = bp_[r * QP]; if (r) v = cmulc(v, T[(r - 1) * Q + k]); x[r] = v; }
;     idft8(x);
; #pragma unroll
;     for (int q = 0; q < 8; ++q) bp_[q * QP] = x[q];
; }
; __device__ __forceinline__ void inv_s0(c2 (&x)[8], const c2* buf, const c2* tws, int tid) {
;     const c2* bp_ = buf + LP(tid);
; #pragma unroll
;     for (int r = 0; r < 8; ++r) { c2 v = bp_[576 * r]; if (r) v = cmulc(v, tws[(r - 1) * 512 + tid]); x[r] = v; }
;     idft8(x);
; }
	v_pk_mul_f32 v[198:199], v[92:93], v[236:237] op_sel:[1,1] op_sel_hi:[0,1]
	v_fma_f32 v200, v92, v236, v198
	v_fma_f32 v201, v93, v236, -v199
	s_nop 0
	v_pk_mul_f32 v[92:93], v[18:19], v[94:95] op_sel:[1,1] op_sel_hi:[0,1]
	v_fma_f32 v196, v18, v94, v92
	v_fma_f32 v197, v19, v94, -v93
	s_nop 0
	v_pk_mul_f32 v[18:19], v[20:21], v[96:97] op_sel:[1,1] op_sel_hi:[0,1]
	v_fma_f32 v92, v20, v96, v18
	v_fma_f32 v93, v21, v96, -v19
	s_nop 0
	v_pk_mul_f32 v[18:19], v[22:23], v[98:99] op_sel:[1,1] op_sel_hi:[0,1]
	v_fma_f32 v20, v22, v98, v18
	v_fma_f32 v21, v23, v98, -v19
	s_nop 0
	v_pk_mul_f32 v[18:19], v[86:87], v[100:101] op_sel:[1,1] op_sel_hi:[0,1]
	v_fma_f32 v22, v86, v100, v18
	v_fma_f32 v23, v87, v100, -v19
	s_nop 0
	v_pk_mul_f32 v[18:19], v[88:89], v[102:103] op_sel:[1,1] op_sel_hi:[0,1]
	v_fma_f32 v86, v88, v102, v18
	v_fma_f32 v87, v89, v102, -v19
	s_nop 0
	v_pk_mul_f32 v[18:19], v[90:91], v[194:195] op_sel:[1,1] op_sel_hi:[0,1]
	v_fma_f32 v88, v90, v194, v18
	v_fma_f32 v89, v91, v194, -v19
	s_nop 0
	v_pk_add_f32 v[18:19], v[16:17], v[22:23]
	v_pk_add_f32 v[16:17], v[16:17], v[22:23] neg_lo:[0,1] neg_hi:[0,1]
	v_pk_add_f32 v[22:23], v[196:197], v[86:87]
	v_pk_add_f32 v[86:87], v[196:197], v[86:87] neg_lo:[0,1] neg_hi:[0,1]
	v_pk_add_f32 v[90:91], v[92:93], v[88:89]
	v_pk_add_f32 v[88:89], v[92:93], v[88:89] neg_lo:[0,1] neg_hi:[0,1]
	v_pk_add_f32 v[92:93], v[20:21], v[200:201]
	v_pk_add_f32 v[20:21], v[20:21], v[200:201] neg_lo:[0,1] neg_hi:[0,1]
	v_pk_add_f32 v[94:95], v[86:87], v[86:87] op_sel:[0,1] neg_lo:[0,1] neg_hi:[0,1]
	v_pk_add_f32 v[86:87], v[86:87], v[86:87] op_sel_hi:[0,1]
	v_mov_b32_e32 v95, v87
	v_xor_b32_e32 v86, 0x80000000, v89
	v_mov_b32_e32 v87, v88
	v_pk_add_f32 v[88:89], v[20:21], v[20:21] op_sel:[0,1]
	v_pk_add_f32 v[20:21], v[20:21], v[20:21] op_sel_hi:[0,1] neg_lo:[0,1] neg_hi:[0,1]
	v_mov_b32_e32 v89, v21
	v_pk_mul_f32 v[20:21], v[88:89], s[84:85]
	v_pk_add_f32 v[88:89], v[18:19], v[90:91]
	v_pk_add_f32 v[18:19], v[18:19], v[90:91] neg_lo:[0,1] neg_hi:[0,1]
	v_pk_add_f32 v[90:91], v[22:23], v[92:93]
	v_pk_add_f32 v[22:23], v[22:23], v[92:93] neg_lo:[0,1] neg_hi:[0,1]
	s_nop 0
	v_xor_b32_e32 v92, 0x80000000, v23
	v_mov_b32_e32 v93, v22
	v_pk_add_f32 v[22:23], v[88:89], v[90:91]
	v_pk_add_f32 v[88:89], v[88:89], v[90:91] neg_lo:[0,1] neg_hi:[0,1]
	v_pk_add_f32 v[90:91], v[18:19], v[92:93]
	v_pk_add_f32 v[18:19], v[18:19], v[92:93] neg_lo:[0,1] neg_hi:[0,1]
	v_pk_add_f32 v[92:93], v[16:17], v[86:87]
	v_pk_add_f32 v[16:17], v[16:17], v[86:87] neg_lo:[0,1] neg_hi:[0,1]
	v_pk_fma_f32 v[86:87], v[94:95], s[20:21], v[20:21] op_sel_hi:[1,0,1]
	v_pk_fma_f32 v[20:21], v[94:95], s[20:21], v[20:21] op_sel_hi:[1,0,1] neg_lo:[0,0,1] neg_hi:[0,0,1]
	s_nop 0
	v_xor_b32_e32 v94, 0x80000000, v21
	v_mov_b32_e32 v95, v20
	v_pk_add_f32 v[20:21], v[92:93], v[86:87]
	v_pk_add_f32 v[86:87], v[92:93], v[86:87] neg_lo:[0,1] neg_hi:[0,1]
	v_pk_add_f32 v[92:93], v[16:17], v[94:95]
	v_pk_add_f32 v[16:17], v[16:17], v[94:95] neg_lo:[0,1] neg_hi:[0,1]
	ds_write2_b64 v191, v[22:23], v[20:21] offset1:72
	ds_write2_b64 v191, v[90:91], v[92:93] offset0:144 offset1:216
	ds_write2_b64 v192, v[88:89], v[86:87] offset0:32 offset1:104
	ds_write2_b64 v192, v[18:19], v[16:17] offset0:176 offset1:248
	s_waitcnt lgkmcnt(0)
	s_barrier
	ds_read2st64_b64 v[20:23], v115 offset1:9
	v_mov_b64_e32 v[98:99], v[210:211]
	v_mov_b64_e32 v[100:101], v[212:213]
	v_mov_b64_e32 v[194:195], v[214:215]
	v_mov_b64_e32 v[196:197], v[216:217]
	ds_read2st64_b64 v[86:89], v115 offset0:36 offset1:45
	s_waitcnt lgkmcnt(0)
	v_pk_mul_f32 v[16:17], v[22:23], v[98:99] op_sel:[0,1]
	s_nop 0
	v_fma_f32 v92, v22, v98, v17
	v_fma_f32 v93, v23, v98, -v16
	s_nop 0
	ds_read2st64_b64 v[16:19], v115 offset0:18 offset1:27
	s_waitcnt lgkmcnt(0)
	v_pk_mul_f32 v[22:23], v[16:17], v[100:101] op_sel:[0,1]
	s_nop 0
	v_fma_f32 v94, v16, v100, v23
	v_fma_f32 v95, v17, v100, -v22
	s_nop 0
	v_pk_mul_f32 v[16:17], v[18:19], v[194:195] op_sel:[0,1]
	s_nop 0
	v_fma_f32 v22, v18, v194, v17
	v_fma_f32 v23, v19, v194, -v16
	s_nop 0
	v_pk_mul_f32 v[16:17], v[86:87], v[196:197] op_sel:[0,1]
	s_nop 0
	v_fma_f32 v96, v86, v196, v17
	v_fma_f32 v97, v87, v196, -v16
	s_nop 0
	v_mov_b64_e32 v[16:17], v[218:219]
	v_mov_b64_e32 v[18:19], v[220:221]
	v_pk_mul_f32 v[86:87], v[88:89], v[16:17] op_sel:[0,1]
	s_nop 0
	v_fma_f32 v102, v88, v16, v87
	v_fma_f32 v103, v89, v16, -v86
	ds_read2st64_b64 v[88:91], v115 offset0:54 offset1:63
	s_waitcnt lgkmcnt(0)
	v_pk_mul_f32 v[86:87], v[88:89], v[18:19] op_sel:[0,1]
	s_nop 0
	v_fma_f32 v198, v88, v18, v87
	v_fma_f32 v199, v89, v18, -v86
	v_mov_b64_e32 v[88:89], v[222:223]
	v_pk_mul_f32 v[86:87], v[90:91], v[88:89] op_sel:[0,1]
	s_nop 0
	v_fma_f32 v200, v90, v88, v87
	v_fma_f32 v201, v91, v88, -v86
	v_pk_add_f32 v[90:91], v[92:93], v[102:103]
	v_pk_add_f32 v[92:93], v[92:93], v[102:103] neg_lo:[0,1] neg_hi:[0,1]
	v_pk_add_f32 v[86:87], v[20:21], v[96:97]
	v_pk_add_f32 v[20:21], v[20:21], v[96:97] neg_lo:[0,1] neg_hi:[0,1]
	v_pk_add_f32 v[96:97], v[94:95], v[198:199]
	v_pk_add_f32 v[94:95], v[94:95], v[198:199] neg_lo:[0,1] neg_hi:[0,1]
	v_pk_add_f32 v[102:103], v[22:23], v[200:201]
	v_pk_add_f32 v[22:23], v[22:23], v[200:201] neg_lo:[0,1] neg_hi:[0,1]
	v_pk_add_f32 v[198:199], v[92:93], v[92:93] op_sel:[0,1] neg_lo:[0,1] neg_hi:[0,1]
	v_pk_add_f32 v[92:93], v[92:93], v[92:93] op_sel_hi:[0,1]
	v_mov_b32_e32 v199, v93
	v_xor_b32_e32 v92, 0x80000000, v95
	v_mov_b32_e32 v93, v94
	v_pk_add_f32 v[94:95], v[22:23], v[22:23] op_sel:[0,1]
	v_pk_add_f32 v[22:23], v[22:23], v[22:23] op_sel_hi:[0,1] neg_lo:[0,1] neg_hi:[0,1]
	v_mov_b32_e32 v95, v23
	v_pk_mul_f32 v[22:23], v[94:95], s[84:85]
	v_pk_add_f32 v[94:95], v[86:87], v[96:97]
	v_pk_add_f32 v[86:87], v[86:87], v[96:97] neg_lo:[0,1] neg_hi:[0,1]
	v_pk_add_f32 v[96:97], v[90:91], v[102:103]
	v_pk_add_f32 v[90:91], v[90:91], v[102:103] neg_lo:[0,1] neg_hi:[0,1]
	v_pk_add_f32 v[94:95], v[94:95], v[96:97]
	v_xor_b32_e32 v102, 0x80000000, v91
	v_mov_b32_e32 v103, v90
	v_pk_add_f32 v[90:91], v[86:87], v[102:103]
	v_pk_add_f32 v[86:87], v[20:21], v[92:93]
	v_pk_add_f32 v[20:21], v[20:21], v[92:93] neg_lo:[0,1] neg_hi:[0,1]
	v_pk_fma_f32 v[92:93], v[198:199], s[20:21], v[22:23] op_sel_hi:[1,0,1]
	v_pk_fma_f32 v[22:23], v[198:199], s[20:21], v[22:23] op_sel_hi:[1,0,1] neg_lo:[0,0,1] neg_hi:[0,0,1]
	v_pk_add_f32 v[92:93], v[86:87], v[92:93]
	v_xor_b32_e32 v96, 0x80000000, v23
	v_mov_b32_e32 v97, v22
	v_pk_add_f32 v[86:87], v[20:21], v[96:97]
	ds_read2st64_b64 v[20:23], v115 offset0:72 offset1:81
	ds_read2st64_b64 v[198:201], v115 offset0:90 offset1:99
	s_waitcnt lgkmcnt(0)
; __device__ __forceinline__ c2 cmulc(c2 a, c2 b) { return (c2){a.x * b.x + a.y * b.y, a.y * b.x - a.x * b.y}; }
; __device__ __forceinline__ void inv_s0(c2 (&x)[8], const c2* buf, const c2* tws, int tid) {
;     const c2* bp_ = buf + LP(tid);
; #pragma unroll
;     for (int r = 0; r < 8; ++r) { c2 v = bp_[576 * r]; if (r) v = cmulc(v, tws[(r - 1) * 512 + tid]); x[r] = v; }
;     idft8(x);
; }
	v_pk_mul_f32 v[102:103], v[98:99], v[22:23] op_sel:[1,0]
	s_nop 0
	v_fma_f32 v96, v98, v22, v103
	v_fma_f32 v97, v98, v23, -v102
	v_pk_mul_f32 v[98:99], v[100:101], v[198:199] op_sel:[1,0]
	v_fma_f32 v22, v100, v198, v99
	v_fma_f32 v23, v100, v199, -v98
	v_pk_mul_f32 v[100:101], v[194:195], v[200:201] op_sel:[1,0]
	v_fma_f32 v98, v194, v200, v101
	v_fma_f32 v99, v194, v201, -v100
	ds_read2st64_b64 v[198:201], v115 offset0:108 offset1:117
	s_waitcnt lgkmcnt(0)
	v_pk_mul_f32 v[102:103], v[196:197], v[198:199] op_sel:[1,0]
	s_nop 0
	v_fma_f32 v100, v196, v198, v103
	v_fma_f32 v101, v196, v199, -v102
	v_pk_mul_f32 v[194:195], v[16:17], v[200:201] op_sel:[1,0]
	v_fma_f32 v102, v16, v200, v195
	v_fma_f32 v103, v16, v201, -v194
	ds_read_b64 v[16:17], v115 offset:64512
	s_waitcnt lgkmcnt(0)
	v_pk_mul_f32 v[194:195], v[18:19], v[16:17] op_sel:[1,0]
	s_nop 0
	v_fma_f32 v196, v18, v16, v195
	v_fma_f32 v197, v18, v17, -v194
	ds_read_b64 v[16:17], v116 offset:32256
	s_waitcnt lgkmcnt(0)
	v_pk_mul_f32 v[18:19], v[88:89], v[16:17] op_sel:[1,0]
	s_nop 0
	v_fma_f32 v194, v88, v16, v19
	v_fma_f32 v195, v88, v17, -v18
	v_pk_add_f32 v[88:89], v[96:97], v[102:103] neg_lo:[0,1] neg_hi:[0,1]
	v_pk_add_f32 v[16:17], v[20:21], v[100:101]
	v_pk_add_f32 v[20:21], v[20:21], v[100:101] neg_lo:[0,1] neg_hi:[0,1]
	v_pk_add_f32 v[18:19], v[96:97], v[102:103]
	v_pk_add_f32 v[96:97], v[22:23], v[196:197]
	v_pk_add_f32 v[22:23], v[22:23], v[196:197] neg_lo:[0,1] neg_hi:[0,1]
	v_pk_add_f32 v[100:101], v[98:99], v[194:195]
	v_pk_add_f32 v[98:99], v[98:99], v[194:195] neg_lo:[0,1] neg_hi:[0,1]
	v_pk_add_f32 v[102:103], v[88:89], v[88:89] op_sel:[0,1] neg_lo:[0,1] neg_hi:[0,1]
	v_pk_add_f32 v[88:89], v[88:89], v[88:89] op_sel_hi:[0,1]
	v_mov_b32_e32 v103, v89
	v_xor_b32_e32 v194, 0x80000000, v23
	v_mov_b32_e32 v195, v22
	v_pk_add_f32 v[22:23], v[98:99], v[98:99] op_sel:[0,1]
	v_pk_add_f32 v[88:89], v[98:99], v[98:99] op_sel_hi:[0,1] neg_lo:[0,1] neg_hi:[0,1]
	v_mov_b32_e32 v23, v89
	v_pk_mul_f32 v[22:23], v[22:23], s[84:85]
	v_pk_add_f32 v[88:89], v[16:17], v[96:97]
	v_pk_add_f32 v[16:17], v[16:17], v[96:97] neg_lo:[0,1] neg_hi:[0,1]
	v_pk_add_f32 v[96:97], v[18:19], v[100:101]
	v_pk_add_f32 v[18:19], v[18:19], v[100:101] neg_lo:[0,1] neg_hi:[0,1]
	v_pk_add_f32 v[88:89], v[88:89], v[96:97]
	v_xor_b32_e32 v98, 0x80000000, v19
	v_mov_b32_e32 v99, v18
	v_pk_fma_f32 v[96:97], v[102:103], s[20:21], v[22:23] op_sel_hi:[1,0,1]
	v_pk_fma_f32 v[22:23], v[102:103], s[20:21], v[22:23] op_sel_hi:[1,0,1] neg_lo:[0,0,1] neg_hi:[0,0,1]
	v_pk_add_f32 v[18:19], v[16:17], v[98:99]
	v_pk_add_f32 v[16:17], v[20:21], v[194:195]
	v_pk_add_f32 v[20:21], v[20:21], v[194:195] neg_lo:[0,1] neg_hi:[0,1]
	v_xor_b32_e32 v98, 0x80000000, v23
	v_mov_b32_e32 v99, v22
	v_pk_add_f32 v[22:23], v[16:17], v[96:97]
	v_pk_add_f32 v[16:17], v[20:21], v[98:99]
	ds_read_u16 v20, v160 offset:14
	ds_read_u16 v21, v160 offset:16
	ds_read_u16 v63, v160 offset:18
	v_pk_mul_f32 v[96:97], v[66:67], v[94:95]
	v_pk_mul_f32 v[22:23], v[66:67], v[22:23]
	s_waitcnt lgkmcnt(0)
	v_lshlrev_b32_e32 v20, 16, v20
	v_lshlrev_b32_e32 v21, 16, v21
	v_mul_f32_e32 v21, v190, v21
	v_fmac_f32_e32 v21, v187, v20
	v_lshlrev_b32_e32 v20, 16, v63
	v_fmac_f32_e32 v21, v189, v20
	v_add_f32_e32 v20, v188, v21
	ds_read_u16 v21, v161 offset:14
	ds_read_u16 v63, v161 offset:16
	ds_read_u16 v94, v161 offset:18
	v_fmac_f32_e32 v97, v184, v85
	v_fma_f32 v22, v184, v74, v22
	s_waitcnt lgkmcnt(0)
	v_lshlrev_b32_e32 v21, 16, v21
	v_lshlrev_b32_e32 v63, 16, v63
	v_mul_f32_e32 v63, v190, v63
	v_fmac_f32_e32 v63, v187, v21
	v_lshlrev_b32_e32 v21, 16, v94
	v_fmac_f32_e32 v63, v189, v21
	v_fma_f32 v21, v184, v84, v96
	v_mul_f32_e32 v20, v21, v20
	v_cvt_pk_bf16_f32 v84, v20, s0
	v_add_u32_e32 v20, s92, v113
	v_ashrrev_i32_e32 v21, 31, v20
	v_lshl_add_u64 v[94:95], v[20:21], 1, s[50:51]
	v_add_f32_e32 v63, v188, v63
	global_store_short v[94:95], v84, off
	v_add_u32_e32 v84, 0x800, v20
	v_mul_f32_e32 v21, v97, v63
	v_ashrrev_i32_e32 v85, 31, v84
	v_cvt_pk_bf16_f32 v21, v21, s0
	v_lshl_add_u64 v[84:85], v[84:85], 1, s[50:51]
	global_store_short v[84:85], v21, off
	v_pk_mul_f32 v[84:85], v[66:67], v[92:93]
	ds_read_u16 v21, v162 offset:14
	ds_read_u16 v63, v162 offset:16
	ds_read_u16 v92, v162 offset:18
	v_fma_f32 v82, v184, v82, v84
	v_fmac_f32_e32 v85, v184, v83
	s_waitcnt lgkmcnt(0)
	v_lshlrev_b32_e32 v21, 16, v21
	v_lshlrev_b32_e32 v63, 16, v63
	v_mul_f32_e32 v63, v190, v63
	v_fmac_f32_e32 v63, v187, v21
	v_lshlrev_b32_e32 v21, 16, v92
	v_fmac_f32_e32 v63, v189, v21
	v_add_f32_e32 v21, v188, v63
	ds_read_u16 v63, v163 offset:14
	ds_read_u16 v92, v163 offset:16
	ds_read_u16 v93, v163 offset:18
	v_mul_f32_e32 v21, v82, v21
	v_cvt_pk_bf16_f32 v21, v21, s0
	s_waitcnt lgkmcnt(0)
	v_lshlrev_b32_e32 v63, 16, v63
	v_lshlrev_b32_e32 v92, 16, v92
	v_mul_f32_e32 v92, v190, v92
	v_fmac_f32_e32 v92, v187, v63
	v_lshlrev_b32_e32 v63, 16, v93
	v_fmac_f32_e32 v92, v189, v63
	v_add_f32_e32 v63, v188, v92
	v_add_u32_e32 v82, 0xa00, v20
	global_store_short v[94:95], v21, off offset:1024
	v_mul_f32_e32 v21, v85, v63
	v_ashrrev_i32_e32 v83, 31, v82
	v_cvt_pk_bf16_f32 v21, v21, s0
	v_lshl_add_u64 v[82:83], v[82:83], 1, s[50:51]
	global_store_short v[82:83], v21, off
	ds_read_u16 v21, v164 offset:14
	ds_read_u16 v63, v164 offset:16
	ds_read_u16 v84, v164 offset:18
	v_pk_mul_f32 v[82:83], v[66:67], v[90:91]
	v_fmac_f32_e32 v23, v184, v75
	s_waitcnt lgkmcnt(0)
	v_lshlrev_b32_e32 v21, 16, v21
	v_lshlrev_b32_e32 v63, 16, v63
	v_mul_f32_e32 v63, v190, v63
	v_fmac_f32_e32 v63, v187, v21
	v_lshlrev_b32_e32 v21, 16, v84
	v_fmac_f32_e32 v63, v189, v21
	v_add_f32_e32 v21, v188, v63
	ds_read_u16 v63, v165 offset:14
	ds_read_u16 v84, v165 offset:16
	ds_read_u16 v85, v165 offset:18
	v_fma_f32 v78, v184, v78, v82
	v_mul_f32_e32 v21, v78, v21
	s_waitcnt lgkmcnt(0)
; __device__ __forceinline__ void phase_conv(const Params& p, int o, unsigned char* smem, int wave) {
;     ...
;                 EPIZ(x0, zk0, 0, gq); EPIZ(x1, zk1, 2, gq);
	v_lshlrev_b32_e32 v63, 16, v63
	v_lshlrev_b32_e32 v84, 16, v84
	v_mul_f32_e32 v84, v190, v84
	v_fmac_f32_e32 v84, v187, v63
	v_lshlrev_b32_e32 v63, 16, v85
	v_fmac_f32_e32 v84, v189, v63
	v_add_f32_e32 v63, v188, v84
	v_cvt_pk_bf16_f32 v21, v21, s0
	v_fmac_f32_e32 v83, v184, v79
	v_add_u32_e32 v78, 0xc00, v20
	global_store_short v[94:95], v21, off offset:2048
	v_mul_f32_e32 v21, v83, v63
	v_ashrrev_i32_e32 v79, 31, v78
	v_cvt_pk_bf16_f32 v21, v21, s0
	v_lshl_add_u64 v[78:79], v[78:79], 1, s[50:51]
	global_store_short v[78:79], v21, off
	ds_read_u16 v21, v166 offset:14
	ds_read_u16 v63, v166 offset:16
	ds_read_u16 v82, v166 offset:18
	v_pk_mul_f32 v[78:79], v[66:67], v[86:87]
	v_pk_mul_f32 v[18:19], v[66:67], v[18:19]
	s_waitcnt lgkmcnt(0)
	v_lshlrev_b32_e32 v21, 16, v21
	v_lshlrev_b32_e32 v63, 16, v63
	v_mul_f32_e32 v63, v190, v63
	v_fmac_f32_e32 v63, v187, v21
	v_lshlrev_b32_e32 v21, 16, v82
	v_fmac_f32_e32 v63, v189, v21
	v_add_f32_e32 v21, v188, v63
	ds_read_u16 v63, v167 offset:14
	ds_read_u16 v82, v167 offset:16
	ds_read_u16 v83, v167 offset:18
	v_fma_f32 v78, v184, v80, v78
	v_mul_f32_e32 v21, v78, v21
	s_waitcnt lgkmcnt(0)
	v_lshlrev_b32_e32 v63, 16, v63
	v_lshlrev_b32_e32 v82, 16, v82
	v_mul_f32_e32 v82, v190, v82
	v_fmac_f32_e32 v82, v187, v63
	v_lshlrev_b32_e32 v63, 16, v83
	v_fmac_f32_e32 v82, v189, v63
	v_add_f32_e32 v63, v188, v82
	v_cvt_pk_bf16_f32 v21, v21, s0
	v_fmac_f32_e32 v79, v184, v81
	v_add_u32_e32 v78, 0xe00, v20
	global_store_short v[94:95], v21, off offset:3072
	v_mul_f32_e32 v21, v79, v63
	v_ashrrev_i32_e32 v79, 31, v78
	v_cvt_pk_bf16_f32 v21, v21, s0
	v_lshl_add_u64 v[78:79], v[78:79], 1, s[50:51]
	global_store_short v[78:79], v21, off
	ds_read_u16 v21, v168 offset:14
	ds_read_u16 v63, v168 offset:16
	ds_read_u16 v80, v168 offset:18
	v_pk_mul_f32 v[78:79], v[66:67], v[88:89]
	v_fma_f32 v18, v184, v72, v18
	s_waitcnt lgkmcnt(0)
	v_lshlrev_b32_e32 v21, 16, v21
	v_lshlrev_b32_e32 v63, 16, v63
	v_mul_f32_e32 v63, v190, v63
	v_fmac_f32_e32 v63, v187, v21
	v_lshlrev_b32_e32 v21, 16, v80
	v_fmac_f32_e32 v63, v189, v21
	v_add_f32_e32 v21, v188, v63
	ds_read_u16 v63, v169 offset:14
	ds_read_u16 v80, v169 offset:16
	ds_read_u16 v81, v169 offset:18
	v_fma_f32 v76, v184, v76, v78
	v_mul_f32_e32 v21, v76, v21
	s_waitcnt lgkmcnt(0)
	v_lshlrev_b32_e32 v63, 16, v63
	v_lshlrev_b32_e32 v80, 16, v80
	v_mul_f32_e32 v80, v190, v80
	v_fmac_f32_e32 v80, v187, v63
	v_lshlrev_b32_e32 v63, 16, v81
	v_fmac_f32_e32 v80, v189, v63
	v_add_f32_e32 v63, v188, v80
	v_add_u32_e32 v80, 0x1000, v20
	v_ashrrev_i32_e32 v81, 31, v80
	v_cvt_pk_bf16_f32 v21, v21, s0
	v_lshl_add_u64 v[80:81], v[80:81], 1, s[50:51]
	v_fmac_f32_e32 v79, v184, v77
	v_add_u32_e32 v76, 0x1800, v20
	global_store_short v[80:81], v21, off
	v_mul_f32_e32 v21, v79, v63
	v_ashrrev_i32_e32 v77, 31, v76
	v_cvt_pk_bf16_f32 v21, v21, s0
	v_lshl_add_u64 v[76:77], v[76:77], 1, s[50:51]
	global_store_short v[76:77], v21, off
	ds_read_u16 v21, v170 offset:14
	ds_read_u16 v63, v170 offset:16
	ds_read_u16 v76, v170 offset:18
	v_fmac_f32_e32 v19, v184, v73
	v_pk_mul_f32 v[16:17], v[66:67], v[16:17]
	s_waitcnt lgkmcnt(0)
	v_lshlrev_b32_e32 v21, 16, v21
	v_lshlrev_b32_e32 v63, 16, v63
	v_mul_f32_e32 v63, v190, v63
	v_fmac_f32_e32 v63, v187, v21
	v_lshlrev_b32_e32 v21, 16, v76
	v_fmac_f32_e32 v63, v189, v21
	v_add_f32_e32 v21, v188, v63
	ds_read_u16 v63, v171 offset:14
	ds_read_u16 v76, v171 offset:16
	ds_read_u16 v77, v171 offset:18
	v_mul_f32_e32 v21, v22, v21
	v_cvt_pk_bf16_f32 v21, v21, s0
	s_waitcnt lgkmcnt(0)
	v_lshlrev_b32_e32 v63, 16, v63
	v_lshlrev_b32_e32 v76, 16, v76
	v_mul_f32_e32 v76, v190, v76
	v_fmac_f32_e32 v76, v187, v63
	v_lshlrev_b32_e32 v63, 16, v77
	v_fmac_f32_e32 v76, v189, v63
	v_add_f32_e32 v63, v188, v76
	v_add_u32_e32 v76, 0x1200, v20
	v_ashrrev_i32_e32 v77, 31, v76
	v_lshl_add_u64 v[76:77], v[76:77], 1, s[50:51]
	v_add_u32_e32 v22, 0x1a00, v20
	global_store_short v[76:77], v21, off
	v_mul_f32_e32 v21, v23, v63
	v_ashrrev_i32_e32 v23, 31, v22
	v_cvt_pk_bf16_f32 v21, v21, s0
	v_lshl_add_u64 v[22:23], v[22:23], 1, s[50:51]
	global_store_short v[22:23], v21, off
	ds_read_u16 v21, v172 offset:14
	ds_read_u16 v22, v172 offset:16
	ds_read_u16 v23, v172 offset:18
	v_fma_f32 v16, v184, v70, v16
	v_fmac_f32_e32 v17, v184, v71
	s_waitcnt lgkmcnt(0)
	v_lshlrev_b32_e32 v21, 16, v21
	v_lshlrev_b32_e32 v22, 16, v22
	v_mul_f32_e32 v22, v190, v22
	v_fmac_f32_e32 v22, v187, v21
	v_lshlrev_b32_e32 v21, 16, v23
	v_fmac_f32_e32 v22, v189, v21
	v_add_f32_e32 v21, v188, v22
	ds_read_u16 v22, v173 offset:14
	ds_read_u16 v23, v173 offset:16
	ds_read_u16 v63, v173 offset:18
	v_mul_f32_e32 v18, v18, v21
	v_cvt_pk_bf16_f32 v18, v18, s0
	s_waitcnt lgkmcnt(0)
	v_lshlrev_b32_e32 v22, 16, v22
	v_lshlrev_b32_e32 v23, 16, v23
	v_mul_f32_e32 v23, v190, v23
	v_fmac_f32_e32 v23, v187, v22
	v_lshlrev_b32_e32 v22, 16, v63
	v_fmac_f32_e32 v23, v189, v22
	v_add_u32_e32 v22, 0x1400, v20
	v_add_f32_e32 v63, v188, v23
	v_ashrrev_i32_e32 v23, 31, v22
	v_lshl_add_u64 v[22:23], v[22:23], 1, s[50:51]
	global_store_short v[22:23], v18, off
	v_mul_f32_e32 v18, v19, v63
	v_cvt_pk_bf16_f32 v21, v18, s0
	v_add_u32_e32 v18, 0x1c00, v20
	v_ashrrev_i32_e32 v19, 31, v18
	v_lshl_add_u64 v[18:19], v[18:19], 1, s[50:51]
	global_store_short v[18:19], v21, off
	ds_read_u16 v18, v174 offset:14
	ds_read_u16 v19, v174 offset:16
	ds_read_u16 v21, v174 offset:18
	s_addk_i32 s92, 0x2000
	s_cmp_eq_u32 s92, 0x10000
	s_waitcnt lgkmcnt(0)
	v_lshlrev_b32_e32 v18, 16, v18
	v_lshlrev_b32_e32 v19, 16, v19
	v_mul_f32_e32 v19, v190, v19
	v_fmac_f32_e32 v19, v187, v18
	v_lshlrev_b32_e32 v18, 16, v21
	v_fmac_f32_e32 v19, v189, v18
	v_add_f32_e32 v18, v188, v19
	ds_read_u16 v19, v175 offset:14
	ds_read_u16 v21, v175 offset:16
	ds_read_u16 v22, v175 offset:18
	v_mul_f32_e32 v16, v16, v18
	v_add_u32_e32 v18, 0x1600, v20
	s_waitcnt lgkmcnt(0)
	v_lshlrev_b32_e32 v19, 16, v19
	v_lshlrev_b32_e32 v21, 16, v21
	v_mul_f32_e32 v21, v190, v21
	v_fmac_f32_e32 v21, v187, v19
	v_lshlrev_b32_e32 v19, 16, v22
	v_fmac_f32_e32 v21, v189, v19
	v_ashrrev_i32_e32 v19, 31, v18
	v_add_f32_e32 v21, v188, v21
	v_cvt_pk_bf16_f32 v16, v16, s0
	v_lshl_add_u64 v[18:19], v[18:19], 1, s[50:51]
	global_store_short v[18:19], v16, off
	v_mul_f32_e32 v16, v17, v21
	v_cvt_pk_bf16_f32 v18, v16, s0
	v_add_u32_e32 v16, 0x1e00, v20
	v_ashrrev_i32_e32 v17, 31, v16
	v_lshl_add_u64 v[16:17], v[16:17], 1, s[50:51]
	global_store_short v[16:17], v18, off
	s_cbranch_scc1 .LBB0_379

; __device__ __forceinline__ float bf2f(bf16_t b) { return __uint_as_float(((unsigned)b) << 16); }
; #define ZVAL(r, t) ((o == 0) ? dwl((r), (t), zw0, zw1, zw2, zb) : bf2f((r)[8 + (t)]))
; __device__ __forceinline__ float dwl(const bf16_t* r, int t, float w0, float w1, float w2, float b) { return w0 * bf2f(r[7 + t]) + w1 * bf2f(r[8 + t]) + w2 * bf2f(r[9 + t]) + b; }
; __device__ __forceinline__ void phase_conv(const Params& p, int o, unsigned char* smem, int wave) {
;     ...
;                 for (int r = 0; r < 4; ++r) { const int t = tid + 512 * r;
;                     x0[r] = (c2){ZVAL(raw, t), ZVAL(raw + RAWROW, t)}; x1[r] = (c2){ZVAL(raw + 2 * RAWROW, t), ZVAL(raw + 3 * RAWROW, t)}; zk0[r] = x0[r]; zk1[r] = x1[r];
;                     x0[4 + r] = (c2){0.f, 0.f}; x1[4 + r] = (c2){0.f, 0.f}; }
.LBB0_320:
	ds_read_u16 v16, v147 offset:16
	ds_read_u16 v17, v147 offset:18
	ds_read_u16 v18, v147 offset:14
	s_waitcnt lgkmcnt(0)
	v_lshlrev_b32_e32 v19, 16, v16
	v_lshlrev_b32_e32 v17, 16, v17
	v_lshlrev_b32_e32 v16, 16, v18
	v_pk_mul_f32 v[16:17], v[64:65], v[16:17]
	s_nop 0
	v_fma_f32 v16, v186, v19, v16
	v_add_f32_e32 v16, v16, v17
	v_add_f32_e32 v77, v185, v16

; __device__ __forceinline__ float bf2f(bf16_t b) { return __uint_as_float(((unsigned)b) << 16); }
; #define ZVAL(r, t) ((o == 0) ? dwl((r), (t), zw0, zw1, zw2, zb) : bf2f((r)[8 + (t)]))
; __device__ __forceinline__ float dwl(const bf16_t* r, int t, float w0, float w1, float w2, float b) { return w0 * bf2f(r[7 + t]) + w1 * bf2f(r[8 + t]) + w2 * bf2f(r[9 + t]) + b; }
; __device__ __forceinline__ void phase_conv(const Params& p, int o, unsigned char* smem, int wave) {
;     ...
;                 for (int r = 0; r < 4; ++r) { const int t = tid + 512 * r;
;                     x0[r] = (c2){ZVAL(raw, t), ZVAL(raw + RAWROW, t)}; x1[r] = (c2){ZVAL(raw + 2 * RAWROW, t), ZVAL(raw + 3 * RAWROW, t)}; zk0[r] = x0[r]; zk1[r] = x1[r];
;                     x0[4 + r] = (c2){0.f, 0.f}; x1[4 + r] = (c2){0.f, 0.f}; }
.LBB0_349:
	ds_read_u16 v16, v144 offset:16
	ds_read_u16 v17, v144 offset:18
	ds_read_u16 v18, v144 offset:14
	s_waitcnt lgkmcnt(0)
	v_lshlrev_b32_e32 v19, 16, v16
	v_lshlrev_b32_e32 v17, 16, v17
	v_lshlrev_b32_e32 v16, 16, v18
	v_pk_mul_f32 v[16:17], v[64:65], v[16:17]
	s_nop 0
	v_fma_f32 v16, v186, v19, v16
	v_add_f32_e32 v16, v16, v17
	v_add_f32_e32 v84, v185, v16
	s_mov_b64 s[72:73], -1
	s_and_b64 vcc, exec, s[30:31]
	s_cbranch_vccz .LBB0_315

; __device__ __forceinline__ float bf2f(bf16_t b) { return __uint_as_float(((unsigned)b) << 16); }
; #define ZVAL(r, t) ((o == 0) ? dwl((r), (t), zw0, zw1, zw2, zb) : bf2f((r)[8 + (t)]))
; __device__ __forceinline__ float dwl(const bf16_t* r, int t, float w0, float w1, float w2, float b) { return w0 * bf2f(r[7 + t]) + w1 * bf2f(r[8 + t]) + w2 * bf2f(r[9 + t]) + b; }
; __device__ __forceinline__ void phase_conv(const Params& p, int o, unsigned char* smem, int wave) {
;     ...
;                 for (int r = 0; r < 4; ++r) { const int t = tid + 512 * r;
;                     x0[r] = (c2){ZVAL(raw, t), ZVAL(raw + RAWROW, t)}; x1[r] = (c2){ZVAL(raw + 2 * RAWROW, t), ZVAL(raw + 3 * RAWROW, t)}; zk0[r] = x0[r]; zk1[r] = x1[r];
;                     x0[4 + r] = (c2){0.f, 0.f}; x1[4 + r] = (c2){0.f, 0.f}; }
.LBB0_351:
	ds_read_u16 v16, v145 offset:16
	ds_read_u16 v17, v145 offset:18
	ds_read_u16 v18, v145 offset:14
	s_waitcnt lgkmcnt(0)
	v_lshlrev_b32_e32 v19, 16, v16
	v_lshlrev_b32_e32 v17, 16, v17
	v_lshlrev_b32_e32 v16, 16, v18
	v_pk_mul_f32 v[16:17], v[64:65], v[16:17]
	s_nop 0
	v_fma_f32 v16, v186, v19, v16
	v_add_f32_e32 v16, v16, v17
	v_add_f32_e32 v85, v185, v16
	s_mov_b64 s[72:73], -1
	s_and_b64 vcc, exec, s[30:31]
	s_cbranch_vccz .LBB0_317

; __device__ __forceinline__ float bf2f(bf16_t b) { return __uint_as_float(((unsigned)b) << 16); }
; #define ZVAL(r, t) ((o == 0) ? dwl((r), (t), zw0, zw1, zw2, zb) : bf2f((r)[8 + (t)]))
; __device__ __forceinline__ float dwl(const bf16_t* r, int t, float w0, float w1, float w2, float b) { return w0 * bf2f(r[7 + t]) + w1 * bf2f(r[8 + t]) + w2 * bf2f(r[9 + t]) + b; }
; __device__ __forceinline__ void phase_conv(const Params& p, int o, unsigned char* smem, int wave) {
;     ...
;                 for (int r = 0; r < 4; ++r) { const int t = tid + 512 * r;
;                     x0[r] = (c2){ZVAL(raw, t), ZVAL(raw + RAWROW, t)}; x1[r] = (c2){ZVAL(raw + 2 * RAWROW, t), ZVAL(raw + 3 * RAWROW, t)}; zk0[r] = x0[r]; zk1[r] = x1[r];
;                     x0[4 + r] = (c2){0.f, 0.f}; x1[4 + r] = (c2){0.f, 0.f}; }
.LBB0_353:
	ds_read_u16 v16, v146 offset:16
	ds_read_u16 v17, v146 offset:18
	ds_read_u16 v18, v146 offset:14
	s_waitcnt lgkmcnt(0)
	v_lshlrev_b32_e32 v19, 16, v16
	v_lshlrev_b32_e32 v17, 16, v17
	v_lshlrev_b32_e32 v16, 16, v18
	v_pk_mul_f32 v[16:17], v[64:65], v[16:17]
	s_nop 0
	v_fma_f32 v16, v186, v19, v16
	v_add_f32_e32 v16, v16, v17
	v_add_f32_e32 v76, v185, v16
	s_mov_b64 s[72:73], -1
	s_and_b64 vcc, exec, s[30:31]
	s_cbranch_vccz .LBB0_319

; __device__ __forceinline__ float bf2f(bf16_t b) { return __uint_as_float(((unsigned)b) << 16); }
; #define ZVAL(r, t) ((o == 0) ? dwl((r), (t), zw0, zw1, zw2, zb) : bf2f((r)[8 + (t)]))
; __device__ __forceinline__ float dwl(const bf16_t* r, int t, float w0, float w1, float w2, float b) { return w0 * bf2f(r[7 + t]) + w1 * bf2f(r[8 + t]) + w2 * bf2f(r[9 + t]) + b; }
; __device__ __forceinline__ void phase_conv(const Params& p, int o, unsigned char* smem, int wave) {
;     ...
;                 for (int r = 0; r < 4; ++r) { const int t = tid + 512 * r;
;                     x0[r] = (c2){ZVAL(raw, t), ZVAL(raw + RAWROW, t)}; x1[r] = (c2){ZVAL(raw + 2 * RAWROW, t), ZVAL(raw + 3 * RAWROW, t)}; zk0[r] = x0[r]; zk1[r] = x1[r];
;                     x0[4 + r] = (c2){0.f, 0.f}; x1[4 + r] = (c2){0.f, 0.f}; }
.LBB0_356:
	ds_read_u16 v16, v148 offset:16
	ds_read_u16 v17, v148 offset:18
	ds_read_u16 v18, v148 offset:14
	s_waitcnt lgkmcnt(0)
	v_lshlrev_b32_e32 v19, 16, v16
	v_lshlrev_b32_e32 v17, 16, v17
	v_lshlrev_b32_e32 v16, 16, v18
	v_pk_mul_f32 v[16:17], v[64:65], v[16:17]
	s_nop 0
	v_fma_f32 v16, v186, v19, v16
	v_add_f32_e32 v16, v16, v17
	v_add_f32_e32 v82, v185, v16
	s_and_b64 vcc, exec, s[84:85]
	s_mov_b64 s[72:73], -1
	s_cbranch_vccnz .LBB0_324

; __device__ __forceinline__ float bf2f(bf16_t b) { return __uint_as_float(((unsigned)b) << 16); }
; #define ZVAL(r, t) ((o == 0) ? dwl((r), (t), zw0, zw1, zw2, zb) : bf2f((r)[8 + (t)]))
; __device__ __forceinline__ float dwl(const bf16_t* r, int t, float w0, float w1, float w2, float b) { return w0 * bf2f(r[7 + t]) + w1 * bf2f(r[8 + t]) + w2 * bf2f(r[9 + t]) + b; }
; __device__ __forceinline__ void phase_conv(const Params& p, int o, unsigned char* smem, int wave) {
;     ...
;                 for (int r = 0; r < 4; ++r) { const int t = tid + 512 * r;
;                     x0[r] = (c2){ZVAL(raw, t), ZVAL(raw + RAWROW, t)}; x1[r] = (c2){ZVAL(raw + 2 * RAWROW, t), ZVAL(raw + 3 * RAWROW, t)}; zk0[r] = x0[r]; zk1[r] = x1[r];
;                     x0[4 + r] = (c2){0.f, 0.f}; x1[4 + r] = (c2){0.f, 0.f}; }
.LBB0_358:
	ds_read_u16 v16, v149 offset:16
	ds_read_u16 v17, v149 offset:18
	ds_read_u16 v18, v149 offset:14
	s_waitcnt lgkmcnt(0)
	v_lshlrev_b32_e32 v19, 16, v16
	v_lshlrev_b32_e32 v17, 16, v17
	v_lshlrev_b32_e32 v16, 16, v18
	v_pk_mul_f32 v[16:17], v[64:65], v[16:17]
	s_nop 0
	v_fma_f32 v16, v186, v19, v16
	v_add_f32_e32 v16, v16, v17
	v_add_f32_e32 v83, v185, v16
	s_and_b64 vcc, exec, s[84:85]
	s_mov_b64 s[72:73], -1
	s_cbranch_vccnz .LBB0_326

; __device__ __forceinline__ float bf2f(bf16_t b) { return __uint_as_float(((unsigned)b) << 16); }
; #define ZVAL(r, t) ((o == 0) ? dwl((r), (t), zw0, zw1, zw2, zb) : bf2f((r)[8 + (t)]))
; __device__ __forceinline__ float dwl(const bf16_t* r, int t, float w0, float w1, float w2, float b) { return w0 * bf2f(r[7 + t]) + w1 * bf2f(r[8 + t]) + w2 * bf2f(r[9 + t]) + b; }
; __device__ __forceinline__ void phase_conv(const Params& p, int o, unsigned char* smem, int wave) {
;     ...
;                 for (int r = 0; r < 4; ++r) { const int t = tid + 512 * r;
;                     x0[r] = (c2){ZVAL(raw, t), ZVAL(raw + RAWROW, t)}; x1[r] = (c2){ZVAL(raw + 2 * RAWROW, t), ZVAL(raw + 3 * RAWROW, t)}; zk0[r] = x0[r]; zk1[r] = x1[r];
;                     x0[4 + r] = (c2){0.f, 0.f}; x1[4 + r] = (c2){0.f, 0.f}; }
.LBB0_360:
	ds_read_u16 v16, v150 offset:16
	ds_read_u16 v17, v150 offset:18
	ds_read_u16 v18, v150 offset:14
	s_waitcnt lgkmcnt(0)
	v_lshlrev_b32_e32 v19, 16, v16
	v_lshlrev_b32_e32 v17, 16, v17
	v_lshlrev_b32_e32 v16, 16, v18
	v_pk_mul_f32 v[16:17], v[64:65], v[16:17]
	s_nop 0
	v_fma_f32 v16, v186, v19, v16
	v_add_f32_e32 v16, v16, v17
	v_add_f32_e32 v74, v185, v16
	s_and_b64 vcc, exec, s[84:85]
	s_mov_b64 s[72:73], -1
	s_cbranch_vccnz .LBB0_328

; __device__ __forceinline__ float bf2f(bf16_t b) { return __uint_as_float(((unsigned)b) << 16); }
; #define ZVAL(r, t) ((o == 0) ? dwl((r), (t), zw0, zw1, zw2, zb) : bf2f((r)[8 + (t)]))
; __device__ __forceinline__ float dwl(const bf16_t* r, int t, float w0, float w1, float w2, float b) { return w0 * bf2f(r[7 + t]) + w1 * bf2f(r[8 + t]) + w2 * bf2f(r[9 + t]) + b; }
; __device__ __forceinline__ void phase_conv(const Params& p, int o, unsigned char* smem, int wave) {
;     ...
;                 for (int r = 0; r < 4; ++r) { const int t = tid + 512 * r;
;                     x0[r] = (c2){ZVAL(raw, t), ZVAL(raw + RAWROW, t)}; x1[r] = (c2){ZVAL(raw + 2 * RAWROW, t), ZVAL(raw + 3 * RAWROW, t)}; zk0[r] = x0[r]; zk1[r] = x1[r];
;                     x0[4 + r] = (c2){0.f, 0.f}; x1[4 + r] = (c2){0.f, 0.f}; }
.LBB0_362:
	ds_read_u16 v16, v151 offset:16
	ds_read_u16 v17, v151 offset:18
	ds_read_u16 v18, v151 offset:14
	s_waitcnt lgkmcnt(0)
	v_lshlrev_b32_e32 v19, 16, v16
	v_lshlrev_b32_e32 v17, 16, v17
	v_lshlrev_b32_e32 v16, 16, v18
	v_pk_mul_f32 v[16:17], v[64:65], v[16:17]
	s_nop 0
	v_fma_f32 v16, v186, v19, v16
	v_add_f32_e32 v16, v16, v17
	v_add_f32_e32 v75, v185, v16
	s_and_b64 vcc, exec, s[84:85]
	s_mov_b64 s[72:73], -1
	s_cbranch_vccnz .LBB0_330

; __device__ __forceinline__ float bf2f(bf16_t b) { return __uint_as_float(((unsigned)b) << 16); }
; #define ZVAL(r, t) ((o == 0) ? dwl((r), (t), zw0, zw1, zw2, zb) : bf2f((r)[8 + (t)]))
; __device__ __forceinline__ float dwl(const bf16_t* r, int t, float w0, float w1, float w2, float b) { return w0 * bf2f(r[7 + t]) + w1 * bf2f(r[8 + t]) + w2 * bf2f(r[9 + t]) + b; }
; __device__ __forceinline__ void phase_conv(const Params& p, int o, unsigned char* smem, int wave) {
;     ...
;                 for (int r = 0; r < 4; ++r) { const int t = tid + 512 * r;
;                     x0[r] = (c2){ZVAL(raw, t), ZVAL(raw + RAWROW, t)}; x1[r] = (c2){ZVAL(raw + 2 * RAWROW, t), ZVAL(raw + 3 * RAWROW, t)}; zk0[r] = x0[r]; zk1[r] = x1[r];
;                     x0[4 + r] = (c2){0.f, 0.f}; x1[4 + r] = (c2){0.f, 0.f}; }
.LBB0_364:
	ds_read_u16 v16, v152 offset:16
	ds_read_u16 v17, v152 offset:18
	ds_read_u16 v18, v152 offset:14
	s_waitcnt lgkmcnt(0)
	v_lshlrev_b32_e32 v19, 16, v16
	v_lshlrev_b32_e32 v17, 16, v17
	v_lshlrev_b32_e32 v16, 16, v18
	v_pk_mul_f32 v[16:17], v[64:65], v[16:17]
	s_nop 0
	v_fma_f32 v16, v186, v19, v16
	v_add_f32_e32 v16, v16, v17
	v_add_f32_e32 v78, v185, v16
	s_and_b64 vcc, exec, s[84:85]
	s_mov_b64 s[72:73], -1
	s_cbranch_vccnz .LBB0_332

; __device__ __forceinline__ float bf2f(bf16_t b) { return __uint_as_float(((unsigned)b) << 16); }
; #define ZVAL(r, t) ((o == 0) ? dwl((r), (t), zw0, zw1, zw2, zb) : bf2f((r)[8 + (t)]))
; __device__ __forceinline__ float dwl(const bf16_t* r, int t, float w0, float w1, float w2, float b) { return w0 * bf2f(r[7 + t]) + w1 * bf2f(r[8 + t]) + w2 * bf2f(r[9 + t]) + b; }
; __device__ __forceinline__ void phase_conv(const Params& p, int o, unsigned char* smem, int wave) {
;     ...
;                 for (int r = 0; r < 4; ++r) { const int t = tid + 512 * r;
;                     x0[r] = (c2){ZVAL(raw, t), ZVAL(raw + RAWROW, t)}; x1[r] = (c2){ZVAL(raw + 2 * RAWROW, t), ZVAL(raw + 3 * RAWROW, t)}; zk0[r] = x0[r]; zk1[r] = x1[r];
;                     x0[4 + r] = (c2){0.f, 0.f}; x1[4 + r] = (c2){0.f, 0.f}; }
.LBB0_366:
	ds_read_u16 v16, v153 offset:16
	ds_read_u16 v17, v153 offset:18
	ds_read_u16 v18, v153 offset:14
	s_waitcnt lgkmcnt(0)
	v_lshlrev_b32_e32 v19, 16, v16
	v_lshlrev_b32_e32 v17, 16, v17
	v_lshlrev_b32_e32 v16, 16, v18
	v_pk_mul_f32 v[16:17], v[64:65], v[16:17]
	s_nop 0
	v_fma_f32 v16, v186, v19, v16
	v_add_f32_e32 v16, v16, v17
	v_add_f32_e32 v79, v185, v16
	s_and_b64 vcc, exec, s[84:85]
	s_mov_b64 s[72:73], -1
	s_cbranch_vccnz .LBB0_334

; __device__ __forceinline__ float bf2f(bf16_t b) { return __uint_as_float(((unsigned)b) << 16); }
; #define ZVAL(r, t) ((o == 0) ? dwl((r), (t), zw0, zw1, zw2, zb) : bf2f((r)[8 + (t)]))
; __device__ __forceinline__ float dwl(const bf16_t* r, int t, float w0, float w1, float w2, float b) { return w0 * bf2f(r[7 + t]) + w1 * bf2f(r[8 + t]) + w2 * bf2f(r[9 + t]) + b; }
; __device__ __forceinline__ void phase_conv(const Params& p, int o, unsigned char* smem, int wave) {
;     ...
;                 for (int r = 0; r < 4; ++r) { const int t = tid + 512 * r;
;                     x0[r] = (c2){ZVAL(raw, t), ZVAL(raw + RAWROW, t)}; x1[r] = (c2){ZVAL(raw + 2 * RAWROW, t), ZVAL(raw + 3 * RAWROW, t)}; zk0[r] = x0[r]; zk1[r] = x1[r];
;                     x0[4 + r] = (c2){0.f, 0.f}; x1[4 + r] = (c2){0.f, 0.f}; }
.LBB0_368:
	ds_read_u16 v16, v154 offset:16
	ds_read_u16 v17, v154 offset:18
	ds_read_u16 v18, v154 offset:14
	s_waitcnt lgkmcnt(0)
	v_lshlrev_b32_e32 v19, 16, v16
	v_lshlrev_b32_e32 v17, 16, v17
	v_lshlrev_b32_e32 v16, 16, v18
	v_pk_mul_f32 v[16:17], v[64:65], v[16:17]
	s_nop 0
	v_fma_f32 v16, v186, v19, v16
	v_add_f32_e32 v16, v16, v17
	v_add_f32_e32 v72, v185, v16
	s_and_b64 vcc, exec, s[84:85]
	s_mov_b64 s[72:73], -1
	s_cbranch_vccnz .LBB0_336

; __device__ __forceinline__ float bf2f(bf16_t b) { return __uint_as_float(((unsigned)b) << 16); }
; #define ZVAL(r, t) ((o == 0) ? dwl((r), (t), zw0, zw1, zw2, zb) : bf2f((r)[8 + (t)]))
; __device__ __forceinline__ float dwl(const bf16_t* r, int t, float w0, float w1, float w2, float b) { return w0 * bf2f(r[7 + t]) + w1 * bf2f(r[8 + t]) + w2 * bf2f(r[9 + t]) + b; }
; __device__ __forceinline__ void phase_conv(const Params& p, int o, unsigned char* smem, int wave) {
;     ...
;                 for (int r = 0; r < 4; ++r) { const int t = tid + 512 * r;
;                     x0[r] = (c2){ZVAL(raw, t), ZVAL(raw + RAWROW, t)}; x1[r] = (c2){ZVAL(raw + 2 * RAWROW, t), ZVAL(raw + 3 * RAWROW, t)}; zk0[r] = x0[r]; zk1[r] = x1[r];
;                     x0[4 + r] = (c2){0.f, 0.f}; x1[4 + r] = (c2){0.f, 0.f}; }
.LBB0_370:
	ds_read_u16 v16, v155 offset:16
	ds_read_u16 v17, v155 offset:18
	ds_read_u16 v18, v155 offset:14
	s_waitcnt lgkmcnt(0)
	v_lshlrev_b32_e32 v19, 16, v16
	v_lshlrev_b32_e32 v17, 16, v17
	v_lshlrev_b32_e32 v16, 16, v18
	v_pk_mul_f32 v[16:17], v[64:65], v[16:17]
	s_nop 0
	v_fma_f32 v16, v186, v19, v16
	v_add_f32_e32 v16, v16, v17
	v_add_f32_e32 v73, v185, v16
	s_and_b64 vcc, exec, s[84:85]
	s_mov_b64 s[72:73], -1
	s_cbranch_vccnz .LBB0_338

; __device__ __forceinline__ float bf2f(bf16_t b) { return __uint_as_float(((unsigned)b) << 16); }
; #define ZVAL(r, t) ((o == 0) ? dwl((r), (t), zw0, zw1, zw2, zb) : bf2f((r)[8 + (t)]))
; __device__ __forceinline__ float dwl(const bf16_t* r, int t, float w0, float w1, float w2, float b) { return w0 * bf2f(r[7 + t]) + w1 * bf2f(r[8 + t]) + w2 * bf2f(r[9 + t]) + b; }
; __device__ __forceinline__ void phase_conv(const Params& p, int o, unsigned char* smem, int wave) {
;     ...
;                 for (int r = 0; r < 4; ++r) { const int t = tid + 512 * r;
;                     x0[r] = (c2){ZVAL(raw, t), ZVAL(raw + RAWROW, t)}; x1[r] = (c2){ZVAL(raw + 2 * RAWROW, t), ZVAL(raw + 3 * RAWROW, t)}; zk0[r] = x0[r]; zk1[r] = x1[r];
;                     x0[4 + r] = (c2){0.f, 0.f}; x1[4 + r] = (c2){0.f, 0.f}; }
.LBB0_372:
	ds_read_u16 v16, v156 offset:16
	ds_read_u16 v17, v156 offset:18
	ds_read_u16 v18, v156 offset:14
	s_waitcnt lgkmcnt(0)
	v_lshlrev_b32_e32 v19, 16, v16
	v_lshlrev_b32_e32 v17, 16, v17
	v_lshlrev_b32_e32 v16, 16, v18
	v_pk_mul_f32 v[16:17], v[64:65], v[16:17]
	s_nop 0
	v_fma_f32 v16, v186, v19, v16
	v_add_f32_e32 v16, v16, v17
	v_add_f32_e32 v80, v185, v16
	s_and_b64 vcc, exec, s[84:85]
	s_mov_b64 s[72:73], -1
	s_cbranch_vccnz .LBB0_340

; __device__ __forceinline__ float bf2f(bf16_t b) { return __uint_as_float(((unsigned)b) << 16); }
; #define ZVAL(r, t) ((o == 0) ? dwl((r), (t), zw0, zw1, zw2, zb) : bf2f((r)[8 + (t)]))
; __device__ __forceinline__ float dwl(const bf16_t* r, int t, float w0, float w1, float w2, float b) { return w0 * bf2f(r[7 + t]) + w1 * bf2f(r[8 + t]) + w2 * bf2f(r[9 + t]) + b; }
; __device__ __forceinline__ void phase_conv(const Params& p, int o, unsigned char* smem, int wave) {
;     ...
;                 for (int r = 0; r < 4; ++r) { const int t = tid + 512 * r;
;                     x0[r] = (c2){ZVAL(raw, t), ZVAL(raw + RAWROW, t)}; x1[r] = (c2){ZVAL(raw + 2 * RAWROW, t), ZVAL(raw + 3 * RAWROW, t)}; zk0[r] = x0[r]; zk1[r] = x1[r];
;                     x0[4 + r] = (c2){0.f, 0.f}; x1[4 + r] = (c2){0.f, 0.f}; }
.LBB0_374:
	ds_read_u16 v16, v157 offset:16
	ds_read_u16 v17, v157 offset:18
	ds_read_u16 v18, v157 offset:14
	s_waitcnt lgkmcnt(0)
	v_lshlrev_b32_e32 v19, 16, v16
	v_lshlrev_b32_e32 v17, 16, v17
	v_lshlrev_b32_e32 v16, 16, v18
	v_pk_mul_f32 v[16:17], v[64:65], v[16:17]
	s_nop 0
	v_fma_f32 v16, v186, v19, v16
	v_add_f32_e32 v16, v16, v17
	v_add_f32_e32 v81, v185, v16
	s_and_b64 vcc, exec, s[84:85]
	s_mov_b64 s[72:73], -1
	s_cbranch_vccnz .LBB0_342

; __device__ __forceinline__ float bf2f(bf16_t b) { return __uint_as_float(((unsigned)b) << 16); }
; #define ZVAL(r, t) ((o == 0) ? dwl((r), (t), zw0, zw1, zw2, zb) : bf2f((r)[8 + (t)]))
; __device__ __forceinline__ float dwl(const bf16_t* r, int t, float w0, float w1, float w2, float b) { return w0 * bf2f(r[7 + t]) + w1 * bf2f(r[8 + t]) + w2 * bf2f(r[9 + t]) + b; }
; __device__ __forceinline__ void phase_conv(const Params& p, int o, unsigned char* smem, int wave) {
;     ...
;                 for (int r = 0; r < 4; ++r) { const int t = tid + 512 * r;
;                     x0[r] = (c2){ZVAL(raw, t), ZVAL(raw + RAWROW, t)}; x1[r] = (c2){ZVAL(raw + 2 * RAWROW, t), ZVAL(raw + 3 * RAWROW, t)}; zk0[r] = x0[r]; zk1[r] = x1[r];
;                     x0[4 + r] = (c2){0.f, 0.f}; x1[4 + r] = (c2){0.f, 0.f}; }
.LBB0_376:
	ds_read_u16 v16, v158 offset:16
	ds_read_u16 v17, v158 offset:18
	ds_read_u16 v18, v158 offset:14
	s_waitcnt lgkmcnt(0)
	v_lshlrev_b32_e32 v19, 16, v16
	v_lshlrev_b32_e32 v17, 16, v17
	v_lshlrev_b32_e32 v16, 16, v18
	v_pk_mul_f32 v[16:17], v[64:65], v[16:17]
	s_nop 0
	v_fma_f32 v16, v186, v19, v16
	v_add_f32_e32 v16, v16, v17
	v_add_f32_e32 v70, v185, v16
	s_and_b64 vcc, exec, s[84:85]
	s_mov_b64 s[72:73], -1
	s_cbranch_vccnz .LBB0_344

; __device__ __forceinline__ float bf2f(bf16_t b) { return __uint_as_float(((unsigned)b) << 16); }
; #define ZVAL(r, t) ((o == 0) ? dwl((r), (t), zw0, zw1, zw2, zb) : bf2f((r)[8 + (t)]))
; __device__ __forceinline__ float dwl(const bf16_t* r, int t, float w0, float w1, float w2, float b) { return w0 * bf2f(r[7 + t]) + w1 * bf2f(r[8 + t]) + w2 * bf2f(r[9 + t]) + b; }
; __device__ __forceinline__ void phase_conv(const Params& p, int o, unsigned char* smem, int wave) {
;     ...
;                 for (int r = 0; r < 4; ++r) { const int t = tid + 512 * r;
;                     x0[r] = (c2){ZVAL(raw, t), ZVAL(raw + RAWROW, t)}; x1[r] = (c2){ZVAL(raw + 2 * RAWROW, t), ZVAL(raw + 3 * RAWROW, t)}; zk0[r] = x0[r]; zk1[r] = x1[r];
;                     x0[4 + r] = (c2){0.f, 0.f}; x1[4 + r] = (c2){0.f, 0.f}; }
.LBB0_378:
	ds_read_u16 v16, v159 offset:16
	ds_read_u16 v17, v159 offset:18
	ds_read_u16 v18, v159 offset:14
	s_waitcnt lgkmcnt(0)
	v_lshlrev_b32_e32 v19, 16, v16
	v_lshlrev_b32_e32 v17, 16, v17
	v_lshlrev_b32_e32 v16, 16, v18
	v_pk_mul_f32 v[16:17], v[64:65], v[16:17]
	s_nop 0
	v_fma_f32 v16, v186, v19, v16
	v_add_f32_e32 v16, v16, v17
	v_add_f32_e32 v71, v185, v16
	s_branch .LBB0_288

; __device__ __forceinline__ c2 mni(c2 a) { return (c2){a.y, -a.x}; }
; __device__ __forceinline__ void dft8(c2 (&x)[8]) {
;     const float s = 0.70710678118654752f;
;     const c2 a0 = x[0] + x[4], a4 = x[0] - x[4], a1 = x[1] + x[5], a5 = x[1] - x[5], a2 = x[2] + x[6], a6 = x[2] - x[6], a3 = x[3] + x[7], a7 = x[3] - x[7];
;     const c2 a5w = (c2){(a5.x + a5.y) * s, (a5.y - a5.x) * s};
;     const c2 a6w = mni(a6);
;     const c2 a7w = (c2){(a7.y - a7.x) * s, -(a7.x + a7.y) * s};
;     const c2 b0 = a0 + a2, b1 = a0 - a2, b2 = a1 + a3, b3 = mni(a1 - a3);
;     x[0] = b0 + b2; x[4] = b0 - b2; x[2] = b1 + b3; x[6] = b1 - b3;
;     const c2 c0 = a4 + a6w, c1 = a4 - a6w, c2_ = a5w + a7w, c3 = mni(a5w - a7w);
;     x[1] = c0 + c2_; x[5] = c0 - c2_; x[3] = c1 + c3; x[7] = c1 - c3;
; }
; __device__ __forceinline__ c2 mpi(c2 a) { return (c2){-a.y, a.x}; }
; __device__ __forceinline__ void idft8(c2 (&x)[8]) {
;     const float s = 0.70710678118654752f;
;     const c2 a0 = x[0] + x[4], a4 = x[0] - x[4], a1 = x[1] + x[5], a5 = x[1] - x[5], a2 = x[2] + x[6], a6 = x[2] - x[6], a3 = x[3] + x[7], a7 = x[3] - x[7];
;     const c2 a5w = (c2){(a5.x - a5.y) * s, (a5.x + a5.y) * s};
;     const c2 a6w = mpi(a6);
;     const c2 a7w = (c2){-(a7.x + a7.y) * s, (a7.x - a7.y) * s};
;     const c2 b0 = a0 + a2, b1 = a0 - a2, b2 = a1 + a3, b3 = mpi(a1 - a3);
;     x[0] = b0 + b2; x[4] = b0 - b2; x[2] = b1 + b3; x[6] = b1 - b3;
;     const c2 c0 = a4 + a6w, c1 = a4 - a6w, c2_ = a5w + a7w, c3 = mpi(a5w - a7w);
;     x[1] = c0 + c2_; x[5] = c0 - c2_; x[3] = c1 + c3; x[7] = c1 - c3;
; }
; __device__ __forceinline__ void fwd_s0(c2 (&x)[8], c2* buf, const c2* tws, int tid) {
;     dft8(x);
; #pragma unroll
;     for (int q = 1; q < 8; ++q) x[q] = cmul(x[q], tws[(q - 1) * 512 + tid]);
;     { c2* bp_ = buf + LP(tid);
; #pragma unroll
;     for (int q = 0; q < 8; ++q) bp_[576 * q] = x[q]; }
; __device__ __forceinline__ void phase_conv(const Params& p, int o, unsigned char* smem, int wave) {
;     ...
;             for (int d = -7; d <= 7; d += 2) {
;                 c2 x0[8], x1[8];
; #pragma unroll
;                 for (int r = 0; r < 8; ++r) { x0[r] = (c2){subfilt(hf, hb, L, d, tid + 512 * r), 0.f}; x1[r] = (c2){d < 7 ? subfilt(hf, hb, L, d + 1, tid + 512 * r) : 0.f, 0.f}; }
;                 __syncthreads();
;                 fft_fwd_regs2(x0, x1, buf0, buf1, tws, tid);
.LBB0_480:
	s_or_b64 exec, exec, s[72:73]
	s_waitcnt vmcnt(0)
	v_pk_add_f32 v[16:17], v[2:3], v[10:11]
	v_sub_f32_e32 v56, v2, v10
	v_sub_f32_e32 v10, v3, v11
	v_pk_add_f32 v[2:3], v[6:7], v[14:15]
	v_sub_f32_e32 v15, v7, v15
	s_barrier
	v_sub_f32_e32 v11, v6, v14
	v_sub_f32_e32 v14, 0, v15
	v_add_f32_e32 v15, 0, v15
	v_pk_add_f32 v[18:19], v[16:17], v[2:3] neg_lo:[0,1] neg_hi:[0,1]
	v_add_f32_e32 v6, 0, v10
	v_sub_f32_e32 v7, 0, v10
	v_pk_mul_f32 v[14:15], v[14:15], s[20:21]
	v_pk_add_f32 v[2:3], v[16:17], v[2:3]
	v_pk_add_f32 v[16:17], v[18:19], 0 neg_lo:[1,1] neg_hi:[1,1]
	v_xor_b32_e32 v11, 0x80000000, v11
	v_mov_b32_e32 v10, v57
	v_mov_b32_e32 v20, v18
	v_mov_b32_e32 v21, v57
	v_mov_b32_e32 v16, v57
	v_pk_fma_f32 v[24:25], v[6:7], s[20:21], v[14:15] op_sel_hi:[1,0,1]
	v_pk_fma_f32 v[6:7], v[6:7], s[20:21], v[14:15] op_sel_hi:[1,0,1] neg_lo:[0,0,1] neg_hi:[0,0,1]
	v_pk_add_f32 v[22:23], v[20:21], v[16:17]
	v_pk_add_f32 v[16:17], v[20:21], v[16:17] neg_lo:[0,1] neg_hi:[0,1]
	v_pk_add_f32 v[20:21], v[56:57], v[10:11]
	v_pk_add_f32 v[10:11], v[56:57], v[10:11] neg_lo:[0,1] neg_hi:[0,1]
	v_xor_b32_e32 v15, 0x80000000, v6
	v_mov_b32_e32 v14, v7
	v_pk_add_f32 v[6:7], v[20:21], v[24:25]
	v_pk_add_f32 v[20:21], v[20:21], v[24:25] neg_lo:[0,1] neg_hi:[0,1]
	v_pk_add_f32 v[24:25], v[10:11], v[14:15]
	v_pk_add_f32 v[10:11], v[10:11], v[14:15] neg_lo:[0,1] neg_hi:[0,1]
	s_waitcnt lgkmcnt(0)
	v_pk_mul_f32 v[32:33], v[6:7], v[210:211] op_sel:[1,1] op_sel_hi:[1,0]
	v_pk_add_f32 v[18:19], v[2:3], v[2:3] op_sel:[0,1] op_sel_hi:[1,0]
	v_fma_f32 v34, v6, v210, -v32
	v_fma_f32 v35, v6, v211, v33
	v_pk_mul_f32 v[6:7], v[22:23], v[212:213] op_sel:[1,1] op_sel_hi:[1,0]
	v_pk_add_f32 v[2:3], v[2:3], v[2:3] op_sel:[0,1] op_sel_hi:[0,1] neg_lo:[0,1] neg_hi:[0,1]
	v_fma_f32 v26, v22, v212, -v6
	v_fma_f32 v27, v22, v213, v7
	v_pk_mul_f32 v[6:7], v[24:25], v[214:215] op_sel:[1,1] op_sel_hi:[1,0]
	v_mov_b32_e32 v19, v57
	v_fma_f32 v14, v24, v214, -v6
	v_fma_f32 v15, v24, v215, v7
	v_pk_mul_f32 v[6:7], v[216:217], 0 op_sel_hi:[1,0]
	v_sub_f32_e32 v56, v0, v8
	v_fma_f32 v22, v2, v216, -v7
	v_fma_f32 v23, v3, v217, v6
	v_pk_mul_f32 v[28:29], v[20:21], v[218:219] op_sel:[1,1] op_sel_hi:[1,0]
	v_mov_b64_e32 v[6:7], v[222:223]
	v_fma_f32 v30, v20, v218, -v28
	v_fma_f32 v31, v20, v219, v29
	v_pk_mul_f32 v[20:21], v[16:17], v[220:221] op_sel:[1,1] op_sel_hi:[1,0]
	v_add_u32_e32 v63, 0x800, v117
	v_fma_f32 v24, v16, v220, -v20
	v_fma_f32 v25, v16, v221, v21
	v_pk_mul_f32 v[2:3], v[10:11], v[6:7] op_sel:[1,1] op_sel_hi:[1,0]
	v_add_u32_e32 v191, 0x9000, v117
	v_fma_f32 v16, v10, v6, -v2
	v_fma_f32 v17, v10, v7, v3
	ds_write2st64_b64 v115, v[18:19], v[34:35] offset1:9
	ds_write2st64_b64 v115, v[26:27], v[14:15] offset0:18 offset1:27
	ds_write2st64_b64 v115, v[22:23], v[30:31] offset0:36 offset1:45
	ds_write2st64_b64 v115, v[24:25], v[16:17] offset0:54 offset1:63
	v_pk_add_f32 v[2:3], v[0:1], v[8:9]
	v_sub_f32_e32 v6, v1, v9
	v_pk_add_f32 v[0:1], v[4:5], v[12:13]
	v_sub_f32_e32 v9, v5, v13
	v_sub_f32_e32 v8, 0, v9
	v_add_f32_e32 v9, 0, v9
	v_pk_add_f32 v[10:11], v[2:3], v[0:1] neg_lo:[0,1] neg_hi:[0,1]
	v_sub_f32_e32 v7, v4, v12
	v_add_f32_e32 v4, 0, v6
	v_sub_f32_e32 v5, 0, v6
	v_pk_mul_f32 v[8:9], v[8:9], s[20:21]
	v_pk_add_f32 v[0:1], v[2:3], v[0:1]
	v_pk_add_f32 v[2:3], v[10:11], 0 neg_lo:[1,1] neg_hi:[1,1]
	v_xor_b32_e32 v7, 0x80000000, v7
	v_mov_b32_e32 v6, v57
	v_mov_b32_e32 v12, v10
	v_mov_b32_e32 v13, v57
	v_mov_b32_e32 v2, v57
	v_pk_fma_f32 v[16:17], v[4:5], s[20:21], v[8:9] op_sel_hi:[1,0,1]
	v_pk_fma_f32 v[4:5], v[4:5], s[20:21], v[8:9] op_sel_hi:[1,0,1] neg_lo:[0,0,1] neg_hi:[0,0,1]
	v_pk_add_f32 v[14:15], v[12:13], v[2:3]
	v_pk_add_f32 v[2:3], v[12:13], v[2:3] neg_lo:[0,1] neg_hi:[0,1]
	v_pk_add_f32 v[12:13], v[56:57], v[6:7]
	v_pk_add_f32 v[6:7], v[56:57], v[6:7] neg_lo:[0,1] neg_hi:[0,1]
	v_xor_b32_e32 v9, 0x80000000, v4
	v_mov_b32_e32 v8, v5
	v_pk_add_f32 v[4:5], v[12:13], v[16:17]
	v_pk_add_f32 v[12:13], v[12:13], v[16:17] neg_lo:[0,1] neg_hi:[0,1]
	v_pk_add_f32 v[16:17], v[6:7], v[8:9]
	v_pk_add_f32 v[6:7], v[6:7], v[8:9] neg_lo:[0,1] neg_hi:[0,1]
	s_waitcnt lgkmcnt(0)
	v_pk_mul_f32 v[24:25], v[4:5], v[210:211] op_sel:[1,1] op_sel_hi:[1,0]
	v_pk_add_f32 v[10:11], v[0:1], v[0:1] op_sel:[0,1] op_sel_hi:[1,0]
	v_fma_f32 v26, v4, v210, -v24
	v_fma_f32 v27, v4, v211, v25
	v_pk_mul_f32 v[4:5], v[14:15], v[212:213] op_sel:[1,1] op_sel_hi:[1,0]
	v_pk_add_f32 v[0:1], v[0:1], v[0:1] op_sel:[0,1] op_sel_hi:[0,1] neg_lo:[0,1] neg_hi:[0,1]
	v_fma_f32 v18, v14, v212, -v4
	v_fma_f32 v19, v14, v213, v5
	v_pk_mul_f32 v[4:5], v[16:17], v[214:215] op_sel:[1,1] op_sel_hi:[1,0]
	v_mov_b32_e32 v11, v57
	v_fma_f32 v8, v16, v214, -v4
	v_fma_f32 v9, v16, v215, v5
	v_pk_mul_f32 v[4:5], v[216:217], 0 op_sel_hi:[1,0]
	v_add_u32_e32 v192, 0x9800, v117
	v_fma_f32 v14, v0, v216, -v5
	v_fma_f32 v15, v1, v217, v4
	v_pk_mul_f32 v[20:21], v[12:13], v[218:219] op_sel:[1,1] op_sel_hi:[1,0]
	v_mov_b64_e32 v[4:5], v[222:223]
	v_fma_f32 v22, v12, v218, -v20
	v_fma_f32 v23, v12, v219, v21
	v_pk_mul_f32 v[12:13], v[2:3], v[220:221] op_sel:[1,1] op_sel_hi:[1,0]
	v_add_u32_e32 v193, 0x9000, v119
	v_fma_f32 v16, v2, v220, -v12
	v_fma_f32 v17, v2, v221, v13
	v_pk_mul_f32 v[0:1], v[6:7], v[4:5] op_sel:[1,1] op_sel_hi:[1,0]
	v_add_u32_e32 v194, 0x9000, v121
	v_fma_f32 v2, v6, v4, -v0
	v_fma_f32 v3, v6, v5, v1
	ds_write2st64_b64 v115, v[10:11], v[26:27] offset0:72 offset1:81
	ds_write2st64_b64 v115, v[18:19], v[8:9] offset0:90 offset1:99
	ds_write2st64_b64 v115, v[14:15], v[22:23] offset0:108 offset1:117
	ds_write_b64 v115, v[16:17] offset:64512
	ds_write_b64 v116, v[2:3] offset:32256
	s_waitcnt lgkmcnt(0)
	s_barrier
; __device__ __forceinline__ c2 cmul(c2 a, c2 b) { return (c2){a.x * b.x - a.y * b.y, a.x * b.y + a.y * b.x}; }
; __device__ __forceinline__ c2 mni(c2 a) { return (c2){a.y, -a.x}; }
; __device__ __forceinline__ void dft8(c2 (&x)[8]) {
;     const float s = 0.70710678118654752f;
;     const c2 a0 = x[0] + x[4], a4 = x[0] - x[4], a1 = x[1] + x[5], a5 = x[1] - x[5], a2 = x[2] + x[6], a6 = x[2] - x[6], a3 = x[3] + x[7], a7 = x[3] - x[7];
;     const c2 a5w = (c2){(a5.x + a5.y) * s, (a5.y - a5.x) * s};
;     const c2 a6w = mni(a6);
;     const c2 a7w = (c2){(a7.y - a7.x) * s, -(a7.x + a7.y) * s};
;     const c2 b0 = a0 + a2, b1 = a0 - a2, b2 = a1 + a3, b3 = mni(a1 - a3);
;     x[0] = b0 + b2; x[4] = b0 - b2; x[2] = b1 + b3; x[6] = b1 - b3;
;     const c2 c0 = a4 + a6w, c1 = a4 - a6w, c2_ = a5w + a7w, c3 = mni(a5w - a7w);
;     x[1] = c0 + c2_; x[5] = c0 - c2_; x[3] = c1 + c3; x[7] = c1 - c3;
; }
; template <int S> __device__ __forceinline__ void fwd_mid(c2* buf, const c2* tws, int tid) {
;     constexpr int lq = 9 - 3 * S, Q = 1 << lq; const c2* T = tws + (S == 1 ? 3584 : 4032);
;     const int k = tid & (Q - 1), base = ((tid >> lq) << (lq + 3)) + k;
;     c2 x[8];
;     c2* bp_ = buf + LP(base); constexpr int QP = Q + Q / 8;
; #pragma unroll
;     for (int r = 0; r < 8; ++r) x[r] = bp_[r * QP];
;     dft8(x);
; #pragma unroll
;     for (int q = 1; q < 8; ++q) x[q] = cmul(x[q], T[(q - 1) * Q + k]);
; #pragma unroll
;     for (int q = 0; q < 8; ++q) bp_[q * QP] = x[q];
; }
	ds_read2_b64 v[0:3], v117 offset1:72
	ds_read2_b64 v[4:7], v63 offset0:32 offset1:104
	ds_read2_b64 v[8:11], v117 offset0:144 offset1:216
	ds_read2_b64 v[12:15], v63 offset0:176 offset1:248
	v_mov_b64_e32 v[18:19], v[224:225]
	v_add_u32_e32 v195, 0x9020, v121
	v_add_u32_e32 v196, 0x9010, v121
	s_waitcnt lgkmcnt(0)
	v_pk_add_f32 v[16:17], v[0:1], v[4:5]
	v_pk_add_f32 v[0:1], v[0:1], v[4:5] neg_lo:[0,1] neg_hi:[0,1]
	v_pk_add_f32 v[4:5], v[2:3], v[6:7]
	v_pk_add_f32 v[2:3], v[2:3], v[6:7] neg_lo:[0,1] neg_hi:[0,1]
	v_pk_add_f32 v[6:7], v[8:9], v[12:13]
	v_pk_add_f32 v[8:9], v[8:9], v[12:13] neg_lo:[0,1] neg_hi:[0,1]
	v_pk_add_f32 v[12:13], v[10:11], v[14:15]
	v_pk_add_f32 v[10:11], v[10:11], v[14:15] neg_lo:[0,1] neg_hi:[0,1]
	v_pk_add_f32 v[14:15], v[2:3], v[2:3] op_sel:[1,0]
	v_pk_add_f32 v[2:3], v[2:3], v[2:3] op_sel_hi:[1,0] neg_lo:[0,1] neg_hi:[0,1]
	v_add_u32_e32 v197, 0x9030, v121
	v_mov_b32_e32 v15, v3
	v_xor_b32_e32 v3, 0x80000000, v8
	v_mov_b32_e32 v2, v9
	v_pk_add_f32 v[8:9], v[10:11], v[10:11] op_sel:[1,0] neg_lo:[0,1] neg_hi:[0,1]
	v_pk_add_f32 v[10:11], v[10:11], v[10:11] op_sel_hi:[1,0]
	s_andn2_b64 vcc, exec, s[70:71]
	v_mov_b32_e32 v9, v11
	v_pk_add_f32 v[10:11], v[16:17], v[6:7]
	v_pk_add_f32 v[6:7], v[16:17], v[6:7] neg_lo:[0,1] neg_hi:[0,1]
	v_pk_add_f32 v[16:17], v[4:5], v[12:13]
	v_pk_add_f32 v[4:5], v[4:5], v[12:13] neg_lo:[0,1] neg_hi:[0,1]
	v_pk_mul_f32 v[8:9], v[8:9], s[20:21]
	v_xor_b32_e32 v13, 0x80000000, v4
	v_mov_b32_e32 v12, v5
	v_pk_add_f32 v[4:5], v[10:11], v[16:17]
	v_pk_add_f32 v[10:11], v[10:11], v[16:17] neg_lo:[0,1] neg_hi:[0,1]
	v_pk_add_f32 v[16:17], v[6:7], v[12:13]
	v_pk_add_f32 v[6:7], v[6:7], v[12:13] neg_lo:[0,1] neg_hi:[0,1]
	v_pk_add_f32 v[12:13], v[0:1], v[2:3]
	v_pk_add_f32 v[0:1], v[0:1], v[2:3] neg_lo:[0,1] neg_hi:[0,1]
	v_pk_fma_f32 v[2:3], v[14:15], s[20:21], v[8:9] op_sel_hi:[1,0,1]
	v_pk_fma_f32 v[8:9], v[14:15], s[20:21], v[8:9] op_sel_hi:[1,0,1] neg_lo:[0,0,1] neg_hi:[0,0,1]
	s_nop 0
	v_xor_b32_e32 v15, 0x80000000, v8
	v_mov_b32_e32 v14, v9
	v_pk_add_f32 v[8:9], v[12:13], v[2:3]
	v_pk_add_f32 v[2:3], v[12:13], v[2:3] neg_lo:[0,1] neg_hi:[0,1]
	v_pk_add_f32 v[12:13], v[0:1], v[14:15]
	v_pk_add_f32 v[0:1], v[0:1], v[14:15] neg_lo:[0,1] neg_hi:[0,1]
	v_pk_mul_f32 v[24:25], v[18:19], v[8:9] op_sel:[1,1] op_sel_hi:[0,1]
	v_fma_f32 v26, v18, v8, -v24
	v_fma_f32 v27, v19, v8, v25
	s_nop 0
	v_pk_mul_f32 v[8:9], v[226:227], v[16:17] op_sel:[1,1] op_sel_hi:[0,1]
	v_fma_f32 v18, v226, v16, -v8
	v_fma_f32 v19, v227, v16, v9
	v_pk_mul_f32 v[8:9], v[228:229], v[12:13] op_sel:[1,1] op_sel_hi:[0,1]
	v_fma_f32 v14, v228, v12, -v8
	v_fma_f32 v15, v229, v12, v9
	v_pk_mul_f32 v[20:21], v[232:233], v[2:3] op_sel:[1,1] op_sel_hi:[0,1]
	v_pk_mul_f32 v[8:9], v[10:11], v[230:231] op_sel:[1,1] op_sel_hi:[1,0]
	s_nop 0
	v_fma_f32 v12, v10, v230, -v8
	v_fma_f32 v13, v10, v231, v9
	v_mov_b64_e32 v[10:11], v[236:237]
	v_fma_f32 v22, v232, v2, -v20
	v_fma_f32 v23, v233, v2, v21
	ds_write2_b64 v117, v[4:5], v[26:27] offset1:72
	ds_write2_b64 v117, v[18:19], v[14:15] offset0:144 offset1:216
	s_waitcnt lgkmcnt(0)
	v_pk_mul_f32 v[2:3], v[6:7], v[234:235] op_sel:[1,1] op_sel_hi:[1,0]
	s_nop 0
	v_fma_f32 v16, v6, v234, -v2
	v_fma_f32 v17, v6, v235, v3
	v_pk_mul_f32 v[2:3], v[10:11], v[0:1] op_sel:[1,1] op_sel_hi:[0,1]
	v_fma_f32 v8, v10, v0, -v2
	v_fma_f32 v9, v11, v0, v3
	ds_read2_b64 v[4:7], v192 offset0:32 offset1:104
	ds_read2_b64 v[0:3], v191 offset1:72
	ds_write2_b64 v63, v[12:13], v[22:23] offset0:32 offset1:104
	ds_write2_b64 v63, v[16:17], v[8:9] offset0:176 offset1:248
	ds_read2_b64 v[8:11], v191 offset0:144 offset1:216
	ds_read2_b64 v[12:15], v192 offset0:176 offset1:248
	v_mov_b64_e32 v[18:19], v[224:225]
	s_waitcnt lgkmcnt(0)
	v_pk_add_f32 v[16:17], v[0:1], v[4:5]
	v_pk_add_f32 v[0:1], v[0:1], v[4:5] neg_lo:[0,1] neg_hi:[0,1]
	v_pk_add_f32 v[4:5], v[2:3], v[6:7]
	v_pk_add_f32 v[2:3], v[2:3], v[6:7] neg_lo:[0,1] neg_hi:[0,1]
	v_pk_add_f32 v[6:7], v[8:9], v[12:13]
	v_pk_add_f32 v[8:9], v[8:9], v[12:13] neg_lo:[0,1] neg_hi:[0,1]
	v_pk_add_f32 v[12:13], v[10:11], v[14:15]
	v_pk_add_f32 v[10:11], v[10:11], v[14:15] neg_lo:[0,1] neg_hi:[0,1]
	v_pk_add_f32 v[14:15], v[2:3], v[2:3] op_sel:[1,0]
	v_pk_add_f32 v[2:3], v[2:3], v[2:3] op_sel_hi:[1,0] neg_lo:[0,1] neg_hi:[0,1]
	s_nop 0
	v_mov_b32_e32 v15, v3
	v_xor_b32_e32 v3, 0x80000000, v8
	v_mov_b32_e32 v2, v9
	v_pk_add_f32 v[8:9], v[10:11], v[10:11] op_sel:[1,0] neg_lo:[0,1] neg_hi:[0,1]
	v_pk_add_f32 v[10:11], v[10:11], v[10:11] op_sel_hi:[1,0]
	s_nop 0
	v_mov_b32_e32 v9, v11
	v_pk_add_f32 v[10:11], v[16:17], v[6:7]
	v_pk_add_f32 v[6:7], v[16:17], v[6:7] neg_lo:[0,1] neg_hi:[0,1]
	v_pk_add_f32 v[16:17], v[4:5], v[12:13]
	v_pk_add_f32 v[4:5], v[4:5], v[12:13] neg_lo:[0,1] neg_hi:[0,1]
	v_pk_mul_f32 v[8:9], v[8:9], s[20:21]
	v_xor_b32_e32 v13, 0x80000000, v4
	v_mov_b32_e32 v12, v5
	v_pk_add_f32 v[4:5], v[10:11], v[16:17]
	v_pk_add_f32 v[10:11], v[10:11], v[16:17] neg_lo:[0,1] neg_hi:[0,1]
	v_pk_add_f32 v[16:17], v[6:7], v[12:13]
	v_pk_add_f32 v[6:7], v[6:7], v[12:13] neg_lo:[0,1] neg_hi:[0,1]
	v_pk_add_f32 v[12:13], v[0:1], v[2:3]
	v_pk_add_f32 v[0:1], v[0:1], v[2:3] neg_lo:[0,1] neg_hi:[0,1]
	v_pk_fma_f32 v[2:3], v[14:15], s[20:21], v[8:9] op_sel_hi:[1,0,1]
	v_pk_fma_f32 v[8:9], v[14:15], s[20:21], v[8:9] op_sel_hi:[1,0,1] neg_lo:[0,0,1] neg_hi:[0,0,1]
	s_nop 0
	v_xor_b32_e32 v15, 0x80000000, v8
	v_mov_b32_e32 v14, v9
	v_pk_add_f32 v[8:9], v[12:13], v[2:3]
	v_pk_add_f32 v[2:3], v[12:13], v[2:3] neg_lo:[0,1] neg_hi:[0,1]
	v_pk_add_f32 v[12:13], v[0:1], v[14:15]
	v_pk_add_f32 v[0:1], v[0:1], v[14:15] neg_lo:[0,1] neg_hi:[0,1]
	v_pk_mul_f32 v[24:25], v[18:19], v[8:9] op_sel:[1,1] op_sel_hi:[0,1]
	v_fma_f32 v26, v18, v8, -v24
	v_fma_f32 v27, v19, v8, v25
	s_nop 0
	v_pk_mul_f32 v[8:9], v[226:227], v[16:17] op_sel:[1,1] op_sel_hi:[0,1]
	v_fma_f32 v18, v226, v16, -v8
	v_fma_f32 v19, v227, v16, v9
	v_pk_mul_f32 v[8:9], v[228:229], v[12:13] op_sel:[1,1] op_sel_hi:[0,1]
	v_fma_f32 v14, v228, v12, -v8
	v_fma_f32 v15, v229, v12, v9
	v_pk_mul_f32 v[20:21], v[232:233], v[2:3] op_sel:[1,1] op_sel_hi:[0,1]
	v_pk_mul_f32 v[8:9], v[10:11], v[230:231] op_sel:[1,1] op_sel_hi:[1,0]
	s_nop 0
	v_fma_f32 v12, v10, v230, -v8
	v_fma_f32 v13, v10, v231, v9
	v_mov_b64_e32 v[8:9], v[234:235]
	v_mov_b64_e32 v[10:11], v[236:237]
	v_fma_f32 v22, v232, v2, -v20
	v_fma_f32 v23, v233, v2, v21
	s_nop 0
	v_pk_mul_f32 v[2:3], v[6:7], v[8:9] op_sel:[1,1] op_sel_hi:[1,0]
	s_nop 0
	v_fma_f32 v16, v6, v8, -v2
	v_fma_f32 v17, v6, v9, v3
	v_pk_mul_f32 v[2:3], v[10:11], v[0:1] op_sel:[1,1] op_sel_hi:[0,1]
	v_fma_f32 v6, v10, v0, -v2
	v_fma_f32 v7, v11, v0, v3
	s_nop 0
	ds_write2_b64 v191, v[4:5], v[26:27] offset1:72
	ds_write2_b64 v191, v[18:19], v[14:15] offset0:144 offset1:216
	ds_write2_b64 v192, v[12:13], v[22:23] offset0:32 offset1:104
	ds_write2_b64 v192, v[16:17], v[6:7] offset0:176 offset1:248
	s_waitcnt lgkmcnt(0)
	s_barrier
; __device__ __forceinline__ c2 cmul(c2 a, c2 b) { return (c2){a.x * b.x - a.y * b.y, a.x * b.y + a.y * b.x}; }
; __device__ __forceinline__ c2 mni(c2 a) { return (c2){a.y, -a.x}; }
; __device__ __forceinline__ void dft8(c2 (&x)[8]) {
;     const float s = 0.70710678118654752f;
;     const c2 a0 = x[0] + x[4], a4 = x[0] - x[4], a1 = x[1] + x[5], a5 = x[1] - x[5], a2 = x[2] + x[6], a6 = x[2] - x[6], a3 = x[3] + x[7], a7 = x[3] - x[7];
;     const c2 a5w = (c2){(a5.x + a5.y) * s, (a5.y - a5.x) * s};
;     const c2 a6w = mni(a6);
;     const c2 a7w = (c2){(a7.y - a7.x) * s, -(a7.x + a7.y) * s};
;     const c2 b0 = a0 + a2, b1 = a0 - a2, b2 = a1 + a3, b3 = mni(a1 - a3);
;     x[0] = b0 + b2; x[4] = b0 - b2; x[2] = b1 + b3; x[6] = b1 - b3;
;     const c2 c0 = a4 + a6w, c1 = a4 - a6w, c2_ = a5w + a7w, c3 = mni(a5w - a7w);
;     x[1] = c0 + c2_; x[5] = c0 - c2_; x[3] = c1 + c3; x[7] = c1 - c3;
; }
; template <int S> __device__ __forceinline__ void fwd_mid(c2* buf, const c2* tws, int tid) {
;     constexpr int lq = 9 - 3 * S, Q = 1 << lq; const c2* T = tws + (S == 1 ? 3584 : 4032);
;     const int k = tid & (Q - 1), base = ((tid >> lq) << (lq + 3)) + k;
;     c2 x[8];
;     c2* bp_ = buf + LP(base); constexpr int QP = Q + Q / 8;
; #pragma unroll
;     for (int r = 0; r < 8; ++r) x[r] = bp_[r * QP];
;     dft8(x);
; #pragma unroll
;     for (int q = 1; q < 8; ++q) x[q] = cmul(x[q], T[(q - 1) * Q + k]);
; #pragma unroll
;     for (int q = 0; q < 8; ++q) bp_[q * QP] = x[q];
; }
	ds_read2_b64 v[0:3], v119 offset1:9
	ds_read2_b64 v[4:7], v119 offset0:36 offset1:45
	ds_read2_b64 v[8:11], v119 offset0:18 offset1:27
	ds_read2_b64 v[12:15], v119 offset0:54 offset1:63
	v_mov_b64_e32 v[18:19], v[238:239]
	s_waitcnt lgkmcnt(0)
	v_pk_add_f32 v[16:17], v[0:1], v[4:5]
	v_pk_add_f32 v[0:1], v[0:1], v[4:5] neg_lo:[0,1] neg_hi:[0,1]
	v_pk_add_f32 v[4:5], v[2:3], v[6:7]
	v_pk_add_f32 v[2:3], v[2:3], v[6:7] neg_lo:[0,1] neg_hi:[0,1]
	v_pk_add_f32 v[6:7], v[8:9], v[12:13]
	v_pk_add_f32 v[8:9], v[8:9], v[12:13] neg_lo:[0,1] neg_hi:[0,1]
	v_pk_add_f32 v[12:13], v[10:11], v[14:15]
	v_pk_add_f32 v[10:11], v[10:11], v[14:15] neg_lo:[0,1] neg_hi:[0,1]
	v_pk_add_f32 v[14:15], v[2:3], v[2:3] op_sel:[1,0]
	v_pk_add_f32 v[2:3], v[2:3], v[2:3] op_sel_hi:[1,0] neg_lo:[0,1] neg_hi:[0,1]
	s_nop 0
	v_mov_b32_e32 v15, v3
	v_xor_b32_e32 v3, 0x80000000, v8
	v_mov_b32_e32 v2, v9
	v_pk_add_f32 v[8:9], v[10:11], v[10:11] op_sel:[1,0] neg_lo:[0,1] neg_hi:[0,1]
	v_pk_add_f32 v[10:11], v[10:11], v[10:11] op_sel_hi:[1,0]
	s_nop 0
	v_mov_b32_e32 v9, v11
	v_pk_add_f32 v[10:11], v[16:17], v[6:7]
	v_pk_add_f32 v[6:7], v[16:17], v[6:7] neg_lo:[0,1] neg_hi:[0,1]
	v_pk_add_f32 v[16:17], v[4:5], v[12:13]
	v_pk_add_f32 v[4:5], v[4:5], v[12:13] neg_lo:[0,1] neg_hi:[0,1]
	v_pk_mul_f32 v[8:9], v[8:9], s[20:21]
	v_xor_b32_e32 v13, 0x80000000, v4
	v_mov_b32_e32 v12, v5
	v_pk_add_f32 v[4:5], v[10:11], v[16:17]
	v_pk_add_f32 v[10:11], v[10:11], v[16:17] neg_lo:[0,1] neg_hi:[0,1]
	v_pk_add_f32 v[16:17], v[6:7], v[12:13]
	v_pk_add_f32 v[6:7], v[6:7], v[12:13] neg_lo:[0,1] neg_hi:[0,1]
	v_pk_add_f32 v[12:13], v[0:1], v[2:3]
	v_pk_add_f32 v[0:1], v[0:1], v[2:3] neg_lo:[0,1] neg_hi:[0,1]
	v_pk_fma_f32 v[2:3], v[14:15], s[20:21], v[8:9] op_sel_hi:[1,0,1]
	v_pk_fma_f32 v[8:9], v[14:15], s[20:21], v[8:9] op_sel_hi:[1,0,1] neg_lo:[0,0,1] neg_hi:[0,0,1]
	s_nop 0
	v_xor_b32_e32 v15, 0x80000000, v8
	v_mov_b32_e32 v14, v9
	v_pk_add_f32 v[8:9], v[12:13], v[2:3]
	v_pk_add_f32 v[2:3], v[12:13], v[2:3] neg_lo:[0,1] neg_hi:[0,1]
	v_pk_add_f32 v[12:13], v[0:1], v[14:15]
	v_pk_add_f32 v[0:1], v[0:1], v[14:15] neg_lo:[0,1] neg_hi:[0,1]
	v_pk_mul_f32 v[24:25], v[18:19], v[8:9] op_sel:[1,1] op_sel_hi:[0,1]
	v_fma_f32 v26, v18, v8, -v24
	v_fma_f32 v27, v19, v8, v25
	s_nop 0
	v_pk_mul_f32 v[8:9], v[240:241], v[16:17] op_sel:[1,1] op_sel_hi:[0,1]
	v_fma_f32 v18, v240, v16, -v8
	v_fma_f32 v19, v241, v16, v9
	v_pk_mul_f32 v[8:9], v[242:243], v[12:13] op_sel:[1,1] op_sel_hi:[0,1]
	v_fma_f32 v14, v242, v12, -v8
	v_fma_f32 v15, v243, v12, v9
	v_pk_mul_f32 v[20:21], v[246:247], v[2:3] op_sel:[1,1] op_sel_hi:[0,1]
	v_pk_mul_f32 v[8:9], v[10:11], v[244:245] op_sel:[1,1] op_sel_hi:[1,0]
	s_nop 0
	v_fma_f32 v12, v10, v244, -v8
	v_fma_f32 v13, v10, v245, v9
	v_mov_b64_e32 v[10:11], v[250:251]
	v_fma_f32 v22, v246, v2, -v20
	v_fma_f32 v23, v247, v2, v21
	ds_write2_b64 v119, v[4:5], v[26:27] offset1:9
	ds_write2_b64 v119, v[18:19], v[14:15] offset0:18 offset1:27
	s_waitcnt lgkmcnt(0)
	v_pk_mul_f32 v[2:3], v[6:7], v[248:249] op_sel:[1,1] op_sel_hi:[1,0]
	s_nop 0
	v_fma_f32 v16, v6, v248, -v2
	v_fma_f32 v17, v6, v249, v3
	v_pk_mul_f32 v[2:3], v[10:11], v[0:1] op_sel:[1,1] op_sel_hi:[0,1]
	v_fma_f32 v8, v10, v0, -v2
	v_fma_f32 v9, v11, v0, v3
	s_nop 0
	ds_read2_b64 v[0:3], v193 offset1:9
	ds_read2_b64 v[4:7], v193 offset0:36 offset1:45
	ds_write2_b64 v119, v[12:13], v[22:23] offset0:36 offset1:45
	ds_write2_b64 v119, v[16:17], v[8:9] offset0:54 offset1:63
	ds_read2_b64 v[8:11], v193 offset0:18 offset1:27
	ds_read2_b64 v[12:15], v193 offset0:54 offset1:63
	v_mov_b64_e32 v[18:19], v[238:239]
	s_waitcnt lgkmcnt(0)
	v_pk_add_f32 v[16:17], v[0:1], v[4:5]
	v_pk_add_f32 v[0:1], v[0:1], v[4:5] neg_lo:[0,1] neg_hi:[0,1]
	v_pk_add_f32 v[4:5], v[2:3], v[6:7]
	v_pk_add_f32 v[2:3], v[2:3], v[6:7] neg_lo:[0,1] neg_hi:[0,1]
	v_pk_add_f32 v[6:7], v[8:9], v[12:13]
	v_pk_add_f32 v[8:9], v[8:9], v[12:13] neg_lo:[0,1] neg_hi:[0,1]
	v_pk_add_f32 v[12:13], v[10:11], v[14:15]
	v_pk_add_f32 v[10:11], v[10:11], v[14:15] neg_lo:[0,1] neg_hi:[0,1]
	v_pk_add_f32 v[14:15], v[2:3], v[2:3] op_sel:[1,0]
	v_pk_add_f32 v[2:3], v[2:3], v[2:3] op_sel_hi:[1,0] neg_lo:[0,1] neg_hi:[0,1]
	s_nop 0
	v_mov_b32_e32 v15, v3
	v_xor_b32_e32 v3, 0x80000000, v8
	v_mov_b32_e32 v2, v9
	v_pk_add_f32 v[8:9], v[10:11], v[10:11] op_sel:[1,0] neg_lo:[0,1] neg_hi:[0,1]
	v_pk_add_f32 v[10:11], v[10:11], v[10:11] op_sel_hi:[1,0]
	s_nop 0
	v_mov_b32_e32 v9, v11
	v_pk_add_f32 v[10:11], v[16:17], v[6:7]
	v_pk_add_f32 v[6:7], v[16:17], v[6:7] neg_lo:[0,1] neg_hi:[0,1]
	v_pk_add_f32 v[16:17], v[4:5], v[12:13]
	v_pk_add_f32 v[4:5], v[4:5], v[12:13] neg_lo:[0,1] neg_hi:[0,1]
	v_pk_mul_f32 v[8:9], v[8:9], s[20:21]
	v_xor_b32_e32 v13, 0x80000000, v4
	v_mov_b32_e32 v12, v5
	v_pk_add_f32 v[4:5], v[10:11], v[16:17]
	v_pk_add_f32 v[10:11], v[10:11], v[16:17] neg_lo:[0,1] neg_hi:[0,1]
	v_pk_add_f32 v[16:17], v[6:7], v[12:13]
	v_pk_add_f32 v[6:7], v[6:7], v[12:13] neg_lo:[0,1] neg_hi:[0,1]
	v_pk_add_f32 v[12:13], v[0:1], v[2:3]
	v_pk_add_f32 v[0:1], v[0:1], v[2:3] neg_lo:[0,1] neg_hi:[0,1]
	v_pk_fma_f32 v[2:3], v[14:15], s[20:21], v[8:9] op_sel_hi:[1,0,1]
	v_pk_fma_f32 v[8:9], v[14:15], s[20:21], v[8:9] op_sel_hi:[1,0,1] neg_lo:[0,0,1] neg_hi:[0,0,1]
	s_nop 0
	v_xor_b32_e32 v15, 0x80000000, v8
	v_mov_b32_e32 v14, v9
	v_pk_add_f32 v[8:9], v[12:13], v[2:3]
	v_pk_add_f32 v[2:3], v[12:13], v[2:3] neg_lo:[0,1] neg_hi:[0,1]
	v_pk_add_f32 v[12:13], v[0:1], v[14:15]
	v_pk_add_f32 v[0:1], v[0:1], v[14:15] neg_lo:[0,1] neg_hi:[0,1]
	v_pk_mul_f32 v[24:25], v[18:19], v[8:9] op_sel:[1,1] op_sel_hi:[0,1]
	v_fma_f32 v26, v18, v8, -v24
	v_fma_f32 v27, v19, v8, v25
	s_nop 0
	v_pk_mul_f32 v[8:9], v[240:241], v[16:17] op_sel:[1,1] op_sel_hi:[0,1]
	v_fma_f32 v18, v240, v16, -v8
	v_fma_f32 v19, v241, v16, v9
	v_pk_mul_f32 v[8:9], v[242:243], v[12:13] op_sel:[1,1] op_sel_hi:[0,1]
	v_fma_f32 v14, v242, v12, -v8
	v_fma_f32 v15, v243, v12, v9
	v_pk_mul_f32 v[20:21], v[246:247], v[2:3] op_sel:[1,1] op_sel_hi:[0,1]
	v_pk_mul_f32 v[8:9], v[10:11], v[244:245] op_sel:[1,1] op_sel_hi:[1,0]
	s_nop 0
	v_fma_f32 v12, v10, v244, -v8
	v_fma_f32 v13, v10, v245, v9
	v_mov_b64_e32 v[8:9], v[248:249]
	v_mov_b64_e32 v[10:11], v[250:251]
	v_fma_f32 v22, v246, v2, -v20
	v_fma_f32 v23, v247, v2, v21
	s_nop 0
	v_pk_mul_f32 v[2:3], v[6:7], v[8:9] op_sel:[1,1] op_sel_hi:[1,0]
	s_nop 0
	v_fma_f32 v16, v6, v8, -v2
	v_fma_f32 v17, v6, v9, v3
	v_pk_mul_f32 v[2:3], v[10:11], v[0:1] op_sel:[1,1] op_sel_hi:[0,1]
	v_fma_f32 v6, v10, v0, -v2
	v_fma_f32 v7, v11, v0, v3
	s_nop 0
	ds_write2_b64 v193, v[4:5], v[26:27] offset1:9
	ds_write2_b64 v193, v[18:19], v[14:15] offset0:18 offset1:27
	ds_write2_b64 v193, v[12:13], v[22:23] offset0:36 offset1:45
	ds_write2_b64 v193, v[16:17], v[6:7] offset0:54 offset1:63
	s_waitcnt lgkmcnt(0)
	s_barrier
; __device__ __forceinline__ void fwd_s3(c2 (&x)[8], const c2* buf, int tid) {
; #pragma unroll
;     for (int r = 0; r < 8; ++r) x[r] = buf[9 * tid + r];
;     dft8(x);
; }
; __device__ __forceinline__ void phase_conv(const Params& p, int o, unsigned char* smem, int wave) {
;     ...
;                 for (int r = 0; r < 8; ++r) { x0[r] = (c2){subfilt(hf, hb, L, d, tid + 512 * r), 0.f}; x1[r] = (c2){d < 7 ? subfilt(hf, hb, L, d + 1, tid + 512 * r) : 0.f, 0.f}; }
;                 __syncthreads();
;                 fft_fwd_regs2(x0, x1, buf0, buf1, tws, tid);
; #pragma unroll
;                 for (int q = 0; q < 8; ++q) { sK[((d + 7) * 8 + q) * 512 + tid] = x0[q]; if (d < 7) sK[((d + 8) * 8 + q) * 512 + tid] = x1[q]; }
;             }
	ds_read2_b64 v[0:3], v121 offset0:4 offset1:5
	ds_read2_b64 v[4:7], v121 offset1:1
	ds_read2_b64 v[8:11], v121 offset0:2 offset1:3
	ds_read2_b64 v[12:15], v121 offset0:6 offset1:7
	ds_read2_b64 v[26:29], v195 offset1:1
	ds_read2_b64 v[30:33], v196 offset1:1
	ds_read2_b64 v[38:41], v197 offset1:1
	s_waitcnt lgkmcnt(0)
	v_pk_add_f32 v[16:17], v[4:5], v[0:1]
	v_pk_add_f32 v[0:1], v[4:5], v[0:1] neg_lo:[0,1] neg_hi:[0,1]
	v_pk_add_f32 v[4:5], v[6:7], v[2:3]
	v_pk_add_f32 v[2:3], v[6:7], v[2:3] neg_lo:[0,1] neg_hi:[0,1]
	v_pk_add_f32 v[6:7], v[8:9], v[12:13]
	v_pk_add_f32 v[8:9], v[8:9], v[12:13] neg_lo:[0,1] neg_hi:[0,1]
	v_pk_add_f32 v[18:19], v[10:11], v[14:15]
	v_pk_add_f32 v[10:11], v[10:11], v[14:15] neg_lo:[0,1] neg_hi:[0,1]
	v_pk_add_f32 v[22:23], v[2:3], v[2:3] op_sel:[1,0]
	v_pk_add_f32 v[2:3], v[2:3], v[2:3] op_sel_hi:[1,0] neg_lo:[0,1] neg_hi:[0,1]
	v_pk_add_f32 v[12:13], v[4:5], v[18:19]
	v_mov_b32_e32 v23, v3
	v_xor_b32_e32 v3, 0x80000000, v8
	v_mov_b32_e32 v2, v9
	v_pk_add_f32 v[8:9], v[10:11], v[10:11] op_sel:[1,0] neg_lo:[0,1] neg_hi:[0,1]
	v_pk_add_f32 v[10:11], v[10:11], v[10:11] op_sel_hi:[1,0]
	v_pk_add_f32 v[4:5], v[4:5], v[18:19] neg_lo:[0,1] neg_hi:[0,1]
	v_mov_b32_e32 v9, v11
	v_pk_mul_f32 v[24:25], v[8:9], s[20:21]
	v_pk_add_f32 v[8:9], v[16:17], v[6:7]
	v_pk_add_f32 v[10:11], v[16:17], v[6:7] neg_lo:[0,1] neg_hi:[0,1]
	v_pk_fma_f32 v[20:21], v[22:23], s[20:21], v[24:25] op_sel_hi:[1,0,1]
	v_pk_fma_f32 v[6:7], v[22:23], s[20:21], v[24:25] op_sel_hi:[1,0,1] neg_lo:[0,0,1] neg_hi:[0,0,1]
	ds_read2_b64 v[22:25], v194 offset1:1
	v_xor_b32_e32 v15, 0x80000000, v4
	v_mov_b32_e32 v14, v5
	v_pk_add_f32 v[16:17], v[0:1], v[2:3]
	v_pk_add_f32 v[0:1], v[0:1], v[2:3] neg_lo:[0,1] neg_hi:[0,1]
	s_waitcnt lgkmcnt(0)
	v_pk_add_f32 v[18:19], v[22:23], v[26:27]
	v_pk_add_f32 v[34:35], v[22:23], v[26:27] neg_lo:[0,1] neg_hi:[0,1]
	v_pk_add_f32 v[22:23], v[24:25], v[28:29] neg_lo:[0,1] neg_hi:[0,1]
	v_pk_add_f32 v[44:45], v[24:25], v[28:29]
	v_pk_add_f32 v[24:25], v[30:31], v[38:39]
	v_pk_add_f32 v[26:27], v[30:31], v[38:39] neg_lo:[0,1] neg_hi:[0,1]
	v_pk_add_f32 v[30:31], v[32:33], v[40:41] neg_lo:[0,1] neg_hi:[0,1]
	v_pk_add_f32 v[38:39], v[22:23], v[22:23] op_sel:[1,0]
	v_pk_add_f32 v[22:23], v[22:23], v[22:23] op_sel_hi:[1,0] neg_lo:[0,1] neg_hi:[0,1]
	v_pk_add_f32 v[28:29], v[32:33], v[40:41]
	v_mov_b32_e32 v39, v23
	v_xor_b32_e32 v33, 0x80000000, v26
	v_mov_b32_e32 v32, v27
	v_pk_add_f32 v[22:23], v[30:31], v[30:31] op_sel:[1,0] neg_lo:[0,1] neg_hi:[0,1]
	v_pk_add_f32 v[26:27], v[30:31], v[30:31] op_sel_hi:[1,0]
	v_pk_add_f32 v[30:31], v[34:35], v[32:33]
	v_mov_b32_e32 v23, v27
	v_pk_mul_f32 v[40:41], v[22:23], s[20:21]
	v_pk_add_f32 v[22:23], v[18:19], v[24:25]
	v_pk_add_f32 v[24:25], v[18:19], v[24:25] neg_lo:[0,1] neg_hi:[0,1]
	v_pk_add_f32 v[18:19], v[44:45], v[28:29] neg_lo:[0,1] neg_hi:[0,1]
	v_pk_add_f32 v[26:27], v[44:45], v[28:29]
	v_xor_b32_e32 v29, 0x80000000, v18
	v_mov_b32_e32 v28, v19
	v_pk_fma_f32 v[18:19], v[38:39], s[20:21], v[40:41] op_sel_hi:[1,0,1] neg_lo:[0,0,1] neg_hi:[0,0,1]
	v_pk_add_f32 v[32:33], v[34:35], v[32:33] neg_lo:[0,1] neg_hi:[0,1]
	v_pk_fma_f32 v[34:35], v[38:39], s[20:21], v[40:41] op_sel_hi:[1,0,1]
	v_xor_b32_e32 v39, 0x80000000, v18
	v_add_u32_e32 v18, s95, v113
	v_mov_b32_e32 v38, v19
	v_ashrrev_i32_e32 v19, 31, v18
	v_xor_b32_e32 v3, 0x80000000, v6
	v_mov_b32_e32 v2, v7
	v_lshl_add_u64 v[40:41], v[18:19], 3, s[8:9]
	v_cndmask_b32_e64 v19, 0, 1, s[70:71]
	v_pk_add_f32 v[42:43], v[8:9], v[12:13]
	v_pk_add_f32 v[4:5], v[10:11], v[14:15]
	v_pk_add_f32 v[36:37], v[16:17], v[20:21]
	v_pk_add_f32 v[6:7], v[0:1], v[2:3]
	v_cmp_ne_u32_e64 s[84:85], 1, v19
	global_store_dwordx2 v[40:41], v[42:43], off
	s_cbranch_vccnz .LBB0_482
	v_add_u32_e32 v48, 0x1000, v18
	v_ashrrev_i32_e32 v49, 31, v48
	v_pk_add_f32 v[46:47], v[22:23], v[26:27]
	v_lshl_add_u64 v[48:49], v[48:49], 3, s[8:9]
	global_store_dwordx2 v[48:49], v[46:47], off
	v_add_u32_e32 v46, 0x200, v18
	v_ashrrev_i32_e32 v47, 31, v46
	v_lshl_add_u64 v[46:47], v[46:47], 3, s[8:9]
	global_store_dwordx2 v[46:47], v[36:37], off
	v_add_u32_e32 v36, 0x1200, v18
	v_ashrrev_i32_e32 v37, 31, v36
	v_pk_add_f32 v[40:41], v[30:31], v[34:35]
	v_lshl_add_u64 v[36:37], v[36:37], 3, s[8:9]
	global_store_dwordx2 v[36:37], v[40:41], off
	v_add_u32_e32 v36, 0x400, v18
	v_ashrrev_i32_e32 v37, 31, v36
	v_pk_add_f32 v[42:43], v[32:33], v[38:39]
	v_pk_add_f32 v[44:45], v[24:25], v[28:29]
	v_lshl_add_u64 v[36:37], v[36:37], 3, s[8:9]
	global_store_dwordx2 v[36:37], v[4:5], off
	v_mov_b32_e32 v41, v178
	v_mov_b64_e32 v[36:37], v[44:45]
	v_mov_b32_e32 v40, v179
	v_mov_b64_e32 v[4:5], v[6:7]
	v_mov_b32_e32 v19, v180
	v_mov_b64_e32 v[6:7], v[42:43]
	s_branch .LBB0_483

; __device__ __forceinline__ c2 mni(c2 a) { return (c2){a.y, -a.x}; }
; __device__ __forceinline__ void dft8(c2 (&x)[8]) {
;     const float s = 0.70710678118654752f;
;     const c2 a0 = x[0] + x[4], a4 = x[0] - x[4], a1 = x[1] + x[5], a5 = x[1] - x[5], a2 = x[2] + x[6], a6 = x[2] - x[6], a3 = x[3] + x[7], a7 = x[3] - x[7];
;     const c2 a5w = (c2){(a5.x + a5.y) * s, (a5.y - a5.x) * s};
;     const c2 a6w = mni(a6);
;     const c2 a7w = (c2){(a7.y - a7.x) * s, -(a7.x + a7.y) * s};
;     const c2 b0 = a0 + a2, b1 = a0 - a2, b2 = a1 + a3, b3 = mni(a1 - a3);
;     x[0] = b0 + b2; x[4] = b0 - b2; x[2] = b1 + b3; x[6] = b1 - b3;
;     const c2 c0 = a4 + a6w, c1 = a4 - a6w, c2_ = a5w + a7w, c3 = mni(a5w - a7w);
;     x[1] = c0 + c2_; x[5] = c0 - c2_; x[3] = c1 + c3; x[7] = c1 - c3;
; }
; __device__ __forceinline__ c2 mpi(c2 a) { return (c2){-a.y, a.x}; }
; __device__ __forceinline__ void idft8(c2 (&x)[8]) {
;     const float s = 0.70710678118654752f;
;     const c2 a0 = x[0] + x[4], a4 = x[0] - x[4], a1 = x[1] + x[5], a5 = x[1] - x[5], a2 = x[2] + x[6], a6 = x[2] - x[6], a3 = x[3] + x[7], a7 = x[3] - x[7];
;     const c2 a5w = (c2){(a5.x - a5.y) * s, (a5.x + a5.y) * s};
;     const c2 a6w = mpi(a6);
;     const c2 a7w = (c2){-(a7.x + a7.y) * s, (a7.x - a7.y) * s};
;     const c2 b0 = a0 + a2, b1 = a0 - a2, b2 = a1 + a3, b3 = mpi(a1 - a3);
;     x[0] = b0 + b2; x[4] = b0 - b2; x[2] = b1 + b3; x[6] = b1 - b3;
;     const c2 c0 = a4 + a6w, c1 = a4 - a6w, c2_ = a5w + a7w, c3 = mpi(a5w - a7w);
;     x[1] = c0 + c2_; x[5] = c0 - c2_; x[3] = c1 + c3; x[7] = c1 - c3;
; }
; __device__ __forceinline__ void fwd_s0(c2 (&x)[8], c2* buf, const c2* tws, int tid) {
;     dft8(x);
; #pragma unroll
;     for (int q = 1; q < 8; ++q) x[q] = cmul(x[q], tws[(q - 1) * 512 + tid]);
;     { c2* bp_ = buf + LP(tid);
; #pragma unroll
;     for (int q = 0; q < 8; ++q) bp_[576 * q] = x[q]; }
; __device__ __forceinline__ void phase_conv(const Params& p, int o, unsigned char* smem, int wave) {
;     ...
;                         c2 x0[8], x1[8];
; #pragma unroll
;                         for (int r = 0; r < 4; ++r) { const int t = tid + 512 * r; x0[r] = (c2){ZVAL(raw + (2 * hh) * RAWROW, t), 0.f}; x1[r] = (c2){ZVAL(raw + (2 * hh + 1) * RAWROW, t), 0.f}; x0[4 + r] = (c2){0.f, 0.f}; x1[4 + r] = (c2){0.f, 0.f}; }
;                         fft_fwd_regs2(x0, x1, buf0, buf1, tws, tid);
; #pragma unroll
.LBB0_558:
	v_pk_add_f32 v[40:41], v[30:31], 0 op_sel_hi:[1,0]
	v_pk_add_f32 v[42:43], v[34:35], 0 op_sel_hi:[1,0]
	v_xor_b32_e32 v45, 0x80000000, v34
	v_sub_f32_e32 v34, 0, v35
	v_mov_b32_e32 v35, v43
	v_pk_add_f32 v[46:47], v[40:41], v[42:43] neg_lo:[0,1] neg_hi:[0,1]
	v_mov_b32_e32 v56, v30
	v_sub_f32_e32 v31, 0, v31
	v_mov_b32_e32 v30, v41
	v_pk_mul_f32 v[34:35], v[34:35], s[20:21]
	v_pk_add_f32 v[40:41], v[40:41], v[42:43]
	v_pk_add_f32 v[42:43], v[46:47], 0 neg_lo:[1,1] neg_hi:[1,1]
	v_mov_b32_e32 v44, v57
	v_mov_b32_e32 v48, v46
	v_mov_b32_e32 v49, v57
	v_mov_b32_e32 v42, v57
	v_pk_fma_f32 v[52:53], v[30:31], s[20:21], v[34:35] op_sel_hi:[1,0,1]
	v_pk_fma_f32 v[30:31], v[30:31], s[20:21], v[34:35] op_sel_hi:[1,0,1] neg_lo:[0,0,1] neg_hi:[0,0,1]
	v_pk_add_f32 v[50:51], v[48:49], v[42:43]
	v_pk_add_f32 v[42:43], v[48:49], v[42:43] neg_lo:[0,1] neg_hi:[0,1]
	v_pk_add_f32 v[48:49], v[56:57], v[44:45]
	v_pk_add_f32 v[44:45], v[56:57], v[44:45] neg_lo:[0,1] neg_hi:[0,1]
	v_xor_b32_e32 v35, 0x80000000, v30
	v_mov_b32_e32 v34, v31
	v_pk_add_f32 v[30:31], v[48:49], v[52:53]
	v_pk_add_f32 v[48:49], v[48:49], v[52:53] neg_lo:[0,1] neg_hi:[0,1]
	v_pk_add_f32 v[52:53], v[44:45], v[34:35]
	v_pk_add_f32 v[34:35], v[44:45], v[34:35] neg_lo:[0,1] neg_hi:[0,1]
	s_waitcnt lgkmcnt(0)
	v_pk_mul_f32 v[94:95], v[30:31], v[210:211] op_sel:[1,1] op_sel_hi:[1,0]
	v_pk_add_f32 v[46:47], v[40:41], v[40:41] op_sel:[0,1] op_sel_hi:[1,0]
	v_fma_f32 v96, v30, v210, -v94
	v_fma_f32 v97, v30, v211, v95
	v_pk_mul_f32 v[30:31], v[50:51], v[212:213] op_sel:[1,1] op_sel_hi:[1,0]
	v_mov_b32_e32 v47, v57
	v_fma_f32 v54, v50, v212, -v30
	v_fma_f32 v55, v50, v213, v31
	v_pk_mul_f32 v[30:31], v[52:53], v[214:215] op_sel:[1,1] op_sel_hi:[1,0]
	v_mov_b32_e32 v56, v28
	v_fma_f32 v44, v52, v214, -v30
	v_fma_f32 v45, v52, v215, v31
	v_pk_add_f32 v[30:31], v[40:41], v[40:41] op_sel:[0,1] op_sel_hi:[0,1] neg_lo:[0,1] neg_hi:[0,1]
	v_pk_mul_f32 v[40:41], v[216:217], 0 op_sel_hi:[1,0]
	s_lshl_b32 s7, s40, 13
	v_fma_f32 v50, v30, v216, -v41
	v_fma_f32 v51, v31, v217, v40
	v_pk_mul_f32 v[90:91], v[48:49], v[218:219] op_sel:[1,1] op_sel_hi:[1,0]
	v_mov_b64_e32 v[40:41], v[222:223]
	v_fma_f32 v92, v48, v218, -v90
	v_fma_f32 v93, v48, v219, v91
	v_pk_mul_f32 v[48:49], v[42:43], v[220:221] op_sel:[1,1] op_sel_hi:[1,0]
	s_or_b32 s7, s7, s3
	v_fma_f32 v52, v42, v220, -v48
	v_fma_f32 v53, v42, v221, v49
	v_pk_mul_f32 v[30:31], v[34:35], v[40:41] op_sel:[1,1] op_sel_hi:[1,0]
	s_or_b32 s16, s7, 0x200
	v_fma_f32 v42, v34, v40, -v30
	v_fma_f32 v43, v34, v41, v31
	ds_write2st64_b64 v115, v[46:47], v[96:97] offset1:9
	ds_write2st64_b64 v115, v[54:55], v[44:45] offset0:18 offset1:27
	ds_write2st64_b64 v115, v[50:51], v[92:93] offset0:36 offset1:45
	ds_write2st64_b64 v115, v[52:53], v[42:43] offset0:54 offset1:63
	v_pk_add_f32 v[30:31], v[28:29], 0 op_sel_hi:[1,0]
	v_pk_add_f32 v[34:35], v[32:33], 0 op_sel_hi:[1,0]
	v_xor_b32_e32 v41, 0x80000000, v32
	v_sub_f32_e32 v32, 0, v33
	v_mov_b32_e32 v33, v35
	v_pk_add_f32 v[42:43], v[30:31], v[34:35] neg_lo:[0,1] neg_hi:[0,1]
	v_sub_f32_e32 v29, 0, v29
	v_mov_b32_e32 v28, v31
	v_pk_mul_f32 v[32:33], v[32:33], s[20:21]
	v_pk_add_f32 v[30:31], v[30:31], v[34:35]
	v_pk_add_f32 v[34:35], v[42:43], 0 neg_lo:[1,1] neg_hi:[1,1]
	v_mov_b32_e32 v40, v57
	v_mov_b32_e32 v44, v42
	v_mov_b32_e32 v45, v57
	v_mov_b32_e32 v34, v57
	v_pk_fma_f32 v[48:49], v[28:29], s[20:21], v[32:33] op_sel_hi:[1,0,1]
	v_pk_fma_f32 v[28:29], v[28:29], s[20:21], v[32:33] op_sel_hi:[1,0,1] neg_lo:[0,0,1] neg_hi:[0,0,1]
	v_pk_add_f32 v[46:47], v[44:45], v[34:35]
	v_pk_add_f32 v[34:35], v[44:45], v[34:35] neg_lo:[0,1] neg_hi:[0,1]
	v_pk_add_f32 v[44:45], v[56:57], v[40:41]
	v_pk_add_f32 v[40:41], v[56:57], v[40:41] neg_lo:[0,1] neg_hi:[0,1]
	v_xor_b32_e32 v33, 0x80000000, v28
	v_mov_b32_e32 v32, v29
	v_pk_add_f32 v[28:29], v[44:45], v[48:49]
	v_pk_add_f32 v[44:45], v[44:45], v[48:49] neg_lo:[0,1] neg_hi:[0,1]
	v_pk_add_f32 v[48:49], v[40:41], v[32:33]
	v_pk_add_f32 v[32:33], v[40:41], v[32:33] neg_lo:[0,1] neg_hi:[0,1]
	s_waitcnt lgkmcnt(0)
	v_pk_mul_f32 v[90:91], v[28:29], v[210:211] op_sel:[1,1] op_sel_hi:[1,0]
	v_pk_add_f32 v[42:43], v[30:31], v[30:31] op_sel:[0,1] op_sel_hi:[1,0]
	v_fma_f32 v92, v28, v210, -v90
	v_fma_f32 v93, v28, v211, v91
	v_pk_mul_f32 v[28:29], v[46:47], v[212:213] op_sel:[1,1] op_sel_hi:[1,0]
	v_mov_b32_e32 v43, v57
	v_fma_f32 v50, v46, v212, -v28
	v_fma_f32 v51, v46, v213, v29
	v_pk_mul_f32 v[28:29], v[48:49], v[214:215] op_sel:[1,1] op_sel_hi:[1,0]
	s_xor_b64 s[70:71], s[62:63], -1
	v_fma_f32 v40, v48, v214, -v28
	v_fma_f32 v41, v48, v215, v29
	v_pk_add_f32 v[28:29], v[30:31], v[30:31] op_sel:[0,1] op_sel_hi:[0,1] neg_lo:[0,1] neg_hi:[0,1]
	v_pk_mul_f32 v[30:31], v[216:217], 0 op_sel_hi:[1,0]
	s_mov_b32 s40, 1
	v_fma_f32 v46, v28, v216, -v31
	v_fma_f32 v47, v29, v217, v30
	v_pk_mul_f32 v[52:53], v[44:45], v[218:219] op_sel:[1,1] op_sel_hi:[1,0]
	v_mov_b64_e32 v[30:31], v[222:223]
	v_fma_f32 v54, v44, v218, -v52
	v_fma_f32 v55, v44, v219, v53
	v_pk_mul_f32 v[44:45], v[34:35], v[220:221] op_sel:[1,1] op_sel_hi:[1,0]
	s_mov_b64 s[62:63], 0
	v_fma_f32 v48, v34, v220, -v44
	v_fma_f32 v49, v34, v221, v45
	v_pk_mul_f32 v[28:29], v[32:33], v[30:31] op_sel:[1,1] op_sel_hi:[1,0]
	s_and_b64 vcc, exec, s[70:71]
	v_fma_f32 v34, v32, v30, -v28
	v_fma_f32 v35, v32, v31, v29
	ds_write2st64_b64 v115, v[42:43], v[92:93] offset0:72 offset1:81
	ds_write2st64_b64 v115, v[50:51], v[40:41] offset0:90 offset1:99
	ds_write2st64_b64 v115, v[46:47], v[54:55] offset0:108 offset1:117
	ds_write_b64 v115, v[48:49] offset:64512
	ds_write_b64 v116, v[34:35] offset:32256
	s_waitcnt lgkmcnt(0)
	s_barrier
; __device__ __forceinline__ c2 cmul(c2 a, c2 b) { return (c2){a.x * b.x - a.y * b.y, a.x * b.y + a.y * b.x}; }
; __device__ __forceinline__ c2 mni(c2 a) { return (c2){a.y, -a.x}; }
; __device__ __forceinline__ void dft8(c2 (&x)[8]) {
;     const float s = 0.70710678118654752f;
;     const c2 a0 = x[0] + x[4], a4 = x[0] - x[4], a1 = x[1] + x[5], a5 = x[1] - x[5], a2 = x[2] + x[6], a6 = x[2] - x[6], a3 = x[3] + x[7], a7 = x[3] - x[7];
;     const c2 a5w = (c2){(a5.x + a5.y) * s, (a5.y - a5.x) * s};
;     const c2 a6w = mni(a6);
;     const c2 a7w = (c2){(a7.y - a7.x) * s, -(a7.x + a7.y) * s};
;     const c2 b0 = a0 + a2, b1 = a0 - a2, b2 = a1 + a3, b3 = mni(a1 - a3);
;     x[0] = b0 + b2; x[4] = b0 - b2; x[2] = b1 + b3; x[6] = b1 - b3;
;     const c2 c0 = a4 + a6w, c1 = a4 - a6w, c2_ = a5w + a7w, c3 = mni(a5w - a7w);
;     x[1] = c0 + c2_; x[5] = c0 - c2_; x[3] = c1 + c3; x[7] = c1 - c3;
; }
; template <int S> __device__ __forceinline__ void fwd_mid(c2* buf, const c2* tws, int tid) {
;     constexpr int lq = 9 - 3 * S, Q = 1 << lq; const c2* T = tws + (S == 1 ? 3584 : 4032);
;     const int k = tid & (Q - 1), base = ((tid >> lq) << (lq + 3)) + k;
;     c2 x[8];
;     c2* bp_ = buf + LP(base); constexpr int QP = Q + Q / 8;
; #pragma unroll
;     for (int r = 0; r < 8; ++r) x[r] = bp_[r * QP];
;     dft8(x);
; #pragma unroll
;     for (int q = 1; q < 8; ++q) x[q] = cmul(x[q], T[(q - 1) * Q + k]);
; #pragma unroll
;     for (int q = 0; q < 8; ++q) bp_[q * QP] = x[q];
; }
	ds_read2_b64 v[28:31], v117 offset1:72
	ds_read2_b64 v[32:35], v63 offset0:32 offset1:104
	ds_read2_b64 v[40:43], v117 offset0:144 offset1:216
	ds_read2_b64 v[44:47], v63 offset0:176 offset1:248
	v_mov_b64_e32 v[50:51], v[224:225]
	s_waitcnt lgkmcnt(0)
	v_pk_add_f32 v[48:49], v[28:29], v[32:33]
	v_pk_add_f32 v[28:29], v[28:29], v[32:33] neg_lo:[0,1] neg_hi:[0,1]
	v_pk_add_f32 v[32:33], v[30:31], v[34:35]
	v_pk_add_f32 v[30:31], v[30:31], v[34:35] neg_lo:[0,1] neg_hi:[0,1]
	v_pk_add_f32 v[34:35], v[40:41], v[44:45]
	v_pk_add_f32 v[40:41], v[40:41], v[44:45] neg_lo:[0,1] neg_hi:[0,1]
	v_pk_add_f32 v[44:45], v[42:43], v[46:47]
	v_pk_add_f32 v[42:43], v[42:43], v[46:47] neg_lo:[0,1] neg_hi:[0,1]
	v_pk_add_f32 v[46:47], v[30:31], v[30:31] op_sel:[1,0]
	v_pk_add_f32 v[30:31], v[30:31], v[30:31] op_sel_hi:[1,0] neg_lo:[0,1] neg_hi:[0,1]
	s_nop 0
	v_mov_b32_e32 v47, v31
	v_xor_b32_e32 v31, 0x80000000, v40
	v_mov_b32_e32 v30, v41
	v_pk_add_f32 v[40:41], v[42:43], v[42:43] op_sel:[1,0] neg_lo:[0,1] neg_hi:[0,1]
	v_pk_add_f32 v[42:43], v[42:43], v[42:43] op_sel_hi:[1,0]
	s_nop 0
	v_mov_b32_e32 v41, v43
	v_pk_add_f32 v[42:43], v[48:49], v[34:35]
	v_pk_add_f32 v[34:35], v[48:49], v[34:35] neg_lo:[0,1] neg_hi:[0,1]
	v_pk_add_f32 v[48:49], v[32:33], v[44:45]
	v_pk_add_f32 v[32:33], v[32:33], v[44:45] neg_lo:[0,1] neg_hi:[0,1]
	v_pk_mul_f32 v[40:41], v[40:41], s[20:21]
	v_xor_b32_e32 v45, 0x80000000, v32
	v_mov_b32_e32 v44, v33
	v_pk_add_f32 v[32:33], v[42:43], v[48:49]
	v_pk_add_f32 v[42:43], v[42:43], v[48:49] neg_lo:[0,1] neg_hi:[0,1]
	v_pk_add_f32 v[48:49], v[34:35], v[44:45]
	v_pk_add_f32 v[34:35], v[34:35], v[44:45] neg_lo:[0,1] neg_hi:[0,1]
	v_pk_add_f32 v[44:45], v[28:29], v[30:31]
	v_pk_add_f32 v[28:29], v[28:29], v[30:31] neg_lo:[0,1] neg_hi:[0,1]
	v_pk_fma_f32 v[30:31], v[46:47], s[20:21], v[40:41] op_sel_hi:[1,0,1]
	v_pk_fma_f32 v[40:41], v[46:47], s[20:21], v[40:41] op_sel_hi:[1,0,1] neg_lo:[0,0,1] neg_hi:[0,0,1]
	s_nop 0
	v_xor_b32_e32 v47, 0x80000000, v40
	v_mov_b32_e32 v46, v41
	v_pk_add_f32 v[40:41], v[44:45], v[30:31]
	v_pk_add_f32 v[30:31], v[44:45], v[30:31] neg_lo:[0,1] neg_hi:[0,1]
	v_pk_add_f32 v[44:45], v[28:29], v[46:47]
	v_pk_add_f32 v[28:29], v[28:29], v[46:47] neg_lo:[0,1] neg_hi:[0,1]
	v_pk_mul_f32 v[90:91], v[50:51], v[40:41] op_sel:[1,1] op_sel_hi:[0,1]
	v_fma_f32 v92, v50, v40, -v90
	v_fma_f32 v93, v51, v40, v91
	s_nop 0
	v_pk_mul_f32 v[40:41], v[226:227], v[48:49] op_sel:[1,1] op_sel_hi:[0,1]
	v_fma_f32 v50, v226, v48, -v40
	v_fma_f32 v51, v227, v48, v41
	v_pk_mul_f32 v[40:41], v[228:229], v[44:45] op_sel:[1,1] op_sel_hi:[0,1]
	v_fma_f32 v46, v228, v44, -v40
	v_fma_f32 v47, v229, v44, v41
	v_pk_mul_f32 v[52:53], v[232:233], v[30:31] op_sel:[1,1] op_sel_hi:[0,1]
	v_pk_mul_f32 v[40:41], v[42:43], v[230:231] op_sel:[1,1] op_sel_hi:[1,0]
	s_nop 0
	v_fma_f32 v44, v42, v230, -v40
	v_fma_f32 v45, v42, v231, v41
	v_mov_b64_e32 v[42:43], v[236:237]
	v_fma_f32 v54, v232, v30, -v52
	v_fma_f32 v55, v233, v30, v53
	ds_write2_b64 v117, v[32:33], v[92:93] offset1:72
	ds_write2_b64 v117, v[50:51], v[46:47] offset0:144 offset1:216
	s_waitcnt lgkmcnt(0)
	v_pk_mul_f32 v[30:31], v[34:35], v[234:235] op_sel:[1,1] op_sel_hi:[1,0]
	s_nop 0
	v_fma_f32 v48, v34, v234, -v30
	v_fma_f32 v49, v34, v235, v31
	v_pk_mul_f32 v[30:31], v[42:43], v[28:29] op_sel:[1,1] op_sel_hi:[0,1]
	v_fma_f32 v40, v42, v28, -v30
	v_fma_f32 v41, v43, v28, v31
	s_nop 0
	ds_read2_b64 v[28:31], v191 offset1:72
	ds_read2_b64 v[32:35], v192 offset0:32 offset1:104
	ds_write2_b64 v63, v[44:45], v[54:55] offset0:32 offset1:104
	ds_write2_b64 v63, v[48:49], v[40:41] offset0:176 offset1:248
	ds_read2_b64 v[40:43], v191 offset0:144 offset1:216
	ds_read2_b64 v[44:47], v192 offset0:176 offset1:248
	v_mov_b64_e32 v[50:51], v[224:225]
	s_waitcnt lgkmcnt(0)
	v_pk_add_f32 v[48:49], v[28:29], v[32:33]
	v_pk_add_f32 v[28:29], v[28:29], v[32:33] neg_lo:[0,1] neg_hi:[0,1]
	v_pk_add_f32 v[32:33], v[30:31], v[34:35]
	v_pk_add_f32 v[30:31], v[30:31], v[34:35] neg_lo:[0,1] neg_hi:[0,1]
	v_pk_add_f32 v[34:35], v[40:41], v[44:45]
	v_pk_add_f32 v[40:41], v[40:41], v[44:45] neg_lo:[0,1] neg_hi:[0,1]
	v_pk_add_f32 v[44:45], v[42:43], v[46:47]
	v_pk_add_f32 v[42:43], v[42:43], v[46:47] neg_lo:[0,1] neg_hi:[0,1]
	v_pk_add_f32 v[46:47], v[30:31], v[30:31] op_sel:[1,0]
	v_pk_add_f32 v[30:31], v[30:31], v[30:31] op_sel_hi:[1,0] neg_lo:[0,1] neg_hi:[0,1]
	s_nop 0
	v_mov_b32_e32 v47, v31
	v_xor_b32_e32 v31, 0x80000000, v40
	v_mov_b32_e32 v30, v41
	v_pk_add_f32 v[40:41], v[42:43], v[42:43] op_sel:[1,0] neg_lo:[0,1] neg_hi:[0,1]
	v_pk_add_f32 v[42:43], v[42:43], v[42:43] op_sel_hi:[1,0]
	s_nop 0
	v_mov_b32_e32 v41, v43
	v_pk_add_f32 v[42:43], v[48:49], v[34:35]
	v_pk_add_f32 v[34:35], v[48:49], v[34:35] neg_lo:[0,1] neg_hi:[0,1]
	v_pk_add_f32 v[48:49], v[32:33], v[44:45]
	v_pk_add_f32 v[32:33], v[32:33], v[44:45] neg_lo:[0,1] neg_hi:[0,1]
	v_pk_mul_f32 v[40:41], v[40:41], s[20:21]
	v_xor_b32_e32 v45, 0x80000000, v32
	v_mov_b32_e32 v44, v33
	v_pk_add_f32 v[32:33], v[42:43], v[48:49]
	v_pk_add_f32 v[42:43], v[42:43], v[48:49] neg_lo:[0,1] neg_hi:[0,1]
	v_pk_add_f32 v[48:49], v[34:35], v[44:45]
	v_pk_add_f32 v[34:35], v[34:35], v[44:45] neg_lo:[0,1] neg_hi:[0,1]
	v_pk_add_f32 v[44:45], v[28:29], v[30:31]
	v_pk_add_f32 v[28:29], v[28:29], v[30:31] neg_lo:[0,1] neg_hi:[0,1]
	v_pk_fma_f32 v[30:31], v[46:47], s[20:21], v[40:41] op_sel_hi:[1,0,1]
	v_pk_fma_f32 v[40:41], v[46:47], s[20:21], v[40:41] op_sel_hi:[1,0,1] neg_lo:[0,0,1] neg_hi:[0,0,1]
	s_nop 0
	v_xor_b32_e32 v47, 0x80000000, v40
	v_mov_b32_e32 v46, v41
	v_pk_add_f32 v[40:41], v[44:45], v[30:31]
	v_pk_add_f32 v[30:31], v[44:45], v[30:31] neg_lo:[0,1] neg_hi:[0,1]
; __device__ __forceinline__ c2 cmul(c2 a, c2 b) { return (c2){a.x * b.x - a.y * b.y, a.x * b.y + a.y * b.x}; }
; __device__ __forceinline__ c2 mni(c2 a) { return (c2){a.y, -a.x}; }
; __device__ __forceinline__ void dft8(c2 (&x)[8]) {
;     const float s = 0.70710678118654752f;
;     const c2 a0 = x[0] + x[4], a4 = x[0] - x[4], a1 = x[1] + x[5], a5 = x[1] - x[5], a2 = x[2] + x[6], a6 = x[2] - x[6], a3 = x[3] + x[7], a7 = x[3] - x[7];
;     const c2 a5w = (c2){(a5.x + a5.y) * s, (a5.y - a5.x) * s};
;     const c2 a6w = mni(a6);
;     const c2 a7w = (c2){(a7.y - a7.x) * s, -(a7.x + a7.y) * s};
;     const c2 b0 = a0 + a2, b1 = a0 - a2, b2 = a1 + a3, b3 = mni(a1 - a3);
;     x[0] = b0 + b2; x[4] = b0 - b2; x[2] = b1 + b3; x[6] = b1 - b3;
;     const c2 c0 = a4 + a6w, c1 = a4 - a6w, c2_ = a5w + a7w, c3 = mni(a5w - a7w);
;     x[1] = c0 + c2_; x[5] = c0 - c2_; x[3] = c1 + c3; x[7] = c1 - c3;
; }
; template <int S> __device__ __forceinline__ void fwd_mid(c2* buf, const c2* tws, int tid) {
;     constexpr int lq = 9 - 3 * S, Q = 1 << lq; const c2* T = tws + (S == 1 ? 3584 : 4032);
;     const int k = tid & (Q - 1), base = ((tid >> lq) << (lq + 3)) + k;
;     c2 x[8];
;     c2* bp_ = buf + LP(base); constexpr int QP = Q + Q / 8;
; #pragma unroll
;     for (int r = 0; r < 8; ++r) x[r] = bp_[r * QP];
;     dft8(x);
; #pragma unroll
;     for (int q = 1; q < 8; ++q) x[q] = cmul(x[q], T[(q - 1) * Q + k]);
; #pragma unroll
;     for (int q = 0; q < 8; ++q) bp_[q * QP] = x[q];
; }
	v_pk_add_f32 v[44:45], v[28:29], v[46:47]
	v_pk_add_f32 v[28:29], v[28:29], v[46:47] neg_lo:[0,1] neg_hi:[0,1]
	v_pk_mul_f32 v[90:91], v[50:51], v[40:41] op_sel:[1,1] op_sel_hi:[0,1]
	v_fma_f32 v92, v50, v40, -v90
	v_fma_f32 v93, v51, v40, v91
	s_nop 0
	v_pk_mul_f32 v[40:41], v[226:227], v[48:49] op_sel:[1,1] op_sel_hi:[0,1]
	v_fma_f32 v50, v226, v48, -v40
	v_fma_f32 v51, v227, v48, v41
	v_pk_mul_f32 v[40:41], v[228:229], v[44:45] op_sel:[1,1] op_sel_hi:[0,1]
	v_fma_f32 v46, v228, v44, -v40
	v_fma_f32 v47, v229, v44, v41
	v_pk_mul_f32 v[52:53], v[232:233], v[30:31] op_sel:[1,1] op_sel_hi:[0,1]
	v_pk_mul_f32 v[40:41], v[42:43], v[230:231] op_sel:[1,1] op_sel_hi:[1,0]
	s_nop 0
	v_fma_f32 v44, v42, v230, -v40
	v_fma_f32 v45, v42, v231, v41
	v_mov_b64_e32 v[40:41], v[234:235]
	v_mov_b64_e32 v[42:43], v[236:237]
	v_fma_f32 v54, v232, v30, -v52
	v_fma_f32 v55, v233, v30, v53
	s_nop 0
	v_pk_mul_f32 v[30:31], v[34:35], v[40:41] op_sel:[1,1] op_sel_hi:[1,0]
	s_nop 0
	v_fma_f32 v48, v34, v40, -v30
	v_fma_f32 v49, v34, v41, v31
	v_pk_mul_f32 v[30:31], v[42:43], v[28:29] op_sel:[1,1] op_sel_hi:[0,1]
	v_fma_f32 v34, v42, v28, -v30
	v_fma_f32 v35, v43, v28, v31
	s_nop 0
	ds_write2_b64 v191, v[32:33], v[92:93] offset1:72
	ds_write2_b64 v191, v[50:51], v[46:47] offset0:144 offset1:216
	ds_write2_b64 v192, v[44:45], v[54:55] offset0:32 offset1:104
	ds_write2_b64 v192, v[48:49], v[34:35] offset0:176 offset1:248
	s_waitcnt lgkmcnt(0)
	s_barrier
	ds_read2_b64 v[28:31], v119 offset1:9
	ds_read2_b64 v[32:35], v119 offset0:36 offset1:45
	ds_read2_b64 v[40:43], v119 offset0:18 offset1:27
	ds_read2_b64 v[44:47], v119 offset0:54 offset1:63
	v_mov_b64_e32 v[50:51], v[238:239]
	s_waitcnt lgkmcnt(0)
	v_pk_add_f32 v[48:49], v[28:29], v[32:33]
	v_pk_add_f32 v[28:29], v[28:29], v[32:33] neg_lo:[0,1] neg_hi:[0,1]
	v_pk_add_f32 v[32:33], v[30:31], v[34:35]
	v_pk_add_f32 v[30:31], v[30:31], v[34:35] neg_lo:[0,1] neg_hi:[0,1]
	v_pk_add_f32 v[34:35], v[40:41], v[44:45]
	v_pk_add_f32 v[40:41], v[40:41], v[44:45] neg_lo:[0,1] neg_hi:[0,1]
	v_pk_add_f32 v[44:45], v[42:43], v[46:47]
	v_pk_add_f32 v[42:43], v[42:43], v[46:47] neg_lo:[0,1] neg_hi:[0,1]
	v_pk_add_f32 v[46:47], v[30:31], v[30:31] op_sel:[1,0]
	v_pk_add_f32 v[30:31], v[30:31], v[30:31] op_sel_hi:[1,0] neg_lo:[0,1] neg_hi:[0,1]
	s_nop 0
	v_mov_b32_e32 v47, v31
	v_xor_b32_e32 v31, 0x80000000, v40
	v_mov_b32_e32 v30, v41
	v_pk_add_f32 v[40:41], v[42:43], v[42:43] op_sel:[1,0] neg_lo:[0,1] neg_hi:[0,1]
	v_pk_add_f32 v[42:43], v[42:43], v[42:43] op_sel_hi:[1,0]
	s_nop 0
	v_mov_b32_e32 v41, v43
	v_pk_add_f32 v[42:43], v[48:49], v[34:35]
	v_pk_add_f32 v[34:35], v[48:49], v[34:35] neg_lo:[0,1] neg_hi:[0,1]
	v_pk_add_f32 v[48:49], v[32:33], v[44:45]
	v_pk_add_f32 v[32:33], v[32:33], v[44:45] neg_lo:[0,1] neg_hi:[0,1]
	v_pk_mul_f32 v[40:41], v[40:41], s[20:21]
	v_xor_b32_e32 v45, 0x80000000, v32
	v_mov_b32_e32 v44, v33
	v_pk_add_f32 v[32:33], v[42:43], v[48:49]
	v_pk_add_f32 v[42:43], v[42:43], v[48:49] neg_lo:[0,1] neg_hi:[0,1]
	v_pk_add_f32 v[48:49], v[34:35], v[44:45]
	v_pk_add_f32 v[34:35], v[34:35], v[44:45] neg_lo:[0,1] neg_hi:[0,1]
	v_pk_add_f32 v[44:45], v[28:29], v[30:31]
	v_pk_add_f32 v[28:29], v[28:29], v[30:31] neg_lo:[0,1] neg_hi:[0,1]
	v_pk_fma_f32 v[30:31], v[46:47], s[20:21], v[40:41] op_sel_hi:[1,0,1]
	v_pk_fma_f32 v[40:41], v[46:47], s[20:21], v[40:41] op_sel_hi:[1,0,1] neg_lo:[0,0,1] neg_hi:[0,0,1]
	s_nop 0
	v_xor_b32_e32 v47, 0x80000000, v40
	v_mov_b32_e32 v46, v41
	v_pk_add_f32 v[40:41], v[44:45], v[30:31]
	v_pk_add_f32 v[30:31], v[44:45], v[30:31] neg_lo:[0,1] neg_hi:[0,1]
	v_pk_add_f32 v[44:45], v[28:29], v[46:47]
	v_pk_add_f32 v[28:29], v[28:29], v[46:47] neg_lo:[0,1] neg_hi:[0,1]
	v_pk_mul_f32 v[90:91], v[50:51], v[40:41] op_sel:[1,1] op_sel_hi:[0,1]
	v_fma_f32 v92, v50, v40, -v90
	v_fma_f32 v93, v51, v40, v91
	s_nop 0
	v_pk_mul_f32 v[40:41], v[240:241], v[48:49] op_sel:[1,1] op_sel_hi:[0,1]
	v_fma_f32 v50, v240, v48, -v40
	v_fma_f32 v51, v241, v48, v41
	v_pk_mul_f32 v[40:41], v[242:243], v[44:45] op_sel:[1,1] op_sel_hi:[0,1]
	v_fma_f32 v46, v242, v44, -v40
	v_fma_f32 v47, v243, v44, v41
	v_pk_mul_f32 v[52:53], v[246:247], v[30:31] op_sel:[1,1] op_sel_hi:[0,1]
	v_pk_mul_f32 v[40:41], v[42:43], v[244:245] op_sel:[1,1] op_sel_hi:[1,0]
	s_nop 0
	v_fma_f32 v44, v42, v244, -v40
	v_fma_f32 v45, v42, v245, v41
	v_mov_b64_e32 v[42:43], v[250:251]
	v_fma_f32 v54, v246, v30, -v52
	v_fma_f32 v55, v247, v30, v53
	ds_write2_b64 v119, v[32:33], v[92:93] offset1:9
	ds_write2_b64 v119, v[50:51], v[46:47] offset0:18 offset1:27
	s_waitcnt lgkmcnt(0)
	v_pk_mul_f32 v[30:31], v[34:35], v[248:249] op_sel:[1,1] op_sel_hi:[1,0]
	s_nop 0
	v_fma_f32 v48, v34, v248, -v30
	v_fma_f32 v49, v34, v249, v31
	v_pk_mul_f32 v[30:31], v[42:43], v[28:29] op_sel:[1,1] op_sel_hi:[0,1]
	v_fma_f32 v40, v42, v28, -v30
	v_fma_f32 v41, v43, v28, v31
	s_nop 0
	ds_read2_b64 v[28:31], v193 offset1:9
	ds_read2_b64 v[32:35], v193 offset0:36 offset1:45
	ds_write2_b64 v119, v[44:45], v[54:55] offset0:36 offset1:45
	ds_write2_b64 v119, v[48:49], v[40:41] offset0:54 offset1:63
	ds_read2_b64 v[40:43], v193 offset0:18 offset1:27
	ds_read2_b64 v[44:47], v193 offset0:54 offset1:63
	v_mov_b64_e32 v[50:51], v[238:239]
	s_waitcnt lgkmcnt(0)
; __device__ __forceinline__ c2 cmul(c2 a, c2 b) { return (c2){a.x * b.x - a.y * b.y, a.x * b.y + a.y * b.x}; }
; __device__ __forceinline__ c2 mni(c2 a) { return (c2){a.y, -a.x}; }
; __device__ __forceinline__ void dft8(c2 (&x)[8]) {
;     const float s = 0.70710678118654752f;
;     const c2 a0 = x[0] + x[4], a4 = x[0] - x[4], a1 = x[1] + x[5], a5 = x[1] - x[5], a2 = x[2] + x[6], a6 = x[2] - x[6], a3 = x[3] + x[7], a7 = x[3] - x[7];
;     const c2 a5w = (c2){(a5.x + a5.y) * s, (a5.y - a5.x) * s};
;     const c2 a6w = mni(a6);
;     const c2 a7w = (c2){(a7.y - a7.x) * s, -(a7.x + a7.y) * s};
;     const c2 b0 = a0 + a2, b1 = a0 - a2, b2 = a1 + a3, b3 = mni(a1 - a3);
;     x[0] = b0 + b2; x[4] = b0 - b2; x[2] = b1 + b3; x[6] = b1 - b3;
;     const c2 c0 = a4 + a6w, c1 = a4 - a6w, c2_ = a5w + a7w, c3 = mni(a5w - a7w);
;     x[1] = c0 + c2_; x[5] = c0 - c2_; x[3] = c1 + c3; x[7] = c1 - c3;
; }
; template <int S> __device__ __forceinline__ void fwd_mid(c2* buf, const c2* tws, int tid) {
;     constexpr int lq = 9 - 3 * S, Q = 1 << lq; const c2* T = tws + (S == 1 ? 3584 : 4032);
;     const int k = tid & (Q - 1), base = ((tid >> lq) << (lq + 3)) + k;
;     c2 x[8];
;     c2* bp_ = buf + LP(base); constexpr int QP = Q + Q / 8;
; #pragma unroll
;     for (int r = 0; r < 8; ++r) x[r] = bp_[r * QP];
;     dft8(x);
; #pragma unroll
;     for (int q = 1; q < 8; ++q) x[q] = cmul(x[q], T[(q - 1) * Q + k]);
; #pragma unroll
;     for (int q = 0; q < 8; ++q) bp_[q * QP] = x[q];
; }
	v_pk_add_f32 v[48:49], v[28:29], v[32:33]
	v_pk_add_f32 v[28:29], v[28:29], v[32:33] neg_lo:[0,1] neg_hi:[0,1]
	v_pk_add_f32 v[32:33], v[30:31], v[34:35]
	v_pk_add_f32 v[30:31], v[30:31], v[34:35] neg_lo:[0,1] neg_hi:[0,1]
	v_pk_add_f32 v[34:35], v[40:41], v[44:45]
	v_pk_add_f32 v[40:41], v[40:41], v[44:45] neg_lo:[0,1] neg_hi:[0,1]
	v_pk_add_f32 v[44:45], v[42:43], v[46:47]
	v_pk_add_f32 v[42:43], v[42:43], v[46:47] neg_lo:[0,1] neg_hi:[0,1]
	v_pk_add_f32 v[46:47], v[30:31], v[30:31] op_sel:[1,0]
	v_pk_add_f32 v[30:31], v[30:31], v[30:31] op_sel_hi:[1,0] neg_lo:[0,1] neg_hi:[0,1]
	s_nop 0
	v_mov_b32_e32 v47, v31
	v_xor_b32_e32 v31, 0x80000000, v40
	v_mov_b32_e32 v30, v41
	v_pk_add_f32 v[40:41], v[42:43], v[42:43] op_sel:[1,0] neg_lo:[0,1] neg_hi:[0,1]
	v_pk_add_f32 v[42:43], v[42:43], v[42:43] op_sel_hi:[1,0]
	s_nop 0
	v_mov_b32_e32 v41, v43
	v_pk_add_f32 v[42:43], v[48:49], v[34:35]
	v_pk_add_f32 v[34:35], v[48:49], v[34:35] neg_lo:[0,1] neg_hi:[0,1]
	v_pk_add_f32 v[48:49], v[32:33], v[44:45]
	v_pk_add_f32 v[32:33], v[32:33], v[44:45] neg_lo:[0,1] neg_hi:[0,1]
	v_pk_mul_f32 v[40:41], v[40:41], s[20:21]
	v_xor_b32_e32 v45, 0x80000000, v32
	v_mov_b32_e32 v44, v33
	v_pk_add_f32 v[32:33], v[42:43], v[48:49]
	v_pk_add_f32 v[42:43], v[42:43], v[48:49] neg_lo:[0,1] neg_hi:[0,1]
	v_pk_add_f32 v[48:49], v[34:35], v[44:45]
	v_pk_add_f32 v[34:35], v[34:35], v[44:45] neg_lo:[0,1] neg_hi:[0,1]
	v_pk_add_f32 v[44:45], v[28:29], v[30:31]
	v_pk_add_f32 v[28:29], v[28:29], v[30:31] neg_lo:[0,1] neg_hi:[0,1]
	v_pk_fma_f32 v[30:31], v[46:47], s[20:21], v[40:41] op_sel_hi:[1,0,1]
	v_pk_fma_f32 v[40:41], v[46:47], s[20:21], v[40:41] op_sel_hi:[1,0,1] neg_lo:[0,0,1] neg_hi:[0,0,1]
	s_nop 0
	v_xor_b32_e32 v47, 0x80000000, v40
	v_mov_b32_e32 v46, v41
	v_pk_add_f32 v[40:41], v[44:45], v[30:31]
	v_pk_add_f32 v[30:31], v[44:45], v[30:31] neg_lo:[0,1] neg_hi:[0,1]
	v_pk_add_f32 v[44:45], v[28:29], v[46:47]
	v_pk_add_f32 v[28:29], v[28:29], v[46:47] neg_lo:[0,1] neg_hi:[0,1]
	v_pk_mul_f32 v[90:91], v[50:51], v[40:41] op_sel:[1,1] op_sel_hi:[0,1]
	v_fma_f32 v92, v50, v40, -v90
	v_fma_f32 v93, v51, v40, v91
	s_nop 0
	v_pk_mul_f32 v[40:41], v[240:241], v[48:49] op_sel:[1,1] op_sel_hi:[0,1]
	v_fma_f32 v50, v240, v48, -v40
	v_fma_f32 v51, v241, v48, v41
	v_pk_mul_f32 v[40:41], v[242:243], v[44:45] op_sel:[1,1] op_sel_hi:[0,1]
	v_fma_f32 v46, v242, v44, -v40
	v_fma_f32 v47, v243, v44, v41
	v_pk_mul_f32 v[52:53], v[246:247], v[30:31] op_sel:[1,1] op_sel_hi:[0,1]
	v_pk_mul_f32 v[40:41], v[42:43], v[244:245] op_sel:[1,1] op_sel_hi:[1,0]
	s_nop 0
	v_fma_f32 v44, v42, v244, -v40
	v_fma_f32 v45, v42, v245, v41
	v_mov_b64_e32 v[40:41], v[248:249]
	v_mov_b64_e32 v[42:43], v[250:251]
	v_fma_f32 v54, v246, v30, -v52
	v_fma_f32 v55, v247, v30, v53
	s_nop 0
	v_pk_mul_f32 v[30:31], v[34:35], v[40:41] op_sel:[1,1] op_sel_hi:[1,0]
	s_nop 0
	v_fma_f32 v48, v34, v40, -v30
	v_fma_f32 v49, v34, v41, v31
	v_pk_mul_f32 v[30:31], v[42:43], v[28:29] op_sel:[1,1] op_sel_hi:[0,1]
	v_fma_f32 v34, v42, v28, -v30
	v_fma_f32 v35, v43, v28, v31
	s_nop 0
	ds_write2_b64 v193, v[32:33], v[92:93] offset1:9
	ds_write2_b64 v193, v[50:51], v[46:47] offset0:18 offset1:27
	ds_write2_b64 v193, v[44:45], v[54:55] offset0:36 offset1:45
	ds_write2_b64 v193, v[48:49], v[34:35] offset0:54 offset1:63
	s_waitcnt lgkmcnt(0)
	s_barrier
; #define ZVAL(r, t) ((o == 0) ? dwl((r), (t), zw0, zw1, zw2, zb) : bf2f((r)[8 + (t)]))
; __device__ __forceinline__ void fwd_s3(c2 (&x)[8], const c2* buf, int tid) {
; #pragma unroll
;     for (int r = 0; r < 8; ++r) x[r] = buf[9 * tid + r];
;     dft8(x);
; }
; __device__ __forceinline__ void phase_conv(const Params& p, int o, unsigned char* smem, int wave) {
;     ...
;                         c2 x0[8], x1[8];
; #pragma unroll
;                         for (int r = 0; r < 4; ++r) { const int t = tid + 512 * r; x0[r] = (c2){ZVAL(raw + (2 * hh) * RAWROW, t), 0.f}; x1[r] = (c2){ZVAL(raw + (2 * hh + 1) * RAWROW, t), 0.f}; x0[4 + r] = (c2){0.f, 0.f}; x1[4 + r] = (c2){0.f, 0.f}; }
;                         fft_fwd_regs2(x0, x1, buf0, buf1, tws, tid);
; #pragma unroll
;                         for (int q = 0; q < 8; ++q) { sZ[((4 * a + 2 * hh) * 8 + q) * 512 + tid] = x0[q]; sZ[((4 * a + 2 * hh + 1) * 8 + q) * 512 + tid] = x1[q]; }
;                         __syncthreads();
;                     }
	ds_read2_b64 v[28:31], v121 offset1:1
	ds_read2_b64 v[32:35], v121 offset0:4 offset1:5
	ds_read2_b64 v[40:43], v121 offset0:2 offset1:3
	ds_read2_b64 v[44:47], v121 offset0:6 offset1:7
	s_waitcnt lgkmcnt(0)
	v_pk_add_f32 v[48:49], v[28:29], v[32:33]
	v_pk_add_f32 v[28:29], v[28:29], v[32:33] neg_lo:[0,1] neg_hi:[0,1]
	v_pk_add_f32 v[32:33], v[30:31], v[34:35]
	v_pk_add_f32 v[30:31], v[30:31], v[34:35] neg_lo:[0,1] neg_hi:[0,1]
	v_pk_add_f32 v[34:35], v[40:41], v[44:45]
	v_pk_add_f32 v[40:41], v[40:41], v[44:45] neg_lo:[0,1] neg_hi:[0,1]
	v_pk_add_f32 v[44:45], v[42:43], v[46:47]
	v_pk_add_f32 v[42:43], v[42:43], v[46:47] neg_lo:[0,1] neg_hi:[0,1]
	v_pk_add_f32 v[46:47], v[30:31], v[30:31] op_sel:[1,0]
	v_pk_add_f32 v[30:31], v[30:31], v[30:31] op_sel_hi:[1,0] neg_lo:[0,1] neg_hi:[0,1]
	s_nop 0
	v_mov_b32_e32 v47, v31
	v_xor_b32_e32 v31, 0x80000000, v40
	v_mov_b32_e32 v30, v41
	v_pk_add_f32 v[40:41], v[42:43], v[42:43] op_sel:[1,0] neg_lo:[0,1] neg_hi:[0,1]
	v_pk_add_f32 v[42:43], v[42:43], v[42:43] op_sel_hi:[1,0]
	s_nop 0
	v_mov_b32_e32 v41, v43
	v_pk_mul_f32 v[40:41], v[40:41], s[20:21]
	v_pk_add_f32 v[42:43], v[48:49], v[34:35]
	v_pk_add_f32 v[34:35], v[48:49], v[34:35] neg_lo:[0,1] neg_hi:[0,1]
	v_pk_add_f32 v[48:49], v[32:33], v[44:45]
	v_pk_add_f32 v[32:33], v[32:33], v[44:45] neg_lo:[0,1] neg_hi:[0,1]
	v_pk_add_f32 v[50:51], v[42:43], v[48:49]
	v_xor_b32_e32 v45, 0x80000000, v32
	v_mov_b32_e32 v44, v33
	v_pk_add_f32 v[48:49], v[42:43], v[48:49] neg_lo:[0,1] neg_hi:[0,1]
	v_pk_add_f32 v[32:33], v[28:29], v[30:31]
	v_pk_add_f32 v[42:43], v[28:29], v[30:31] neg_lo:[0,1] neg_hi:[0,1]
	v_pk_fma_f32 v[28:29], v[46:47], s[20:21], v[40:41] op_sel_hi:[1,0,1]
	v_pk_fma_f32 v[30:31], v[46:47], s[20:21], v[40:41] op_sel_hi:[1,0,1] neg_lo:[0,0,1] neg_hi:[0,0,1]
	v_pk_add_f32 v[52:53], v[34:35], v[44:45]
	v_pk_add_f32 v[54:55], v[34:35], v[44:45] neg_lo:[0,1] neg_hi:[0,1]
	v_xor_b32_e32 v41, 0x80000000, v30
	v_mov_b32_e32 v40, v31
	v_pk_add_f32 v[90:91], v[32:33], v[28:29]
	v_pk_add_f32 v[92:93], v[32:33], v[28:29] neg_lo:[0,1] neg_hi:[0,1]
	ds_read2_b64 v[28:31], v194 offset1:1
	ds_read2_b64 v[32:35], v195 offset1:1
	v_pk_add_f32 v[94:95], v[42:43], v[40:41]
	v_pk_add_f32 v[96:97], v[42:43], v[40:41] neg_lo:[0,1] neg_hi:[0,1]
	ds_read2_b64 v[40:43], v196 offset1:1
	ds_read2_b64 v[44:47], v197 offset1:1
	s_waitcnt lgkmcnt(0)
	v_pk_add_f32 v[98:99], v[28:29], v[32:33]
	v_pk_add_f32 v[28:29], v[28:29], v[32:33] neg_lo:[0,1] neg_hi:[0,1]
	v_pk_add_f32 v[32:33], v[30:31], v[34:35]
	v_pk_add_f32 v[30:31], v[30:31], v[34:35] neg_lo:[0,1] neg_hi:[0,1]
	v_pk_add_f32 v[34:35], v[40:41], v[44:45]
	v_pk_add_f32 v[40:41], v[40:41], v[44:45] neg_lo:[0,1] neg_hi:[0,1]
	v_pk_add_f32 v[44:45], v[42:43], v[46:47]
	v_pk_add_f32 v[42:43], v[42:43], v[46:47] neg_lo:[0,1] neg_hi:[0,1]
	v_pk_add_f32 v[46:47], v[30:31], v[30:31] op_sel:[1,0]
	v_pk_add_f32 v[30:31], v[30:31], v[30:31] op_sel_hi:[1,0] neg_lo:[0,1] neg_hi:[0,1]
	s_nop 0
	v_mov_b32_e32 v47, v31
	v_xor_b32_e32 v31, 0x80000000, v40
	v_mov_b32_e32 v30, v41
	v_pk_add_f32 v[40:41], v[42:43], v[42:43] op_sel:[1,0] neg_lo:[0,1] neg_hi:[0,1]
	v_pk_add_f32 v[42:43], v[42:43], v[42:43] op_sel_hi:[1,0]
	s_nop 0
	v_mov_b32_e32 v41, v43
	v_pk_add_f32 v[42:43], v[98:99], v[34:35]
	v_pk_add_f32 v[34:35], v[98:99], v[34:35] neg_lo:[0,1] neg_hi:[0,1]
	v_pk_add_f32 v[98:99], v[32:33], v[44:45]
	v_pk_add_f32 v[32:33], v[32:33], v[44:45] neg_lo:[0,1] neg_hi:[0,1]
	v_pk_mul_f32 v[40:41], v[40:41], s[20:21]
	v_xor_b32_e32 v45, 0x80000000, v32
	v_mov_b32_e32 v44, v33
	v_pk_add_f32 v[32:33], v[42:43], v[98:99]
	v_pk_add_f32 v[42:43], v[42:43], v[98:99] neg_lo:[0,1] neg_hi:[0,1]
	v_pk_add_f32 v[98:99], v[34:35], v[44:45]
	v_pk_add_f32 v[34:35], v[34:35], v[44:45] neg_lo:[0,1] neg_hi:[0,1]
	v_pk_add_f32 v[44:45], v[28:29], v[30:31]
	v_pk_add_f32 v[28:29], v[28:29], v[30:31] neg_lo:[0,1] neg_hi:[0,1]
	v_pk_fma_f32 v[30:31], v[46:47], s[20:21], v[40:41] op_sel_hi:[1,0,1]
	v_pk_fma_f32 v[40:41], v[46:47], s[20:21], v[40:41] op_sel_hi:[1,0,1] neg_lo:[0,0,1] neg_hi:[0,0,1]
	s_nop 0
	v_xor_b32_e32 v47, 0x80000000, v40
	v_mov_b32_e32 v46, v41
	v_pk_add_f32 v[40:41], v[44:45], v[30:31]
	v_pk_add_f32 v[30:31], v[44:45], v[30:31] neg_lo:[0,1] neg_hi:[0,1]
	v_pk_add_f32 v[44:45], v[28:29], v[46:47]
	v_pk_add_f32 v[28:29], v[28:29], v[46:47] neg_lo:[0,1] neg_hi:[0,1]
	v_add_u32_e32 v46, s7, v113
	v_ashrrev_i32_e32 v47, 31, v46
	v_lshl_add_u64 v[46:47], v[46:47], 3, s[18:19]
	global_store_dwordx2 v[46:47], v[50:51], off
	v_add_u32_e32 v46, s7, v124
	v_ashrrev_i32_e32 v47, 31, v46
	v_lshl_add_u64 v[46:47], v[46:47], 3, s[18:19]
	global_store_dwordx2 v[46:47], v[32:33], off
	v_add_u32_e32 v32, s16, v113
	v_ashrrev_i32_e32 v33, 31, v32
	v_lshl_add_u64 v[32:33], v[32:33], 3, s[18:19]
	global_store_dwordx2 v[32:33], v[90:91], off
	v_add_u32_e32 v32, s16, v124
	v_ashrrev_i32_e32 v33, 31, v32
	v_lshl_add_u64 v[32:33], v[32:33], 3, s[18:19]
	s_or_b32 s16, s7, 0x400
	global_store_dwordx2 v[32:33], v[40:41], off
	v_add_u32_e32 v32, s16, v113
	v_ashrrev_i32_e32 v33, 31, v32
	v_lshl_add_u64 v[32:33], v[32:33], 3, s[18:19]
	global_store_dwordx2 v[32:33], v[52:53], off
	v_add_u32_e32 v32, s16, v124
	v_ashrrev_i32_e32 v33, 31, v32
	v_lshl_add_u64 v[32:33], v[32:33], 3, s[18:19]
	s_or_b32 s16, s7, 0x600
	global_store_dwordx2 v[32:33], v[98:99], off
	v_add_u32_e32 v32, s16, v113
	v_ashrrev_i32_e32 v33, 31, v32
	v_lshl_add_u64 v[32:33], v[32:33], 3, s[18:19]
	global_store_dwordx2 v[32:33], v[94:95], off
	v_add_u32_e32 v32, s16, v124
	v_ashrrev_i32_e32 v33, 31, v32
	v_lshl_add_u64 v[32:33], v[32:33], 3, s[18:19]
	s_or_b32 s16, s7, 0x800
	global_store_dwordx2 v[32:33], v[44:45], off
	v_add_u32_e32 v32, s16, v113
	v_ashrrev_i32_e32 v33, 31, v32
	v_lshl_add_u64 v[32:33], v[32:33], 3, s[18:19]
	global_store_dwordx2 v[32:33], v[48:49], off
	v_add_u32_e32 v32, s16, v124
	v_ashrrev_i32_e32 v33, 31, v32
	v_lshl_add_u64 v[32:33], v[32:33], 3, s[18:19]
	s_or_b32 s16, s7, 0xa00
	global_store_dwordx2 v[32:33], v[42:43], off
	v_add_u32_e32 v32, s16, v113
	v_ashrrev_i32_e32 v33, 31, v32
	v_lshl_add_u64 v[32:33], v[32:33], 3, s[18:19]
	global_store_dwordx2 v[32:33], v[92:93], off
	v_add_u32_e32 v32, s16, v124
	v_ashrrev_i32_e32 v33, 31, v32
	v_lshl_add_u64 v[32:33], v[32:33], 3, s[18:19]
	s_or_b32 s16, s7, 0xc00
	global_store_dwordx2 v[32:33], v[30:31], off
	v_add_u32_e32 v30, s16, v113
	v_ashrrev_i32_e32 v31, 31, v30
	v_lshl_add_u64 v[30:31], v[30:31], 3, s[18:19]
	global_store_dwordx2 v[30:31], v[54:55], off
	v_add_u32_e32 v30, s16, v124
	v_ashrrev_i32_e32 v31, 31, v30
	v_lshl_add_u64 v[30:31], v[30:31], 3, s[18:19]
	s_or_b32 s7, s7, 0xe00
	global_store_dwordx2 v[30:31], v[34:35], off
	v_add_u32_e32 v30, s7, v113
	v_ashrrev_i32_e32 v31, 31, v30
	v_lshl_add_u64 v[30:31], v[30:31], 3, s[18:19]
	global_store_dwordx2 v[30:31], v[96:97], off
	v_add_u32_e32 v30, s7, v124
	v_ashrrev_i32_e32 v31, 31, v30
	v_lshl_add_u64 v[30:31], v[30:31], 3, s[18:19]
	global_store_dwordx2 v[30:31], v[28:29], off
	s_barrier
	s_cbranch_vccnz .LBB0_526

; __device__ __forceinline__ float bf2f(bf16_t b) { return __uint_as_float(((unsigned)b) << 16); }
; #define ZVAL(r, t) ((o == 0) ? dwl((r), (t), zw0, zw1, zw2, zb) : bf2f((r)[8 + (t)]))
; __device__ __forceinline__ float dwl(const bf16_t* r, int t, float w0, float w1, float w2, float b) { return w0 * bf2f(r[7 + t]) + w1 * bf2f(r[8 + t]) + w2 * bf2f(r[9 + t]) + b; }
; __device__ __forceinline__ void phase_conv(const Params& p, int o, unsigned char* smem, int wave) {
;     ...
;                         c2 x0[8], x1[8];
; #pragma unroll
;                         for (int r = 0; r < 4; ++r) { const int t = tid + 512 * r; x0[r] = (c2){ZVAL(raw + (2 * hh) * RAWROW, t), 0.f}; x1[r] = (c2){ZVAL(raw + (2 * hh + 1) * RAWROW, t), 0.f}; x0[4 + r] = (c2){0.f, 0.f}; x1[4 + r] = (c2){0.f, 0.f}; }
.LBB0_563:
	ds_read_u16 v28, v40 offset:4144
	ds_read_u16 v29, v40 offset:4146
	ds_read_u16 v31, v40 offset:4142
	s_waitcnt lgkmcnt(0)
	v_lshlrev_b32_e32 v32, 16, v28
	v_lshlrev_b32_e32 v29, 16, v29
	v_lshlrev_b32_e32 v28, 16, v31
	v_pk_mul_f32 v[28:29], v[64:65], v[28:29]
	s_nop 0
	v_fma_f32 v28, v186, v32, v28
	v_add_f32_e32 v28, v28, v29
	v_add_f32_e32 v28, v185, v28

; __device__ __forceinline__ float bf2f(bf16_t b) { return __uint_as_float(((unsigned)b) << 16); }
; #define ZVAL(r, t) ((o == 0) ? dwl((r), (t), zw0, zw1, zw2, zb) : bf2f((r)[8 + (t)]))
; __device__ __forceinline__ float dwl(const bf16_t* r, int t, float w0, float w1, float w2, float b) { return w0 * bf2f(r[7 + t]) + w1 * bf2f(r[8 + t]) + w2 * bf2f(r[9 + t]) + b; }
; __device__ __forceinline__ void phase_conv(const Params& p, int o, unsigned char* smem, int wave) {
;     ...
;                         c2 x0[8], x1[8];
; #pragma unroll
;                         for (int r = 0; r < 4; ++r) { const int t = tid + 512 * r; x0[r] = (c2){ZVAL(raw + (2 * hh) * RAWROW, t), 0.f}; x1[r] = (c2){ZVAL(raw + (2 * hh + 1) * RAWROW, t), 0.f}; x0[4 + r] = (c2){0.f, 0.f}; x1[4 + r] = (c2){0.f, 0.f}; }
.LBB0_577:
	ds_read_u16 v28, v40 offset:16
	ds_read_u16 v29, v40 offset:18
	ds_read_u16 v30, v40 offset:14
	s_waitcnt lgkmcnt(0)
	v_lshlrev_b32_e32 v31, 16, v28
	v_lshlrev_b32_e32 v29, 16, v29
	v_lshlrev_b32_e32 v28, 16, v30
	v_pk_mul_f32 v[28:29], v[64:65], v[28:29]
	s_nop 0
	v_fma_f32 v28, v186, v31, v28
	v_add_f32_e32 v28, v28, v29
	v_add_f32_e32 v30, v185, v28
	s_mov_b64 s[70:71], -1
	s_and_b64 vcc, exec, s[30:31]
	s_cbranch_vccz .LBB0_562

; __device__ __forceinline__ float bf2f(bf16_t b) { return __uint_as_float(((unsigned)b) << 16); }
; #define ZVAL(r, t) ((o == 0) ? dwl((r), (t), zw0, zw1, zw2, zb) : bf2f((r)[8 + (t)]))
; __device__ __forceinline__ float dwl(const bf16_t* r, int t, float w0, float w1, float w2, float b) { return w0 * bf2f(r[7 + t]) + w1 * bf2f(r[8 + t]) + w2 * bf2f(r[9 + t]) + b; }
; __device__ __forceinline__ void phase_conv(const Params& p, int o, unsigned char* smem, int wave) {
;     ...
;                         c2 x0[8], x1[8];
; #pragma unroll
;                         for (int r = 0; r < 4; ++r) { const int t = tid + 512 * r; x0[r] = (c2){ZVAL(raw + (2 * hh) * RAWROW, t), 0.f}; x1[r] = (c2){ZVAL(raw + (2 * hh + 1) * RAWROW, t), 0.f}; x0[4 + r] = (c2){0.f, 0.f}; x1[4 + r] = (c2){0.f, 0.f}; }
.LBB0_580:
	ds_read_u16 v29, v40 offset:1040
	ds_read_u16 v31, v40 offset:1042
	ds_read_u16 v32, v40 offset:1038
	s_waitcnt lgkmcnt(0)
	v_lshlrev_b32_e32 v29, 16, v29
	v_lshlrev_b32_e32 v33, 16, v31
	v_lshlrev_b32_e32 v32, 16, v32
	v_pk_mul_f32 v[32:33], v[64:65], v[32:33]
	s_nop 0
	v_fma_f32 v29, v186, v29, v32
	v_add_f32_e32 v29, v29, v33
	v_add_f32_e32 v31, v185, v29
	s_and_b64 vcc, exec, s[84:85]
	s_mov_b64 s[70:71], -1
	s_cbranch_vccnz .LBB0_567

; __device__ __forceinline__ float bf2f(bf16_t b) { return __uint_as_float(((unsigned)b) << 16); }
; #define ZVAL(r, t) ((o == 0) ? dwl((r), (t), zw0, zw1, zw2, zb) : bf2f((r)[8 + (t)]))
; __device__ __forceinline__ float dwl(const bf16_t* r, int t, float w0, float w1, float w2, float b) { return w0 * bf2f(r[7 + t]) + w1 * bf2f(r[8 + t]) + w2 * bf2f(r[9 + t]) + b; }
; __device__ __forceinline__ void phase_conv(const Params& p, int o, unsigned char* smem, int wave) {
;     ...
;                         c2 x0[8], x1[8];
; #pragma unroll
;                         for (int r = 0; r < 4; ++r) { const int t = tid + 512 * r; x0[r] = (c2){ZVAL(raw + (2 * hh) * RAWROW, t), 0.f}; x1[r] = (c2){ZVAL(raw + (2 * hh + 1) * RAWROW, t), 0.f}; x0[4 + r] = (c2){0.f, 0.f}; x1[4 + r] = (c2){0.f, 0.f}; }
.LBB0_582:
	ds_read_u16 v29, v40 offset:5168
	ds_read_u16 v32, v40 offset:5170
	ds_read_u16 v34, v40 offset:5166
	s_waitcnt lgkmcnt(0)
	v_lshlrev_b32_e32 v29, 16, v29
	v_lshlrev_b32_e32 v33, 16, v32
	v_lshlrev_b32_e32 v32, 16, v34
	v_pk_mul_f32 v[32:33], v[64:65], v[32:33]
	s_nop 0
	v_fma_f32 v29, v186, v29, v32
	v_add_f32_e32 v29, v29, v33
	v_add_f32_e32 v29, v185, v29
	s_and_b64 vcc, exec, s[84:85]
	s_mov_b64 s[70:71], -1
	s_cbranch_vccnz .LBB0_569

; __device__ __forceinline__ float bf2f(bf16_t b) { return __uint_as_float(((unsigned)b) << 16); }
; #define ZVAL(r, t) ((o == 0) ? dwl((r), (t), zw0, zw1, zw2, zb) : bf2f((r)[8 + (t)]))
; __device__ __forceinline__ float dwl(const bf16_t* r, int t, float w0, float w1, float w2, float b) { return w0 * bf2f(r[7 + t]) + w1 * bf2f(r[8 + t]) + w2 * bf2f(r[9 + t]) + b; }
; __device__ __forceinline__ void phase_conv(const Params& p, int o, unsigned char* smem, int wave) {
;     ...
;                         c2 x0[8], x1[8];
; #pragma unroll
;                         for (int r = 0; r < 4; ++r) { const int t = tid + 512 * r; x0[r] = (c2){ZVAL(raw + (2 * hh) * RAWROW, t), 0.f}; x1[r] = (c2){ZVAL(raw + (2 * hh + 1) * RAWROW, t), 0.f}; x0[4 + r] = (c2){0.f, 0.f}; x1[4 + r] = (c2){0.f, 0.f}; }
.LBB0_584:
	ds_read_u16 v32, v40 offset:2064
	ds_read_u16 v33, v40 offset:2066
	ds_read_u16 v34, v40 offset:2062
	s_waitcnt lgkmcnt(0)
	v_lshlrev_b32_e32 v35, 16, v32
	v_lshlrev_b32_e32 v33, 16, v33
	v_lshlrev_b32_e32 v32, 16, v34
	v_pk_mul_f32 v[32:33], v[64:65], v[32:33]
	s_nop 0
	v_fma_f32 v32, v186, v35, v32
	v_add_f32_e32 v32, v32, v33
	v_add_f32_e32 v34, v185, v32
	s_and_b64 vcc, exec, s[84:85]
	s_mov_b64 s[70:71], -1
	s_cbranch_vccnz .LBB0_571

; __device__ __forceinline__ float bf2f(bf16_t b) { return __uint_as_float(((unsigned)b) << 16); }
; #define ZVAL(r, t) ((o == 0) ? dwl((r), (t), zw0, zw1, zw2, zb) : bf2f((r)[8 + (t)]))
; __device__ __forceinline__ float dwl(const bf16_t* r, int t, float w0, float w1, float w2, float b) { return w0 * bf2f(r[7 + t]) + w1 * bf2f(r[8 + t]) + w2 * bf2f(r[9 + t]) + b; }
; __device__ __forceinline__ void phase_conv(const Params& p, int o, unsigned char* smem, int wave) {
;     ...
;                         c2 x0[8], x1[8];
; #pragma unroll
;                         for (int r = 0; r < 4; ++r) { const int t = tid + 512 * r; x0[r] = (c2){ZVAL(raw + (2 * hh) * RAWROW, t), 0.f}; x1[r] = (c2){ZVAL(raw + (2 * hh + 1) * RAWROW, t), 0.f}; x0[4 + r] = (c2){0.f, 0.f}; x1[4 + r] = (c2){0.f, 0.f}; }
.LBB0_586:
	ds_read_u16 v32, v40 offset:6192
	ds_read_u16 v33, v40 offset:6194
	ds_read_u16 v35, v40 offset:6190
	s_waitcnt lgkmcnt(0)
	v_lshlrev_b32_e32 v41, 16, v32
	v_lshlrev_b32_e32 v33, 16, v33
	v_lshlrev_b32_e32 v32, 16, v35
	v_pk_mul_f32 v[32:33], v[64:65], v[32:33]
	s_nop 0
	v_fma_f32 v32, v186, v41, v32
	v_add_f32_e32 v32, v32, v33
	v_add_f32_e32 v32, v185, v32
	s_and_b64 vcc, exec, s[84:85]
	s_mov_b64 s[70:71], -1
	s_cbranch_vccnz .LBB0_573

; __device__ __forceinline__ float bf2f(bf16_t b) { return __uint_as_float(((unsigned)b) << 16); }
; #define ZVAL(r, t) ((o == 0) ? dwl((r), (t), zw0, zw1, zw2, zb) : bf2f((r)[8 + (t)]))
; __device__ __forceinline__ float dwl(const bf16_t* r, int t, float w0, float w1, float w2, float b) { return w0 * bf2f(r[7 + t]) + w1 * bf2f(r[8 + t]) + w2 * bf2f(r[9 + t]) + b; }
; __device__ __forceinline__ void phase_conv(const Params& p, int o, unsigned char* smem, int wave) {
;     ...
;                         c2 x0[8], x1[8];
; #pragma unroll
;                         for (int r = 0; r < 4; ++r) { const int t = tid + 512 * r; x0[r] = (c2){ZVAL(raw + (2 * hh) * RAWROW, t), 0.f}; x1[r] = (c2){ZVAL(raw + (2 * hh + 1) * RAWROW, t), 0.f}; x0[4 + r] = (c2){0.f, 0.f}; x1[4 + r] = (c2){0.f, 0.f}; }
.LBB0_588:
	ds_read_u16 v33, v40 offset:3088
	ds_read_u16 v35, v40 offset:3090
	ds_read_u16 v41, v40 offset:3086
	s_waitcnt lgkmcnt(0)
	v_lshlrev_b32_e32 v33, 16, v33
	v_lshlrev_b32_e32 v43, 16, v35
	v_lshlrev_b32_e32 v42, 16, v41
	v_pk_mul_f32 v[42:43], v[64:65], v[42:43]
	s_nop 0
	v_fma_f32 v33, v186, v33, v42
	v_add_f32_e32 v33, v33, v43
	v_add_f32_e32 v35, v185, v33
	s_and_b64 vcc, exec, s[84:85]
	s_mov_b64 s[70:71], -1
	s_cbranch_vccnz .LBB0_575

; __device__ __forceinline__ float bf2f(bf16_t b) { return __uint_as_float(((unsigned)b) << 16); }
; #define ZVAL(r, t) ((o == 0) ? dwl((r), (t), zw0, zw1, zw2, zb) : bf2f((r)[8 + (t)]))
; __device__ __forceinline__ float dwl(const bf16_t* r, int t, float w0, float w1, float w2, float b) { return w0 * bf2f(r[7 + t]) + w1 * bf2f(r[8 + t]) + w2 * bf2f(r[9 + t]) + b; }
; __device__ __forceinline__ void phase_conv(const Params& p, int o, unsigned char* smem, int wave) {
;     ...
;                         c2 x0[8], x1[8];
; #pragma unroll
;                         for (int r = 0; r < 4; ++r) { const int t = tid + 512 * r; x0[r] = (c2){ZVAL(raw + (2 * hh) * RAWROW, t), 0.f}; x1[r] = (c2){ZVAL(raw + (2 * hh + 1) * RAWROW, t), 0.f}; x0[4 + r] = (c2){0.f, 0.f}; x1[4 + r] = (c2){0.f, 0.f}; }
.LBB0_590:
	ds_read_u16 v33, v40 offset:7216
	ds_read_u16 v41, v40 offset:7218
	ds_read_u16 v40, v40 offset:7214
	s_waitcnt lgkmcnt(0)
	v_lshlrev_b32_e32 v33, 16, v33
	v_lshlrev_b32_e32 v41, 16, v41
	v_lshlrev_b32_e32 v40, 16, v40
	v_pk_mul_f32 v[40:41], v[64:65], v[40:41]
	s_nop 0
	v_fma_f32 v33, v186, v33, v40
	v_add_f32_e32 v33, v33, v41
	v_add_f32_e32 v33, v185, v33
	s_branch .LBB0_558

; __device__ __forceinline__ c2 mpi(c2 a) { return (c2){-a.y, a.x}; }
; __device__ __forceinline__ void idft8(c2 (&x)[8]) {
;     const float s = 0.70710678118654752f;
;     const c2 a0 = x[0] + x[4], a4 = x[0] - x[4], a1 = x[1] + x[5], a5 = x[1] - x[5], a2 = x[2] + x[6], a6 = x[2] - x[6], a3 = x[3] + x[7], a7 = x[3] - x[7];
;     const c2 a5w = (c2){(a5.x - a5.y) * s, (a5.x + a5.y) * s};
;     const c2 a6w = mpi(a6);
;     const c2 a7w = (c2){-(a7.x + a7.y) * s, (a7.x - a7.y) * s};
;     const c2 b0 = a0 + a2, b1 = a0 - a2, b2 = a1 + a3, b3 = mpi(a1 - a3);
;     x[0] = b0 + b2; x[4] = b0 - b2; x[2] = b1 + b3; x[6] = b1 - b3;
;     const c2 c0 = a4 + a6w, c1 = a4 - a6w, c2_ = a5w + a7w, c3 = mpi(a5w - a7w);
;     x[1] = c0 + c2_; x[5] = c0 - c2_; x[3] = c1 + c3; x[7] = c1 - c3;
.LBB0_602:
	v_pk_mul_f32 v[20:21], v[26:27], s[20:21] op_sel_hi:[1,0]
	v_pk_add_f32 v[16:17], v[16:17], v[28:29] neg_lo:[0,1] neg_hi:[0,1]
	v_pk_add_f32 v[20:21], v[20:21], v[30:31] neg_lo:[0,1] neg_hi:[0,1]
	s_mov_b64 s[62:63], 0
	v_xor_b32_e32 v22, 0x80000000, v21
	v_mov_b32_e32 v23, v20
	v_pk_add_f32 v[16:17], v[16:17], v[22:23]
	ds_read_u16 v20, v174 offset:14
	ds_read_u16 v21, v174 offset:16
	ds_read_u16 v22, v174 offset:18
	ds_read_u16 v23, v175 offset:14
	ds_read_u16 v24, v175 offset:16
	ds_read_u16 v25, v175 offset:18
	s_waitcnt lgkmcnt(0)
	v_lshlrev_b32_e32 v21, 16, v21
	v_lshlrev_b32_e32 v20, 16, v20
	v_mul_f32_e32 v21, v190, v21
	v_fmac_f32_e32 v21, v187, v20
	v_lshlrev_b32_e32 v20, 16, v22
	v_pk_mul_f32 v[16:17], v[66:67], v[16:17]
	v_fmac_f32_e32 v21, v189, v20
	v_lshlrev_b32_e32 v22, 16, v24
	v_add_f32_e32 v20, v188, v21
	v_lshlrev_b32_e32 v21, 16, v23
	v_mul_f32_e32 v22, v190, v22
	v_fma_f32 v16, v184, v18, v16
	v_fmac_f32_e32 v22, v187, v21
	v_lshlrev_b32_e32 v21, 16, v25
	v_mul_f32_e32 v16, v16, v20
	v_add_u32_e32 v20, s7, v133
	v_fmac_f32_e32 v22, v189, v21
	v_ashrrev_i32_e32 v21, 31, v20
	v_add_f32_e32 v22, v188, v22
	v_cvt_pk_bf16_f32 v16, v16, s0
	v_lshl_add_u64 v[20:21], v[20:21], 1, s[50:51]
	v_fmac_f32_e32 v17, v184, v19
	global_store_short v[20:21], v16, off
	v_mul_f32_e32 v16, v17, v22
	v_cvt_pk_bf16_f32 v18, v16, s0
	v_add_u32_e32 v16, s3, v133
	v_ashrrev_i32_e32 v17, 31, v16
	v_lshl_add_u64 v[16:17], v[16:17], 1, s[50:51]
	s_movk_i32 s3, 0x2000
	s_and_b64 vcc, exec, s[60:61]
	global_store_short v[16:17], v18, off
	s_cbranch_vccnz .LBB0_215

; __device__ __forceinline__ c2 cmulc(c2 a, c2 b) { return (c2){a.x * b.x + a.y * b.y, a.y * b.x - a.x * b.y}; }
; __device__ __forceinline__ void inv_s0(c2 (&x)[8], const c2* buf, const c2* tws, int tid) {
;     const c2* bp_ = buf + LP(tid);
; #pragma unroll
;     for (int r = 0; r < 8; ++r) { c2 v = bp_[576 * r]; if (r) v = cmulc(v, tws[(r - 1) * 512 + tid]); x[r] = v; }
;     idft8(x);
; }
.LBB0_637:
	ds_read_u16 v96, v145 offset:16
	ds_read_u16 v97, v145 offset:18
	ds_read_u16 v98, v145 offset:14
	s_waitcnt lgkmcnt(0)
	v_lshlrev_b32_e32 v99, 16, v96
	v_lshlrev_b32_e32 v97, 16, v97
	v_lshlrev_b32_e32 v96, 16, v98
	v_pk_mul_f32 v[96:97], v[64:65], v[96:97]
	s_nop 0
	v_fma_f32 v96, v186, v99, v96
	v_add_f32_e32 v96, v96, v97
	v_add_f32_e32 v203, v185, v96
.LBB0_638:
	s_waitcnt lgkmcnt(0)
	v_pk_mul_f32 v[98:99], v[42:43], v[28:29] op_sel:[0,1]
	s_or_b32 s16, s3, 0x10000
	v_fma_f32 v96, v42, v28, v99
	v_fma_f32 v97, v43, v28, -v98
	s_or_b32 s7, s3, 0x10800
	v_pk_mul_f32 v[42:43], v[52:53], v[30:31] op_sel:[0,1]
	s_mov_b64 s[62:63], -1
	v_fma_f32 v98, v52, v30, v43
	v_fma_f32 v99, v53, v30, -v42
	s_and_b64 vcc, exec, s[84:85]
	v_pk_mul_f32 v[42:43], v[54:55], v[24:25] op_sel:[0,1]
	s_nop 0
	v_fma_f32 v52, v54, v24, v43
	v_fma_f32 v53, v55, v24, -v42
	s_nop 0
	v_pk_mul_f32 v[42:43], v[48:49], v[26:27] op_sel:[0,1]
	s_nop 0
	v_fma_f32 v54, v48, v26, v43
	v_fma_f32 v55, v49, v26, -v42
	s_nop 0
	v_pk_mul_f32 v[42:43], v[50:51], v[20:21] op_sel:[0,1]
	s_nop 0
	v_fma_f32 v100, v50, v20, v43
	v_fma_f32 v101, v51, v20, -v42
	s_nop 0
	v_pk_mul_f32 v[42:43], v[44:45], v[22:23] op_sel:[0,1]
	s_nop 0
	v_fma_f32 v50, v44, v22, v43
	v_fma_f32 v51, v45, v22, -v42
	v_pk_add_f32 v[44:45], v[96:97], v[100:101]
	v_pk_mul_f32 v[42:43], v[46:47], v[90:91] op_sel:[0,1]
	s_nop 0
	v_fma_f32 v102, v46, v90, v43
	v_fma_f32 v103, v47, v90, -v42
	v_pk_add_f32 v[46:47], v[98:99], v[50:51]
	v_pk_add_f32 v[42:43], v[40:41], v[54:55]
	v_pk_add_f32 v[48:49], v[52:53], v[102:103]
	v_pk_add_f32 v[204:205], v[42:43], v[46:47]
	v_pk_add_f32 v[206:207], v[44:45], v[48:49]
	s_nop 0
	v_pk_add_f32 v[204:205], v[204:205], v[206:207]
	ds_read_u16 v206, v160 offset:14
	ds_read_u16 v207, v160 offset:16
	ds_read_u16 v208, v160 offset:18
	v_pk_mul_f32 v[204:205], v[66:67], v[204:205]
	s_waitcnt lgkmcnt(0)
	v_lshlrev_b32_e32 v206, 16, v206
	v_lshlrev_b32_e32 v207, 16, v207
	v_mul_f32_e32 v207, v190, v207
	v_fmac_f32_e32 v207, v187, v206
	v_lshlrev_b32_e32 v206, 16, v208
	v_fmac_f32_e32 v207, v189, v206
	v_add_f32_e32 v206, v188, v207
	ds_read_u16 v207, v161 offset:14
	ds_read_u16 v208, v161 offset:16
	ds_read_u16 v209, v161 offset:18
	v_fma_f32 v202, v184, v202, v204
	v_mul_f32_e32 v202, v202, v206
	s_waitcnt lgkmcnt(0)
	v_lshlrev_b32_e32 v207, 16, v207
	v_lshlrev_b32_e32 v208, 16, v208
	v_mul_f32_e32 v208, v190, v208
	v_fmac_f32_e32 v208, v187, v207
	v_lshlrev_b32_e32 v207, 16, v209
	v_add_u32_e32 v206, s16, v113
	v_fmac_f32_e32 v208, v189, v207
	v_ashrrev_i32_e32 v207, 31, v206
	v_add_f32_e32 v208, v188, v208
	v_cvt_pk_bf16_f32 v202, v202, s0
	v_lshl_add_u64 v[206:207], v[206:207], 1, s[50:51]
	v_fmac_f32_e32 v205, v184, v203
	global_store_short v[206:207], v202, off
	v_mul_f32_e32 v202, v205, v208
	v_cvt_pk_bf16_f32 v204, v202, s0
	v_add_u32_e32 v202, s7, v113
	v_ashrrev_i32_e32 v203, 31, v202
	v_lshl_add_u64 v[202:203], v[202:203], 1, s[50:51]
	global_store_short v[202:203], v204, off
	s_cbranch_vccz .LBB0_677
	s_andn2_b64 vcc, exec, s[62:63]
	s_cbranch_vccz .LBB0_678

; __device__ __forceinline__ c2 mpi(c2 a) { return (c2){-a.y, a.x}; }
; __device__ __forceinline__ void idft8(c2 (&x)[8]) {
;     const float s = 0.70710678118654752f;
;     const c2 a0 = x[0] + x[4], a4 = x[0] - x[4], a1 = x[1] + x[5], a5 = x[1] - x[5], a2 = x[2] + x[6], a6 = x[2] - x[6], a3 = x[3] + x[7], a7 = x[3] - x[7];
;     const c2 a5w = (c2){(a5.x - a5.y) * s, (a5.x + a5.y) * s};
;     const c2 a6w = mpi(a6);
;     const c2 a7w = (c2){-(a7.x + a7.y) * s, (a7.x - a7.y) * s};
;     const c2 b0 = a0 + a2, b1 = a0 - a2, b2 = a1 + a3, b3 = mpi(a1 - a3);
;     x[0] = b0 + b2; x[4] = b0 - b2; x[2] = b1 + b3; x[6] = b1 - b3;
;     const c2 c0 = a4 + a6w, c1 = a4 - a6w, c2_ = a5w + a7w, c3 = mpi(a5w - a7w);
;     x[1] = c0 + c2_; x[5] = c0 - c2_; x[3] = c1 + c3; x[7] = c1 - c3;
.LBB0_642:
	ds_read_u16 v203, v149 offset:16
	ds_read_u16 v204, v149 offset:18
	ds_read_u16 v206, v149 offset:14
	s_waitcnt lgkmcnt(0)
	v_lshlrev_b32_e32 v203, 16, v203
	v_lshlrev_b32_e32 v205, 16, v204
	v_lshlrev_b32_e32 v204, 16, v206
	v_pk_mul_f32 v[204:205], v[64:65], v[204:205]
	s_nop 0
	v_fma_f32 v203, v186, v203, v204
	v_add_f32_e32 v203, v203, v205
	v_add_f32_e32 v203, v185, v203
.LBB0_643:
	v_pk_add_f32 v[40:41], v[40:41], v[54:55] neg_lo:[0,1] neg_hi:[0,1]
	v_pk_add_f32 v[54:55], v[96:97], v[100:101] neg_lo:[0,1] neg_hi:[0,1]
	v_pk_add_f32 v[96:97], v[98:99], v[50:51] neg_lo:[0,1] neg_hi:[0,1]
	v_pk_add_f32 v[98:99], v[52:53], v[102:103] neg_lo:[0,1] neg_hi:[0,1]
	v_pk_add_f32 v[50:51], v[54:55], v[54:55] op_sel:[0,1] neg_lo:[0,1] neg_hi:[0,1]
	v_pk_add_f32 v[52:53], v[54:55], v[54:55] op_sel_hi:[0,1]
	v_mov_b32_e32 v51, v53
	v_xor_b32_e32 v52, 0x80000000, v97
	v_mov_b32_e32 v53, v96
	v_pk_add_f32 v[54:55], v[98:99], v[98:99] op_sel:[0,1]
	v_pk_add_f32 v[96:97], v[98:99], v[98:99] op_sel_hi:[0,1] neg_lo:[0,1] neg_hi:[0,1]
	v_mov_b32_e32 v55, v97
	s_mov_b32 s40, s21
	s_mov_b32 s41, s20
	v_pk_mul_f32 v[54:55], v[54:55], s[40:41]
	v_pk_add_f32 v[96:97], v[40:41], v[52:53]
	v_pk_fma_f32 v[98:99], v[50:51], s[20:21], v[54:55] op_sel_hi:[1,0,1]
	s_and_b64 vcc, exec, s[84:85]
	v_pk_add_f32 v[96:97], v[96:97], v[98:99]
	ds_read_u16 v98, v162 offset:14
	ds_read_u16 v99, v162 offset:16
	ds_read_u16 v100, v162 offset:18
	ds_read_u16 v101, v163 offset:14
	ds_read_u16 v102, v163 offset:16
	ds_read_u16 v103, v163 offset:18
	s_waitcnt lgkmcnt(0)
	v_lshlrev_b32_e32 v99, 16, v99
	v_lshlrev_b32_e32 v98, 16, v98
	v_mul_f32_e32 v99, v190, v99
	v_fmac_f32_e32 v99, v187, v98
	v_lshlrev_b32_e32 v98, 16, v100
	v_pk_mul_f32 v[96:97], v[66:67], v[96:97]
	v_fmac_f32_e32 v99, v189, v98
	v_lshlrev_b32_e32 v100, 16, v102
	v_add_f32_e32 v98, v188, v99
	v_lshlrev_b32_e32 v99, 16, v101
	v_mul_f32_e32 v100, v190, v100
	v_fma_f32 v96, v184, v202, v96
	v_fmac_f32_e32 v100, v187, v99
	v_lshlrev_b32_e32 v99, 16, v103
	v_mul_f32_e32 v96, v96, v98
	v_add_u32_e32 v98, s16, v127
	v_fmac_f32_e32 v100, v189, v99
	v_ashrrev_i32_e32 v99, 31, v98
	v_add_f32_e32 v100, v188, v100
	v_cvt_pk_bf16_f32 v96, v96, s0
	v_lshl_add_u64 v[98:99], v[98:99], 1, s[50:51]
	v_fmac_f32_e32 v97, v184, v203
	global_store_short v[98:99], v96, off
	v_mul_f32_e32 v96, v97, v100
	v_cvt_pk_bf16_f32 v98, v96, s0
	v_add_u32_e32 v96, s7, v127
	v_ashrrev_i32_e32 v97, 31, v96
	v_lshl_add_u64 v[96:97], v[96:97], 1, s[50:51]
	s_mov_b64 s[62:63], -1
	global_store_short v[96:97], v98, off
	s_cbranch_vccz .LBB0_680
	s_andn2_b64 vcc, exec, s[62:63]
	s_cbranch_vccz .LBB0_681

; __device__ __forceinline__ c2 mpi(c2 a) { return (c2){-a.y, a.x}; }
; __device__ __forceinline__ void idft8(c2 (&x)[8]) {
;     const float s = 0.70710678118654752f;
;     const c2 a0 = x[0] + x[4], a4 = x[0] - x[4], a1 = x[1] + x[5], a5 = x[1] - x[5], a2 = x[2] + x[6], a6 = x[2] - x[6], a3 = x[3] + x[7], a7 = x[3] - x[7];
;     const c2 a5w = (c2){(a5.x - a5.y) * s, (a5.x + a5.y) * s};
;     const c2 a6w = mpi(a6);
;     const c2 a7w = (c2){-(a7.x + a7.y) * s, (a7.x - a7.y) * s};
;     const c2 b0 = a0 + a2, b1 = a0 - a2, b2 = a1 + a3, b3 = mpi(a1 - a3);
;     x[0] = b0 + b2; x[4] = b0 - b2; x[2] = b1 + b3; x[6] = b1 - b3;
;     const c2 c0 = a4 + a6w, c1 = a4 - a6w, c2_ = a5w + a7w, c3 = mpi(a5w - a7w);
;     x[1] = c0 + c2_; x[5] = c0 - c2_; x[3] = c1 + c3; x[7] = c1 - c3;
.LBB0_647:
	ds_read_u16 v97, v153 offset:16
	ds_read_u16 v98, v153 offset:18
	ds_read_u16 v100, v153 offset:14
	s_waitcnt lgkmcnt(0)
	v_lshlrev_b32_e32 v97, 16, v97
	v_lshlrev_b32_e32 v99, 16, v98
	v_lshlrev_b32_e32 v98, 16, v100
	v_pk_mul_f32 v[98:99], v[64:65], v[98:99]
	s_nop 0
	v_fma_f32 v97, v186, v97, v98
	v_add_f32_e32 v97, v97, v99
	v_add_f32_e32 v97, v185, v97
.LBB0_648:
	v_pk_add_f32 v[44:45], v[44:45], v[48:49] neg_lo:[0,1] neg_hi:[0,1]
	v_pk_add_f32 v[42:43], v[42:43], v[46:47] neg_lo:[0,1] neg_hi:[0,1]
	v_xor_b32_e32 v46, 0x80000000, v45
	v_mov_b32_e32 v47, v44
	v_pk_add_f32 v[42:43], v[42:43], v[46:47]
	ds_read_u16 v44, v164 offset:14
	ds_read_u16 v45, v164 offset:16
	ds_read_u16 v46, v164 offset:18
	ds_read_u16 v47, v165 offset:14
	ds_read_u16 v48, v165 offset:16
	ds_read_u16 v49, v165 offset:18
	s_waitcnt lgkmcnt(0)
	v_lshlrev_b32_e32 v45, 16, v45
	v_lshlrev_b32_e32 v44, 16, v44
	v_mul_f32_e32 v45, v190, v45
	v_fmac_f32_e32 v45, v187, v44
	v_lshlrev_b32_e32 v44, 16, v46
	v_pk_mul_f32 v[42:43], v[66:67], v[42:43]
	v_fmac_f32_e32 v45, v189, v44
	v_lshlrev_b32_e32 v46, 16, v48
	v_add_f32_e32 v44, v188, v45
	v_lshlrev_b32_e32 v45, 16, v47
	v_mul_f32_e32 v46, v190, v46
	v_fma_f32 v42, v184, v96, v42
	v_fmac_f32_e32 v46, v187, v45
	v_lshlrev_b32_e32 v45, 16, v49
	v_mul_f32_e32 v42, v42, v44
	v_add_u32_e32 v44, s16, v130
	v_fmac_f32_e32 v46, v189, v45
	v_ashrrev_i32_e32 v45, 31, v44
	v_add_f32_e32 v46, v188, v46
	v_cvt_pk_bf16_f32 v42, v42, s0
	v_lshl_add_u64 v[44:45], v[44:45], 1, s[50:51]
	v_fmac_f32_e32 v43, v184, v97
	global_store_short v[44:45], v42, off
	v_mul_f32_e32 v42, v43, v46
	v_cvt_pk_bf16_f32 v44, v42, s0
	v_add_u32_e32 v42, s7, v130
	v_ashrrev_i32_e32 v43, 31, v42
	v_lshl_add_u64 v[42:43], v[42:43], 1, s[50:51]
	s_and_b64 vcc, exec, s[84:85]
	s_mov_b64 s[62:63], -1
	global_store_short v[42:43], v44, off
	s_cbranch_vccz .LBB0_683
	s_andn2_b64 vcc, exec, s[62:63]
	s_cbranch_vccz .LBB0_684

; __device__ __forceinline__ c2 mpi(c2 a) { return (c2){-a.y, a.x}; }
; __device__ __forceinline__ void idft8(c2 (&x)[8]) {
;     const float s = 0.70710678118654752f;
;     const c2 a0 = x[0] + x[4], a4 = x[0] - x[4], a1 = x[1] + x[5], a5 = x[1] - x[5], a2 = x[2] + x[6], a6 = x[2] - x[6], a3 = x[3] + x[7], a7 = x[3] - x[7];
;     const c2 a5w = (c2){(a5.x - a5.y) * s, (a5.x + a5.y) * s};
;     const c2 a6w = mpi(a6);
;     const c2 a7w = (c2){-(a7.x + a7.y) * s, (a7.x - a7.y) * s};
;     const c2 b0 = a0 + a2, b1 = a0 - a2, b2 = a1 + a3, b3 = mpi(a1 - a3);
;     x[0] = b0 + b2; x[4] = b0 - b2; x[2] = b1 + b3; x[6] = b1 - b3;
;     const c2 c0 = a4 + a6w, c1 = a4 - a6w, c2_ = a5w + a7w, c3 = mpi(a5w - a7w);
;     x[1] = c0 + c2_; x[5] = c0 - c2_; x[3] = c1 + c3; x[7] = c1 - c3;
.LBB0_652:
	ds_read_u16 v43, v157 offset:16
	ds_read_u16 v44, v157 offset:18
	ds_read_u16 v46, v157 offset:14
	s_waitcnt lgkmcnt(0)
	v_lshlrev_b32_e32 v43, 16, v43
	v_lshlrev_b32_e32 v45, 16, v44
	v_lshlrev_b32_e32 v44, 16, v46
	v_pk_mul_f32 v[44:45], v[64:65], v[44:45]
	s_nop 0
	v_fma_f32 v43, v186, v43, v44
	v_add_f32_e32 v43, v43, v45
	v_add_f32_e32 v43, v185, v43
.LBB0_653:
	v_pk_mul_f32 v[44:45], v[50:51], s[20:21] op_sel_hi:[1,0]
	v_pk_add_f32 v[40:41], v[40:41], v[52:53] neg_lo:[0,1] neg_hi:[0,1]
	v_pk_add_f32 v[44:45], v[44:45], v[54:55] neg_lo:[0,1] neg_hi:[0,1]
	s_mov_b64 s[62:63], -1
	v_xor_b32_e32 v46, 0x80000000, v45
	v_mov_b32_e32 v47, v44
	v_pk_add_f32 v[40:41], v[40:41], v[46:47]
	ds_read_u16 v44, v166 offset:14
	ds_read_u16 v45, v166 offset:16
	ds_read_u16 v46, v166 offset:18
	ds_read_u16 v47, v167 offset:14
	ds_read_u16 v48, v167 offset:16
	ds_read_u16 v49, v167 offset:18
	s_waitcnt lgkmcnt(0)
	v_lshlrev_b32_e32 v45, 16, v45
	v_lshlrev_b32_e32 v44, 16, v44
	v_mul_f32_e32 v45, v190, v45
	v_fmac_f32_e32 v45, v187, v44
	v_lshlrev_b32_e32 v44, 16, v46
	v_pk_mul_f32 v[40:41], v[66:67], v[40:41]
	v_fmac_f32_e32 v45, v189, v44
	v_lshlrev_b32_e32 v46, 16, v48
	v_add_f32_e32 v44, v188, v45
	v_lshlrev_b32_e32 v45, 16, v47
	v_mul_f32_e32 v46, v190, v46
	v_fma_f32 v40, v184, v42, v40
	v_fmac_f32_e32 v46, v187, v45
	v_lshlrev_b32_e32 v45, 16, v49
	v_mul_f32_e32 v40, v40, v44
	v_add_u32_e32 v44, s16, v133
	v_fmac_f32_e32 v46, v189, v45
	v_ashrrev_i32_e32 v45, 31, v44
	v_add_f32_e32 v46, v188, v46
	v_cvt_pk_bf16_f32 v40, v40, s0
	v_lshl_add_u64 v[44:45], v[44:45], 1, s[50:51]
	v_fmac_f32_e32 v41, v184, v43
	global_store_short v[44:45], v40, off
	v_mul_f32_e32 v40, v41, v46
	v_cvt_pk_bf16_f32 v42, v40, s0
	v_add_u32_e32 v40, s7, v133
	v_ashrrev_i32_e32 v41, 31, v40
	v_lshl_add_u64 v[40:41], v[40:41], 1, s[50:51]
	s_and_b64 vcc, exec, s[30:31]
	global_store_short v[40:41], v42, off
	s_cbranch_vccnz .LBB0_686
	s_andn2_b64 vcc, exec, s[62:63]
	s_cbranch_vccz .LBB0_687

; __device__ __forceinline__ c2 cmulc(c2 a, c2 b) { return (c2){a.x * b.x + a.y * b.y, a.y * b.x - a.x * b.y}; }
; __device__ __forceinline__ void inv_s0(c2 (&x)[8], const c2* buf, const c2* tws, int tid) {
;     const c2* bp_ = buf + LP(tid);
; #pragma unroll
;     for (int r = 0; r < 8; ++r) { c2 v = bp_[576 * r]; if (r) v = cmulc(v, tws[(r - 1) * 512 + tid]); x[r] = v; }
;     idft8(x);
; }
.LBB0_657:
	ds_read_u16 v41, v147 offset:16
	ds_read_u16 v42, v147 offset:18
	ds_read_u16 v44, v147 offset:14
	s_waitcnt lgkmcnt(0)
	v_lshlrev_b32_e32 v41, 16, v41
	v_lshlrev_b32_e32 v43, 16, v42
	v_lshlrev_b32_e32 v42, 16, v44
	v_pk_mul_f32 v[42:43], v[64:65], v[42:43]
	s_nop 0
	v_fma_f32 v41, v186, v41, v42
	v_add_f32_e32 v41, v41, v43
	v_add_f32_e32 v41, v185, v41
.LBB0_658:
	v_mov_b32_e32 v42, v28
	v_mov_b32_e32 v43, v28
	v_mov_b32_e32 v28, v29
	v_pk_mul_f32 v[96:97], v[28:29], v[18:19]
	v_mov_b32_e32 v44, v30
	v_mov_b32_e32 v45, v30
	v_mov_b32_e32 v30, v31
	v_fma_f32 v28, v42, v18, v97
	v_fma_f32 v29, v43, v19, -v96
	v_mov_b32_e32 v46, v24
	v_pk_mul_f32 v[18:19], v[30:31], v[36:37]
	v_mov_b32_e32 v47, v24
	v_mov_b32_e32 v24, v25
	v_fma_f32 v30, v44, v36, v19
	v_fma_f32 v31, v45, v37, -v18
	v_mov_b32_e32 v48, v26
	v_pk_mul_f32 v[18:19], v[24:25], v[38:39]
	v_mov_b32_e32 v49, v26
	v_mov_b32_e32 v26, v27
	v_fma_f32 v36, v46, v38, v19
	v_fma_f32 v37, v47, v39, -v18
	v_mov_b32_e32 v50, v20
	v_pk_mul_f32 v[18:19], v[26:27], v[32:33]
	v_mov_b32_e32 v51, v20
	v_mov_b32_e32 v20, v21
	v_fma_f32 v26, v48, v32, v19
	v_fma_f32 v27, v49, v33, -v18
	v_mov_b32_e32 v52, v22
	v_pk_mul_f32 v[18:19], v[20:21], v[34:35]
	v_mov_b32_e32 v53, v22
	v_mov_b32_e32 v22, v23
	v_fma_f32 v32, v50, v34, v19
	v_fma_f32 v33, v51, v35, -v18
	v_mov_b32_e32 v54, v90
	v_pk_mul_f32 v[18:19], v[22:23], v[94:95]
	v_mov_b32_e32 v55, v90
	v_mov_b32_e32 v90, v91
	v_fma_f32 v34, v52, v94, v19
	v_fma_f32 v35, v53, v95, -v18
	v_pk_add_f32 v[20:21], v[28:29], v[32:33]
	v_pk_mul_f32 v[18:19], v[90:91], v[92:93]
	v_pk_add_f32 v[22:23], v[30:31], v[34:35]
	v_fma_f32 v38, v54, v92, v19
	v_fma_f32 v39, v55, v93, -v18
	s_or_b32 s7, s3, 0x11000
	v_pk_add_f32 v[18:19], v[16:17], v[26:27]
	v_pk_add_f32 v[24:25], v[36:37], v[38:39]
	v_pk_add_f32 v[42:43], v[18:19], v[22:23]
	v_pk_add_f32 v[44:45], v[20:21], v[24:25]
	s_or_b32 s3, s3, 0x11800
	v_pk_add_f32 v[42:43], v[42:43], v[44:45]
	ds_read_u16 v44, v168 offset:14
	ds_read_u16 v45, v168 offset:16
	ds_read_u16 v46, v168 offset:18
	ds_read_u16 v47, v169 offset:14
	ds_read_u16 v48, v169 offset:16
	ds_read_u16 v49, v169 offset:18
	s_waitcnt lgkmcnt(0)
	v_lshlrev_b32_e32 v45, 16, v45
	v_lshlrev_b32_e32 v44, 16, v44
	v_mul_f32_e32 v45, v190, v45
	v_fmac_f32_e32 v45, v187, v44
	v_lshlrev_b32_e32 v44, 16, v46
	v_pk_mul_f32 v[42:43], v[66:67], v[42:43]
	v_fmac_f32_e32 v45, v189, v44
	v_lshlrev_b32_e32 v46, 16, v48
	v_add_f32_e32 v44, v188, v45
	v_lshlrev_b32_e32 v45, 16, v47
	v_mul_f32_e32 v46, v190, v46
	v_fma_f32 v40, v184, v40, v42
	v_fmac_f32_e32 v46, v187, v45
	v_lshlrev_b32_e32 v45, 16, v49
	v_mul_f32_e32 v40, v40, v44
	v_add_u32_e32 v44, s7, v113
	v_fmac_f32_e32 v46, v189, v45
	v_ashrrev_i32_e32 v45, 31, v44
	v_add_f32_e32 v46, v188, v46
	v_cvt_pk_bf16_f32 v40, v40, s0
	v_lshl_add_u64 v[44:45], v[44:45], 1, s[50:51]
	v_fmac_f32_e32 v43, v184, v41
	global_store_short v[44:45], v40, off
	v_mul_f32_e32 v40, v43, v46
	v_cvt_pk_bf16_f32 v42, v40, s0
	v_add_u32_e32 v40, s3, v113
	v_ashrrev_i32_e32 v41, 31, v40
	v_lshl_add_u64 v[40:41], v[40:41], 1, s[50:51]
	s_and_b64 vcc, exec, s[84:85]
	s_mov_b64 s[62:63], -1
	global_store_short v[40:41], v42, off
	s_cbranch_vccz .LBB0_689
	s_andn2_b64 vcc, exec, s[62:63]
	s_cbranch_vccz .LBB0_690

; __device__ __forceinline__ c2 mpi(c2 a) { return (c2){-a.y, a.x}; }
; __device__ __forceinline__ void idft8(c2 (&x)[8]) {
;     const float s = 0.70710678118654752f;
;     const c2 a0 = x[0] + x[4], a4 = x[0] - x[4], a1 = x[1] + x[5], a5 = x[1] - x[5], a2 = x[2] + x[6], a6 = x[2] - x[6], a3 = x[3] + x[7], a7 = x[3] - x[7];
;     const c2 a5w = (c2){(a5.x - a5.y) * s, (a5.x + a5.y) * s};
;     const c2 a6w = mpi(a6);
;     const c2 a7w = (c2){-(a7.x + a7.y) * s, (a7.x - a7.y) * s};
;     const c2 b0 = a0 + a2, b1 = a0 - a2, b2 = a1 + a3, b3 = mpi(a1 - a3);
;     x[0] = b0 + b2; x[4] = b0 - b2; x[2] = b1 + b3; x[6] = b1 - b3;
;     const c2 c0 = a4 + a6w, c1 = a4 - a6w, c2_ = a5w + a7w, c3 = mpi(a5w - a7w);
;     x[1] = c0 + c2_; x[5] = c0 - c2_; x[3] = c1 + c3; x[7] = c1 - c3;
.LBB0_662:
	ds_read_u16 v41, v151 offset:16
	ds_read_u16 v42, v151 offset:18
	ds_read_u16 v44, v151 offset:14
	s_waitcnt lgkmcnt(0)
	v_lshlrev_b32_e32 v41, 16, v41
	v_lshlrev_b32_e32 v43, 16, v42
	v_lshlrev_b32_e32 v42, 16, v44
	v_pk_mul_f32 v[42:43], v[64:65], v[42:43]
	s_nop 0
	v_fma_f32 v41, v186, v41, v42
	v_add_f32_e32 v41, v41, v43
	v_add_f32_e32 v41, v185, v41
.LBB0_663:
	v_pk_add_f32 v[28:29], v[28:29], v[32:33] neg_lo:[0,1] neg_hi:[0,1]
	v_pk_add_f32 v[16:17], v[16:17], v[26:27] neg_lo:[0,1] neg_hi:[0,1]
	v_pk_add_f32 v[30:31], v[30:31], v[34:35] neg_lo:[0,1] neg_hi:[0,1]
	v_pk_add_f32 v[32:33], v[36:37], v[38:39] neg_lo:[0,1] neg_hi:[0,1]
	v_pk_add_f32 v[26:27], v[28:29], v[28:29] op_sel:[0,1] neg_lo:[0,1] neg_hi:[0,1]
	v_pk_add_f32 v[28:29], v[28:29], v[28:29] op_sel_hi:[0,1]
	v_mov_b32_e32 v27, v29
	v_xor_b32_e32 v28, 0x80000000, v31
	v_mov_b32_e32 v29, v30
	v_pk_add_f32 v[30:31], v[32:33], v[32:33] op_sel:[0,1]
	v_pk_add_f32 v[32:33], v[32:33], v[32:33] op_sel_hi:[0,1] neg_lo:[0,1] neg_hi:[0,1]
	v_mov_b32_e32 v31, v33
	s_mov_b32 s40, s21
	s_mov_b32 s41, s20
	v_pk_mul_f32 v[30:31], v[30:31], s[40:41]
	v_pk_add_f32 v[32:33], v[16:17], v[28:29]
	v_pk_fma_f32 v[34:35], v[26:27], s[20:21], v[30:31] op_sel_hi:[1,0,1]
	s_and_b64 vcc, exec, s[84:85]
	v_pk_add_f32 v[32:33], v[32:33], v[34:35]
	ds_read_u16 v34, v170 offset:14
	ds_read_u16 v35, v170 offset:16
	ds_read_u16 v36, v170 offset:18
	ds_read_u16 v37, v171 offset:14
	ds_read_u16 v38, v171 offset:16
	ds_read_u16 v39, v171 offset:18
	s_waitcnt lgkmcnt(0)
	v_lshlrev_b32_e32 v35, 16, v35
	v_lshlrev_b32_e32 v34, 16, v34
	v_mul_f32_e32 v35, v190, v35
	v_fmac_f32_e32 v35, v187, v34
	v_lshlrev_b32_e32 v34, 16, v36
	v_pk_mul_f32 v[32:33], v[66:67], v[32:33]
	v_fmac_f32_e32 v35, v189, v34
	v_lshlrev_b32_e32 v36, 16, v38
	v_add_f32_e32 v34, v188, v35
	v_lshlrev_b32_e32 v35, 16, v37
	v_mul_f32_e32 v36, v190, v36
	v_fma_f32 v32, v184, v40, v32
	v_fmac_f32_e32 v36, v187, v35
	v_lshlrev_b32_e32 v35, 16, v39
	v_mul_f32_e32 v32, v32, v34
	v_add_u32_e32 v34, s7, v127
	v_fmac_f32_e32 v36, v189, v35
	v_ashrrev_i32_e32 v35, 31, v34
	v_add_f32_e32 v36, v188, v36
	v_cvt_pk_bf16_f32 v32, v32, s0
	v_lshl_add_u64 v[34:35], v[34:35], 1, s[50:51]
	v_fmac_f32_e32 v33, v184, v41
	global_store_short v[34:35], v32, off
	v_mul_f32_e32 v32, v33, v36
	v_cvt_pk_bf16_f32 v34, v32, s0
	v_add_u32_e32 v32, s3, v127
	v_ashrrev_i32_e32 v33, 31, v32
	v_lshl_add_u64 v[32:33], v[32:33], 1, s[50:51]
	s_mov_b64 s[62:63], -1
	global_store_short v[32:33], v34, off
	s_cbranch_vccz .LBB0_692
	s_andn2_b64 vcc, exec, s[62:63]
	s_cbranch_vccz .LBB0_693

; __device__ __forceinline__ c2 mpi(c2 a) { return (c2){-a.y, a.x}; }
; __device__ __forceinline__ void idft8(c2 (&x)[8]) {
;     const float s = 0.70710678118654752f;
;     const c2 a0 = x[0] + x[4], a4 = x[0] - x[4], a1 = x[1] + x[5], a5 = x[1] - x[5], a2 = x[2] + x[6], a6 = x[2] - x[6], a3 = x[3] + x[7], a7 = x[3] - x[7];
;     const c2 a5w = (c2){(a5.x - a5.y) * s, (a5.x + a5.y) * s};
;     const c2 a6w = mpi(a6);
;     const c2 a7w = (c2){-(a7.x + a7.y) * s, (a7.x - a7.y) * s};
;     const c2 b0 = a0 + a2, b1 = a0 - a2, b2 = a1 + a3, b3 = mpi(a1 - a3);
;     x[0] = b0 + b2; x[4] = b0 - b2; x[2] = b1 + b3; x[6] = b1 - b3;
;     const c2 c0 = a4 + a6w, c1 = a4 - a6w, c2_ = a5w + a7w, c3 = mpi(a5w - a7w);
;     x[1] = c0 + c2_; x[5] = c0 - c2_; x[3] = c1 + c3; x[7] = c1 - c3;
.LBB0_667:
	ds_read_u16 v33, v155 offset:16
	ds_read_u16 v34, v155 offset:18
	ds_read_u16 v36, v155 offset:14
	s_waitcnt lgkmcnt(0)
	v_lshlrev_b32_e32 v33, 16, v33
	v_lshlrev_b32_e32 v35, 16, v34
	v_lshlrev_b32_e32 v34, 16, v36
	v_pk_mul_f32 v[34:35], v[64:65], v[34:35]
	s_nop 0
	v_fma_f32 v33, v186, v33, v34
	v_add_f32_e32 v33, v33, v35
	v_add_f32_e32 v33, v185, v33
.LBB0_668:
	v_pk_add_f32 v[20:21], v[20:21], v[24:25] neg_lo:[0,1] neg_hi:[0,1]
	v_pk_add_f32 v[18:19], v[18:19], v[22:23] neg_lo:[0,1] neg_hi:[0,1]
	v_xor_b32_e32 v22, 0x80000000, v21
	v_mov_b32_e32 v23, v20
	v_pk_add_f32 v[18:19], v[18:19], v[22:23]
	ds_read_u16 v20, v172 offset:14
	ds_read_u16 v21, v172 offset:16
	ds_read_u16 v22, v172 offset:18
	ds_read_u16 v23, v173 offset:14
	ds_read_u16 v24, v173 offset:16
	ds_read_u16 v25, v173 offset:18
	s_waitcnt lgkmcnt(0)
	v_lshlrev_b32_e32 v21, 16, v21
	v_lshlrev_b32_e32 v20, 16, v20
	v_mul_f32_e32 v21, v190, v21
	v_fmac_f32_e32 v21, v187, v20
	v_lshlrev_b32_e32 v20, 16, v22
	v_pk_mul_f32 v[18:19], v[66:67], v[18:19]
	v_fmac_f32_e32 v21, v189, v20
	v_lshlrev_b32_e32 v22, 16, v24
	v_add_f32_e32 v20, v188, v21
	v_lshlrev_b32_e32 v21, 16, v23
	v_mul_f32_e32 v22, v190, v22
	v_fma_f32 v18, v184, v32, v18
	v_fmac_f32_e32 v22, v187, v21
	v_lshlrev_b32_e32 v21, 16, v25
	v_mul_f32_e32 v18, v18, v20
	v_add_u32_e32 v20, s7, v130
	v_fmac_f32_e32 v22, v189, v21
	v_ashrrev_i32_e32 v21, 31, v20
	v_add_f32_e32 v22, v188, v22
	v_cvt_pk_bf16_f32 v18, v18, s0
	v_lshl_add_u64 v[20:21], v[20:21], 1, s[50:51]
	v_fmac_f32_e32 v19, v184, v33
	global_store_short v[20:21], v18, off
	v_mul_f32_e32 v18, v19, v22
	v_cvt_pk_bf16_f32 v20, v18, s0
	v_add_u32_e32 v18, s3, v130
	v_ashrrev_i32_e32 v19, 31, v18
	v_lshl_add_u64 v[18:19], v[18:19], 1, s[50:51]
	s_and_b64 vcc, exec, s[84:85]
	s_mov_b64 s[62:63], -1
	global_store_short v[18:19], v20, off
	s_cbranch_vccz .LBB0_695
	s_andn2_b64 vcc, exec, s[62:63]
	s_cbranch_vccz .LBB0_696

; __device__ __forceinline__ float bf2f(bf16_t b) { return __uint_as_float(((unsigned)b) << 16); }
; __device__ __forceinline__ float dwl(const bf16_t* r, int t, float w0, float w1, float w2, float b) { return w0 * bf2f(r[7 + t]) + w1 * bf2f(r[8 + t]) + w2 * bf2f(r[9 + t]) + b; }
.LBB0_675:
	ds_read_u16 v96, v144 offset:16
	ds_read_u16 v97, v144 offset:18
	ds_read_u16 v98, v144 offset:14
	s_waitcnt lgkmcnt(0)
	v_lshlrev_b32_e32 v99, 16, v96
	v_lshlrev_b32_e32 v97, 16, v97
	v_lshlrev_b32_e32 v96, 16, v98
	v_pk_mul_f32 v[96:97], v[64:65], v[96:97]
	s_nop 0
	v_fma_f32 v96, v186, v99, v96
	v_add_f32_e32 v96, v96, v97
	v_add_f32_e32 v202, v185, v96
	s_mov_b64 s[62:63], -1
	s_and_b64 vcc, exec, s[30:31]
	s_cbranch_vccz .LBB0_636

; __device__ __forceinline__ float bf2f(bf16_t b) { return __uint_as_float(((unsigned)b) << 16); }
; __device__ __forceinline__ float dwl(const bf16_t* r, int t, float w0, float w1, float w2, float b) { return w0 * bf2f(r[7 + t]) + w1 * bf2f(r[8 + t]) + w2 * bf2f(r[9 + t]) + b; }
.LBB0_678:
	ds_read_u16 v202, v148 offset:16
	ds_read_u16 v203, v148 offset:18
	ds_read_u16 v204, v148 offset:14
	s_waitcnt lgkmcnt(0)
	v_lshlrev_b32_e32 v205, 16, v202
	v_lshlrev_b32_e32 v203, 16, v203
	v_lshlrev_b32_e32 v202, 16, v204
	v_pk_mul_f32 v[202:203], v[64:65], v[202:203]
	s_nop 0
	v_fma_f32 v202, v186, v205, v202
	v_add_f32_e32 v202, v202, v203
	v_add_f32_e32 v202, v185, v202
	s_and_b64 vcc, exec, s[84:85]
	s_mov_b64 s[62:63], -1
	s_cbranch_vccnz .LBB0_641

; __device__ __forceinline__ float bf2f(bf16_t b) { return __uint_as_float(((unsigned)b) << 16); }
; __device__ __forceinline__ float dwl(const bf16_t* r, int t, float w0, float w1, float w2, float b) { return w0 * bf2f(r[7 + t]) + w1 * bf2f(r[8 + t]) + w2 * bf2f(r[9 + t]) + b; }
.LBB0_681:
	ds_read_u16 v96, v152 offset:16
	ds_read_u16 v97, v152 offset:18
	ds_read_u16 v98, v152 offset:14
	s_waitcnt lgkmcnt(0)
	v_lshlrev_b32_e32 v99, 16, v96
	v_lshlrev_b32_e32 v97, 16, v97
	v_lshlrev_b32_e32 v96, 16, v98
	v_pk_mul_f32 v[96:97], v[64:65], v[96:97]
	s_nop 0
	v_fma_f32 v96, v186, v99, v96
	v_add_f32_e32 v96, v96, v97
	v_add_f32_e32 v96, v185, v96
	s_and_b64 vcc, exec, s[84:85]
	s_mov_b64 s[62:63], -1
	s_cbranch_vccnz .LBB0_646

; __device__ __forceinline__ float bf2f(bf16_t b) { return __uint_as_float(((unsigned)b) << 16); }
; __device__ __forceinline__ float dwl(const bf16_t* r, int t, float w0, float w1, float w2, float b) { return w0 * bf2f(r[7 + t]) + w1 * bf2f(r[8 + t]) + w2 * bf2f(r[9 + t]) + b; }
.LBB0_684:
	ds_read_u16 v42, v156 offset:16
	ds_read_u16 v43, v156 offset:18
	ds_read_u16 v44, v156 offset:14
	s_waitcnt lgkmcnt(0)
	v_lshlrev_b32_e32 v45, 16, v42
	v_lshlrev_b32_e32 v43, 16, v43
	v_lshlrev_b32_e32 v42, 16, v44
	v_pk_mul_f32 v[42:43], v[64:65], v[42:43]
	s_nop 0
	v_fma_f32 v42, v186, v45, v42
	v_add_f32_e32 v42, v42, v43
	v_add_f32_e32 v42, v185, v42
	s_and_b64 vcc, exec, s[84:85]
	s_mov_b64 s[62:63], -1
	s_cbranch_vccnz .LBB0_651

; __device__ __forceinline__ float bf2f(bf16_t b) { return __uint_as_float(((unsigned)b) << 16); }
; __device__ __forceinline__ float dwl(const bf16_t* r, int t, float w0, float w1, float w2, float b) { return w0 * bf2f(r[7 + t]) + w1 * bf2f(r[8 + t]) + w2 * bf2f(r[9 + t]) + b; }
.LBB0_687:
	ds_read_u16 v40, v146 offset:16
	ds_read_u16 v41, v146 offset:18
	ds_read_u16 v42, v146 offset:14
	s_waitcnt lgkmcnt(0)
	v_lshlrev_b32_e32 v43, 16, v40
	v_lshlrev_b32_e32 v41, 16, v41
	v_lshlrev_b32_e32 v40, 16, v42
	v_pk_mul_f32 v[40:41], v[64:65], v[40:41]
	s_nop 0
	v_fma_f32 v40, v186, v43, v40
	v_add_f32_e32 v40, v40, v41
	v_add_f32_e32 v40, v185, v40
	s_mov_b64 s[62:63], -1
	s_and_b64 vcc, exec, s[30:31]
	s_cbranch_vccz .LBB0_656

; __device__ __forceinline__ float bf2f(bf16_t b) { return __uint_as_float(((unsigned)b) << 16); }
; __device__ __forceinline__ float dwl(const bf16_t* r, int t, float w0, float w1, float w2, float b) { return w0 * bf2f(r[7 + t]) + w1 * bf2f(r[8 + t]) + w2 * bf2f(r[9 + t]) + b; }
.LBB0_690:
	ds_read_u16 v40, v150 offset:16
	ds_read_u16 v41, v150 offset:18
	ds_read_u16 v42, v150 offset:14
	s_waitcnt lgkmcnt(0)
	v_lshlrev_b32_e32 v43, 16, v40
	v_lshlrev_b32_e32 v41, 16, v41
	v_lshlrev_b32_e32 v40, 16, v42
	v_pk_mul_f32 v[40:41], v[64:65], v[40:41]
	s_nop 0
	v_fma_f32 v40, v186, v43, v40
	v_add_f32_e32 v40, v40, v41
	v_add_f32_e32 v40, v185, v40
	s_and_b64 vcc, exec, s[84:85]
	s_mov_b64 s[62:63], -1
	s_cbranch_vccnz .LBB0_661

; __device__ __forceinline__ float bf2f(bf16_t b) { return __uint_as_float(((unsigned)b) << 16); }
; __device__ __forceinline__ float dwl(const bf16_t* r, int t, float w0, float w1, float w2, float b) { return w0 * bf2f(r[7 + t]) + w1 * bf2f(r[8 + t]) + w2 * bf2f(r[9 + t]) + b; }
.LBB0_693:
	ds_read_u16 v32, v154 offset:16
	ds_read_u16 v33, v154 offset:18
	ds_read_u16 v34, v154 offset:14
	s_waitcnt lgkmcnt(0)
	v_lshlrev_b32_e32 v35, 16, v32
	v_lshlrev_b32_e32 v33, 16, v33
	v_lshlrev_b32_e32 v32, 16, v34
	v_pk_mul_f32 v[32:33], v[64:65], v[32:33]
	s_nop 0
	v_fma_f32 v32, v186, v35, v32
	v_add_f32_e32 v32, v32, v33
	v_add_f32_e32 v32, v185, v32
	s_and_b64 vcc, exec, s[84:85]
	s_mov_b64 s[62:63], -1
	s_cbranch_vccnz .LBB0_666

; __device__ __forceinline__ float bf2f(bf16_t b) { return __uint_as_float(((unsigned)b) << 16); }
; __device__ __forceinline__ float dwl(const bf16_t* r, int t, float w0, float w1, float w2, float b) { return w0 * bf2f(r[7 + t]) + w1 * bf2f(r[8 + t]) + w2 * bf2f(r[9 + t]) + b; }
.LBB0_696:
	ds_read_u16 v18, v158 offset:16
	ds_read_u16 v19, v158 offset:18
	ds_read_u16 v20, v158 offset:14
	s_waitcnt lgkmcnt(0)
	v_lshlrev_b32_e32 v21, 16, v18
	v_lshlrev_b32_e32 v19, 16, v19
	v_lshlrev_b32_e32 v18, 16, v20
	v_pk_mul_f32 v[18:19], v[64:65], v[18:19]
	s_nop 0
	v_fma_f32 v18, v186, v21, v18
	v_add_f32_e32 v18, v18, v19
	v_add_f32_e32 v18, v185, v18
	s_and_b64 vcc, exec, s[84:85]
	s_mov_b64 s[62:63], -1
	s_cbranch_vccnz .LBB0_671

; __device__ __forceinline__ float bf2f(bf16_t b) { return __uint_as_float(((unsigned)b) << 16); }
; __device__ __forceinline__ float dwl(const bf16_t* r, int t, float w0, float w1, float w2, float b) { return w0 * bf2f(r[7 + t]) + w1 * bf2f(r[8 + t]) + w2 * bf2f(r[9 + t]) + b; }
.LBB0_698:
	ds_read_u16 v19, v159 offset:16
	ds_read_u16 v20, v159 offset:18
	ds_read_u16 v22, v159 offset:14
	s_waitcnt lgkmcnt(0)
	v_lshlrev_b32_e32 v19, 16, v19
	v_lshlrev_b32_e32 v21, 16, v20
	v_lshlrev_b32_e32 v20, 16, v22
	v_pk_mul_f32 v[20:21], v[64:65], v[20:21]
	s_nop 0
	v_fma_f32 v19, v186, v19, v20
	v_add_f32_e32 v19, v19, v21
	v_add_f32_e32 v19, v185, v19
	s_branch .LBB0_602
